# K-loop load segments: ds_reads issued first, address math and LDS-DMA after; s_nop pads replaced by real instructions (on top of v13)
# speedup vs baseline: 1.0037x; 1.0017x over previous
.LBB0_92:
	ds_read_b128 v[146:149], v143
	ds_read_b128 v[150:153], v143 offset:1024
	ds_read_b128 v[154:157], v143 offset:2048
	ds_read_b128 v[158:161], v143 offset:3072
	ds_read_b128 v[162:165], v144
	ds_read_b128 v[166:169], v144 offset:1024
	ds_read_b128 v[170:173], v144 offset:2048
	ds_read_b128 v[178:181], v144 offset:3072
	ds_read_b128 v[182:185], v145
	ds_read_b128 v[186:189], v145 offset:1024
	ds_read_b128 v[190:193], v145 offset:2048
	ds_read_b128 v[194:197], v145 offset:3072
	ds_read_b128 v[198:201], v145 offset:4096
	ds_read_b128 v[206:209], v145 offset:5120
	ds_read_b128 v[210:213], v145 offset:6144
	ds_read_b128 v[214:217], v145 offset:7168
	s_add_u32 s0, s28, 0xfff80080
	s_addc_u32 s1, s29, -1
	s_cmp_eq_u32 s68, 28
	s_cselect_b32 s35, s13, s1
	s_cselect_b32 s34, s63, s0
	s_cselect_b32 s31, s64, s67
	s_cselect_b32 s30, s65, s66
	s_add_i32 m0, s27, 0xc000
	v_lshl_add_u64 v[174:175], s[28:29], 0, v[136:137]
	global_load_lds_dwordx4 v[174:175], off
	s_add_i32 m0, s27, 0xe000
	v_lshl_add_u64 v[174:175], s[28:29], 0, v[138:139]
	global_load_lds_dwordx4 v[174:175], off
	s_waitcnt vmcnt(8)
	s_waitcnt lgkmcnt(0)
	s_barrier
	s_setprio 1
	v_mfma_f32_16x16x32_bf16 v[124:127], v[146:149], v[182:185], v[124:127]
	v_mfma_f32_16x16x32_bf16 v[120:123], v[154:157], v[182:185], v[120:123]
	v_mfma_f32_16x16x32_bf16 v[116:119], v[146:149], v[190:193], v[116:119]
	v_mfma_f32_16x16x32_bf16 v[108:111], v[154:157], v[190:193], v[108:111]
	v_mfma_f32_16x16x32_bf16 v[100:103], v[146:149], v[198:201], v[100:103]
	v_mfma_f32_16x16x32_bf16 v[92:95], v[154:157], v[198:201], v[92:95]
	v_mfma_f32_16x16x32_bf16 v[84:87], v[146:149], v[210:213], v[84:87]
	v_mfma_f32_16x16x32_bf16 v[76:79], v[154:157], v[210:213], v[76:79]
	v_mfma_f32_16x16x32_bf16 v[124:127], v[150:153], v[186:189], v[124:127]
	v_mfma_f32_16x16x32_bf16 v[120:123], v[158:161], v[186:189], v[120:123]
	v_mfma_f32_16x16x32_bf16 v[116:119], v[150:153], v[194:197], v[116:119]
	v_mfma_f32_16x16x32_bf16 v[108:111], v[158:161], v[194:197], v[108:111]
	v_mfma_f32_16x16x32_bf16 v[100:103], v[150:153], v[206:209], v[100:103]
	v_mfma_f32_16x16x32_bf16 v[92:95], v[158:161], v[206:209], v[92:95]
	v_mfma_f32_16x16x32_bf16 v[84:87], v[150:153], v[214:217], v[84:87]
	v_mfma_f32_16x16x32_bf16 v[76:79], v[158:161], v[214:217], v[76:79]
	v_mfma_f32_16x16x32_bf16 v[112:115], v[162:165], v[182:185], v[112:115]
	v_mfma_f32_16x16x32_bf16 v[104:107], v[170:173], v[182:185], v[104:107]
	v_mfma_f32_16x16x32_bf16 v[96:99], v[162:165], v[190:193], v[96:99]
	v_mfma_f32_16x16x32_bf16 v[88:91], v[170:173], v[190:193], v[88:91]
	v_mfma_f32_16x16x32_bf16 v[80:83], v[162:165], v[198:201], v[80:83]
	v_mfma_f32_16x16x32_bf16 v[72:75], v[170:173], v[198:201], v[72:75]
	v_mfma_f32_16x16x32_bf16 v[68:71], v[162:165], v[210:213], v[68:71]
	v_mfma_f32_16x16x32_bf16 v[64:67], v[170:173], v[210:213], v[64:67]
	v_mfma_f32_16x16x32_bf16 v[112:115], v[166:169], v[186:189], v[112:115]
	v_mfma_f32_16x16x32_bf16 v[104:107], v[178:181], v[186:189], v[104:107]
	v_mfma_f32_16x16x32_bf16 v[96:99], v[166:169], v[194:197], v[96:99]
	v_mfma_f32_16x16x32_bf16 v[88:91], v[178:181], v[194:197], v[88:91]
	v_mfma_f32_16x16x32_bf16 v[80:83], v[166:169], v[206:209], v[80:83]
	v_mfma_f32_16x16x32_bf16 v[72:75], v[178:181], v[206:209], v[72:75]
	v_mfma_f32_16x16x32_bf16 v[68:71], v[166:169], v[214:217], v[68:71]
	v_mfma_f32_16x16x32_bf16 v[64:67], v[178:181], v[214:217], v[64:67]
	s_setprio 0
	s_barrier
	ds_read_b128 v[182:185], v145 offset:16384
	ds_read_b128 v[186:189], v145 offset:17408
	ds_read_b128 v[190:193], v145 offset:18432
	ds_read_b128 v[194:197], v145 offset:19456
	ds_read_b128 v[198:201], v145 offset:20480
	ds_read_b128 v[206:209], v145 offset:21504
	ds_read_b128 v[210:213], v145 offset:22528
	ds_read_b128 v[214:217], v145 offset:23552
	s_add_i32 s0, s58, s48
	s_mov_b32 m0, s0
	v_lshl_add_u64 v[174:175], s[30:31], 0, v[132:133]
	global_load_lds_dwordx4 v[174:175], off
	s_add_i32 m0, s0, 0x2000
	s_add_u32 s0, s30, 0x80000
	v_lshl_add_u64 v[202:203], s[30:31], 0, v[128:129]
	s_addc_u32 s1, s31, 0
	s_add_i32 s2, s59, s48
	global_load_lds_dwordx4 v[202:203], off
	v_lshl_add_u64 v[218:219], s[0:1], 0, v[132:133]
	s_mov_b32 m0, s2
	v_lshl_add_u64 v[220:221], s[34:35], 0, v[130:131]
	global_load_lds_dwordx4 v[218:219], off
	s_add_i32 m0, s2, 0x2000
	v_lshl_add_u64 v[218:219], s[0:1], 0, v[128:129]
	global_load_lds_dwordx4 v[218:219], off
	s_mov_b32 m0, s27
	v_lshl_add_u64 v[218:219], s[34:35], 0, v[134:135]
	global_load_lds_dwordx4 v[218:219], off
	s_mov_b32 m0, s50
	s_nop 0
	global_load_lds_dwordx4 v[220:221], off
	s_waitcnt vmcnt(8)
	s_waitcnt lgkmcnt(0)
	s_barrier
	s_setprio 1
	v_mfma_f32_16x16x32_bf16 v[60:63], v[146:149], v[182:185], v[60:63]
	v_mfma_f32_16x16x32_bf16 v[56:59], v[154:157], v[182:185], v[56:59]
	v_mfma_f32_16x16x32_bf16 v[52:55], v[146:149], v[190:193], v[52:55]
	v_mfma_f32_16x16x32_bf16 v[44:47], v[154:157], v[190:193], v[44:47]
	v_mfma_f32_16x16x32_bf16 v[36:39], v[146:149], v[198:201], v[36:39]
	v_mfma_f32_16x16x32_bf16 v[28:31], v[154:157], v[198:201], v[28:31]
	v_mfma_f32_16x16x32_bf16 v[20:23], v[146:149], v[210:213], v[20:23]
	v_mfma_f32_16x16x32_bf16 v[12:15], v[154:157], v[210:213], v[12:15]
	v_mfma_f32_16x16x32_bf16 v[60:63], v[150:153], v[186:189], v[60:63]
	v_mfma_f32_16x16x32_bf16 v[56:59], v[158:161], v[186:189], v[56:59]
	v_mfma_f32_16x16x32_bf16 v[52:55], v[150:153], v[194:197], v[52:55]
	v_mfma_f32_16x16x32_bf16 v[44:47], v[158:161], v[194:197], v[44:47]
	v_mfma_f32_16x16x32_bf16 v[36:39], v[150:153], v[206:209], v[36:39]
	v_mfma_f32_16x16x32_bf16 v[28:31], v[158:161], v[206:209], v[28:31]
	v_mfma_f32_16x16x32_bf16 v[20:23], v[150:153], v[214:217], v[20:23]
	v_mfma_f32_16x16x32_bf16 v[12:15], v[158:161], v[214:217], v[12:15]
	v_mfma_f32_16x16x32_bf16 v[48:51], v[162:165], v[182:185], v[48:51]
	v_mfma_f32_16x16x32_bf16 v[40:43], v[170:173], v[182:185], v[40:43]
	v_mfma_f32_16x16x32_bf16 v[32:35], v[162:165], v[190:193], v[32:35]
	v_mfma_f32_16x16x32_bf16 v[24:27], v[170:173], v[190:193], v[24:27]
	v_mfma_f32_16x16x32_bf16 v[16:19], v[162:165], v[198:201], v[16:19]
	v_mfma_f32_16x16x32_bf16 v[8:11], v[170:173], v[198:201], v[8:11]
	v_mfma_f32_16x16x32_bf16 v[4:7], v[162:165], v[210:213], v[4:7]
	v_mfma_f32_16x16x32_bf16 v[0:3], v[170:173], v[210:213], v[0:3]
	v_mfma_f32_16x16x32_bf16 v[48:51], v[166:169], v[186:189], v[48:51]
	v_mfma_f32_16x16x32_bf16 v[40:43], v[178:181], v[186:189], v[40:43]
	v_mfma_f32_16x16x32_bf16 v[32:35], v[166:169], v[194:197], v[32:35]
	v_mfma_f32_16x16x32_bf16 v[24:27], v[178:181], v[194:197], v[24:27]
	v_mfma_f32_16x16x32_bf16 v[16:19], v[166:169], v[206:209], v[16:19]
	v_mfma_f32_16x16x32_bf16 v[8:11], v[178:181], v[206:209], v[8:11]
	v_mfma_f32_16x16x32_bf16 v[4:7], v[166:169], v[214:217], v[4:7]
	v_mfma_f32_16x16x32_bf16 v[0:3], v[178:181], v[214:217], v[0:3]
	s_setprio 0
	s_barrier
	ds_read_b128 v[182:185], v145 offset:32768
	ds_read_b128 v[186:189], v145 offset:33792
	ds_read_b128 v[190:193], v145 offset:34816
	ds_read_b128 v[194:197], v145 offset:35840
	ds_read_b128 v[198:201], v145 offset:36864
	ds_read_b128 v[206:209], v145 offset:37888
	ds_read_b128 v[210:213], v145 offset:38912
	ds_read_b128 v[214:217], v145 offset:39936
	s_add_i32 s2, 0, 0x18000
	s_add_i32 s38, 0, 0x1c000
	v_add_u32_e32 v158, s2, v142
	v_add_u32_e32 v177, s38, v142
	ds_read_b128 v[146:149], v158
	ds_read_b128 v[150:153], v158 offset:1024
	ds_read_b128 v[154:157], v158 offset:2048
	ds_read_b128 v[158:161], v158 offset:3072
	ds_read_b128 v[162:165], v177
	ds_read_b128 v[166:169], v177 offset:1024
	ds_read_b128 v[170:173], v177 offset:2048
	ds_read_b128 v[178:181], v177 offset:3072
	s_add_u32 s0, s34, 0x80000
	s_addc_u32 s1, s35, 0
	s_mov_b32 m0, s51
	v_lshl_add_u64 v[222:223], s[0:1], 0, v[134:135]
	global_load_lds_dwordx4 v[222:223], off
	s_mov_b32 m0, s52
	v_lshl_add_u64 v[222:223], s[0:1], 0, v[130:131]
	global_load_lds_dwordx4 v[222:223], off
	s_waitcnt vmcnt(8)
	s_waitcnt lgkmcnt(0)
	s_barrier
	s_setprio 1
	v_mfma_f32_16x16x32_bf16 v[124:127], v[146:149], v[182:185], v[124:127]
	v_mfma_f32_16x16x32_bf16 v[120:123], v[154:157], v[182:185], v[120:123]
	v_mfma_f32_16x16x32_bf16 v[116:119], v[146:149], v[190:193], v[116:119]
	v_mfma_f32_16x16x32_bf16 v[108:111], v[154:157], v[190:193], v[108:111]
	v_mfma_f32_16x16x32_bf16 v[100:103], v[146:149], v[198:201], v[100:103]
	v_mfma_f32_16x16x32_bf16 v[92:95], v[154:157], v[198:201], v[92:95]
	v_mfma_f32_16x16x32_bf16 v[84:87], v[146:149], v[210:213], v[84:87]
	v_mfma_f32_16x16x32_bf16 v[76:79], v[154:157], v[210:213], v[76:79]
	v_mfma_f32_16x16x32_bf16 v[124:127], v[150:153], v[186:189], v[124:127]
	v_mfma_f32_16x16x32_bf16 v[120:123], v[158:161], v[186:189], v[120:123]
	v_mfma_f32_16x16x32_bf16 v[116:119], v[150:153], v[194:197], v[116:119]
	v_mfma_f32_16x16x32_bf16 v[108:111], v[158:161], v[194:197], v[108:111]
	v_mfma_f32_16x16x32_bf16 v[100:103], v[150:153], v[206:209], v[100:103]
	v_mfma_f32_16x16x32_bf16 v[92:95], v[158:161], v[206:209], v[92:95]
	v_mfma_f32_16x16x32_bf16 v[84:87], v[150:153], v[214:217], v[84:87]
	v_mfma_f32_16x16x32_bf16 v[76:79], v[158:161], v[214:217], v[76:79]
	v_mfma_f32_16x16x32_bf16 v[112:115], v[162:165], v[182:185], v[112:115]
	v_mfma_f32_16x16x32_bf16 v[104:107], v[170:173], v[182:185], v[104:107]
	v_mfma_f32_16x16x32_bf16 v[96:99], v[162:165], v[190:193], v[96:99]
	v_mfma_f32_16x16x32_bf16 v[88:91], v[170:173], v[190:193], v[88:91]
	v_mfma_f32_16x16x32_bf16 v[80:83], v[162:165], v[198:201], v[80:83]
	v_mfma_f32_16x16x32_bf16 v[72:75], v[170:173], v[198:201], v[72:75]
	v_mfma_f32_16x16x32_bf16 v[68:71], v[162:165], v[210:213], v[68:71]
	v_mfma_f32_16x16x32_bf16 v[64:67], v[170:173], v[210:213], v[64:67]
	v_mfma_f32_16x16x32_bf16 v[112:115], v[166:169], v[186:189], v[112:115]
	v_mfma_f32_16x16x32_bf16 v[104:107], v[178:181], v[186:189], v[104:107]
	v_mfma_f32_16x16x32_bf16 v[96:99], v[166:169], v[194:197], v[96:99]
	v_mfma_f32_16x16x32_bf16 v[88:91], v[178:181], v[194:197], v[88:91]
	v_mfma_f32_16x16x32_bf16 v[80:83], v[166:169], v[206:209], v[80:83]
	v_mfma_f32_16x16x32_bf16 v[72:75], v[178:181], v[206:209], v[72:75]
	v_mfma_f32_16x16x32_bf16 v[68:71], v[166:169], v[214:217], v[68:71]
	v_mfma_f32_16x16x32_bf16 v[64:67], v[178:181], v[214:217], v[64:67]
	s_setprio 0
	s_barrier
	ds_read_b128 v[182:185], v145 offset:49152
	ds_read_b128 v[186:189], v145 offset:50176
	ds_read_b128 v[190:193], v145 offset:51200
	ds_read_b128 v[194:197], v145 offset:52224
	ds_read_b128 v[198:201], v145 offset:53248
	ds_read_b128 v[206:209], v145 offset:54272
	ds_read_b128 v[210:213], v145 offset:55296
	ds_read_b128 v[214:217], v145 offset:56320
	s_add_i32 s0, s2, s48
	s_mov_b32 m0, s0
	v_lshl_add_u64 v[174:175], v[174:175], 0, s[8:9]
	global_load_lds_dwordx4 v[174:175], off
	s_add_i32 m0, s0, 0x2000
	s_add_u32 s0, s30, 0x80080
	v_lshl_add_u64 v[174:175], v[202:203], 0, s[8:9]
	s_addc_u32 s1, s31, 0
	s_add_i32 s2, s38, s48
	global_load_lds_dwordx4 v[174:175], off
	s_mov_b32 m0, s2
	v_lshl_add_u64 v[174:175], s[0:1], 0, v[132:133]
	global_load_lds_dwordx4 v[174:175], off
	s_add_i32 m0, s2, 0x2000
	v_lshl_add_u64 v[174:175], s[0:1], 0, v[128:129]
	global_load_lds_dwordx4 v[174:175], off
	s_mov_b32 m0, s55
	v_lshl_add_u64 v[174:175], v[218:219], 0, s[8:9]
	global_load_lds_dwordx4 v[174:175], off
	s_mov_b32 m0, s56
	v_lshl_add_u64 v[174:175], v[220:221], 0, s[8:9]
	global_load_lds_dwordx4 v[174:175], off
	s_waitcnt vmcnt(8)
	s_waitcnt lgkmcnt(0)
	s_barrier
	s_setprio 1
	v_mfma_f32_16x16x32_bf16 v[60:63], v[146:149], v[182:185], v[60:63]
	v_mfma_f32_16x16x32_bf16 v[56:59], v[154:157], v[182:185], v[56:59]
	v_mfma_f32_16x16x32_bf16 v[52:55], v[146:149], v[190:193], v[52:55]
	v_mfma_f32_16x16x32_bf16 v[44:47], v[154:157], v[190:193], v[44:47]
	v_mfma_f32_16x16x32_bf16 v[36:39], v[146:149], v[198:201], v[36:39]
	v_mfma_f32_16x16x32_bf16 v[28:31], v[154:157], v[198:201], v[28:31]
	v_mfma_f32_16x16x32_bf16 v[20:23], v[146:149], v[210:213], v[20:23]
	v_mfma_f32_16x16x32_bf16 v[12:15], v[154:157], v[210:213], v[12:15]
	v_mfma_f32_16x16x32_bf16 v[60:63], v[150:153], v[186:189], v[60:63]
	v_mfma_f32_16x16x32_bf16 v[56:59], v[158:161], v[186:189], v[56:59]
	v_mfma_f32_16x16x32_bf16 v[52:55], v[150:153], v[194:197], v[52:55]
	v_mfma_f32_16x16x32_bf16 v[44:47], v[158:161], v[194:197], v[44:47]
	v_mfma_f32_16x16x32_bf16 v[36:39], v[150:153], v[206:209], v[36:39]
	v_mfma_f32_16x16x32_bf16 v[28:31], v[158:161], v[206:209], v[28:31]
	v_mfma_f32_16x16x32_bf16 v[20:23], v[150:153], v[214:217], v[20:23]
	v_mfma_f32_16x16x32_bf16 v[12:15], v[158:161], v[214:217], v[12:15]
	v_mfma_f32_16x16x32_bf16 v[48:51], v[162:165], v[182:185], v[48:51]
	v_mfma_f32_16x16x32_bf16 v[40:43], v[170:173], v[182:185], v[40:43]
	v_mfma_f32_16x16x32_bf16 v[32:35], v[162:165], v[190:193], v[32:35]
	v_mfma_f32_16x16x32_bf16 v[24:27], v[170:173], v[190:193], v[24:27]
	v_mfma_f32_16x16x32_bf16 v[16:19], v[162:165], v[198:201], v[16:19]
	v_mfma_f32_16x16x32_bf16 v[8:11], v[170:173], v[198:201], v[8:11]
	v_mfma_f32_16x16x32_bf16 v[4:7], v[162:165], v[210:213], v[4:7]
	v_mfma_f32_16x16x32_bf16 v[0:3], v[170:173], v[210:213], v[0:3]
	v_mfma_f32_16x16x32_bf16 v[48:51], v[166:169], v[186:189], v[48:51]
	v_mfma_f32_16x16x32_bf16 v[40:43], v[178:181], v[186:189], v[40:43]
	v_mfma_f32_16x16x32_bf16 v[32:35], v[166:169], v[194:197], v[32:35]
	v_mfma_f32_16x16x32_bf16 v[24:27], v[178:181], v[194:197], v[24:27]
	v_mfma_f32_16x16x32_bf16 v[16:19], v[166:169], v[206:209], v[16:19]
	v_mfma_f32_16x16x32_bf16 v[8:11], v[178:181], v[206:209], v[8:11]
	v_mfma_f32_16x16x32_bf16 v[4:7], v[166:169], v[214:217], v[4:7]
	v_mfma_f32_16x16x32_bf16 v[0:3], v[178:181], v[214:217], v[0:3]
	s_setprio 0
	s_barrier
	s_add_i32 s68, s68, 2
	s_add_u32 s28, s28, 0x100
	s_addc_u32 s29, s29, 0
	s_add_u32 s66, s66, 0x100
	s_addc_u32 s67, s67, 0
	s_cmp_gt_u32 s68, 29
	s_cbranch_scc0 .LBB0_92
	s_and_b64 vcc, exec, s[10:11]
	s_cbranch_vccz .LBB0_95
	s_barrier

.LBB0_300:
	ds_read_b128 v[128:131], v157
	ds_read_b128 v[132:135], v157 offset:1024
	ds_read_b128 v[136:139], v157 offset:2048
	ds_read_b128 v[140:143], v157 offset:3072
	ds_read_b128 v[160:163], v158
	ds_read_b128 v[164:167], v158 offset:1024
	ds_read_b128 v[168:171], v158 offset:2048
	ds_read_b128 v[172:175], v158 offset:3072
	ds_read_b128 v[178:181], v159
	ds_read_b128 v[182:185], v159 offset:1024
	ds_read_b128 v[186:189], v159 offset:2048
	ds_read_b128 v[190:193], v159 offset:3072
	ds_read_b128 v[194:197], v159 offset:4096
	ds_read_b128 v[198:201], v159 offset:5120
	ds_read_b128 v[206:209], v159 offset:6144
	ds_read_b128 v[210:213], v159 offset:7168
	s_add_u32 s0, s62, 0xfff80080
	s_addc_u32 s1, s63, -1
	s_cmp_eq_u32 s89, 28
	s_cselect_b32 s67, s14, s1
	s_cselect_b32 s66, s49, s0
	s_cselect_b32 s65, s61, s88
	s_cselect_b32 s64, s68, s69
	s_add_i32 m0, s72, 0xc000
	v_lshl_add_u64 v[152:153], s[62:63], 0, v[148:149]
	global_load_lds_dwordx4 v[152:153], off
	s_add_i32 m0, s72, 0xe000
	v_lshl_add_u64 v[152:153], s[62:63], 0, v[150:151]
	global_load_lds_dwordx4 v[152:153], off
	s_waitcnt vmcnt(8)
	s_waitcnt lgkmcnt(0)
	s_barrier
	s_setprio 1
	v_mfma_f32_16x16x32_bf16 v[124:127], v[128:131], v[178:181], v[124:127]
	v_mfma_f32_16x16x32_bf16 v[120:123], v[136:139], v[178:181], v[120:123]
	v_mfma_f32_16x16x32_bf16 v[112:115], v[128:131], v[186:189], v[112:115]
	v_mfma_f32_16x16x32_bf16 v[108:111], v[136:139], v[186:189], v[108:111]
	v_mfma_f32_16x16x32_bf16 v[96:99], v[128:131], v[194:197], v[96:99]
	v_mfma_f32_16x16x32_bf16 v[92:95], v[136:139], v[194:197], v[92:95]
	v_mfma_f32_16x16x32_bf16 v[80:83], v[128:131], v[206:209], v[80:83]
	v_mfma_f32_16x16x32_bf16 v[76:79], v[136:139], v[206:209], v[76:79]
	v_mfma_f32_16x16x32_bf16 v[124:127], v[132:135], v[182:185], v[124:127]
	v_mfma_f32_16x16x32_bf16 v[120:123], v[140:143], v[182:185], v[120:123]
	v_mfma_f32_16x16x32_bf16 v[112:115], v[132:135], v[190:193], v[112:115]
	v_mfma_f32_16x16x32_bf16 v[108:111], v[140:143], v[190:193], v[108:111]
	v_mfma_f32_16x16x32_bf16 v[96:99], v[132:135], v[198:201], v[96:99]
	v_mfma_f32_16x16x32_bf16 v[92:95], v[140:143], v[198:201], v[92:95]
	v_mfma_f32_16x16x32_bf16 v[80:83], v[132:135], v[210:213], v[80:83]
	v_mfma_f32_16x16x32_bf16 v[76:79], v[140:143], v[210:213], v[76:79]
	v_mfma_f32_16x16x32_bf16 v[116:119], v[160:163], v[178:181], v[116:119]
	v_mfma_f32_16x16x32_bf16 v[104:107], v[168:171], v[178:181], v[104:107]
	v_mfma_f32_16x16x32_bf16 v[100:103], v[160:163], v[186:189], v[100:103]
	v_mfma_f32_16x16x32_bf16 v[88:91], v[168:171], v[186:189], v[88:91]
	v_mfma_f32_16x16x32_bf16 v[84:87], v[160:163], v[194:197], v[84:87]
	v_mfma_f32_16x16x32_bf16 v[72:75], v[168:171], v[194:197], v[72:75]
	v_mfma_f32_16x16x32_bf16 v[68:71], v[160:163], v[206:209], v[68:71]
	v_mfma_f32_16x16x32_bf16 v[64:67], v[168:171], v[206:209], v[64:67]
	v_mfma_f32_16x16x32_bf16 v[116:119], v[164:167], v[182:185], v[116:119]
	v_mfma_f32_16x16x32_bf16 v[104:107], v[172:175], v[182:185], v[104:107]
	v_mfma_f32_16x16x32_bf16 v[100:103], v[164:167], v[190:193], v[100:103]
	v_mfma_f32_16x16x32_bf16 v[88:91], v[172:175], v[190:193], v[88:91]
	v_mfma_f32_16x16x32_bf16 v[84:87], v[164:167], v[198:201], v[84:87]
	v_mfma_f32_16x16x32_bf16 v[72:75], v[172:175], v[198:201], v[72:75]
	v_mfma_f32_16x16x32_bf16 v[68:71], v[164:167], v[210:213], v[68:71]
	v_mfma_f32_16x16x32_bf16 v[64:67], v[172:175], v[210:213], v[64:67]
	s_setprio 0
	s_barrier
	ds_read_b128 v[178:181], v159 offset:16384
	ds_read_b128 v[182:185], v159 offset:17408
	ds_read_b128 v[186:189], v159 offset:18432
	ds_read_b128 v[190:193], v159 offset:19456
	ds_read_b128 v[194:197], v159 offset:20480
	ds_read_b128 v[198:201], v159 offset:21504
	ds_read_b128 v[206:209], v159 offset:22528
	ds_read_b128 v[210:213], v159 offset:23552
	s_add_i32 s0, s83, s71
	s_mov_b32 m0, s0
	v_lshl_add_u64 v[152:153], s[64:65], 0, v[146:147]
	global_load_lds_dwordx4 v[152:153], off
	s_add_i32 m0, s0, 0x2000
	s_add_u32 s0, s64, 0x80000
	v_lshl_add_u64 v[202:203], s[64:65], 0, v[144:145]
	s_addc_u32 s1, s65, 0
	s_add_i32 s2, s84, s71
	global_load_lds_dwordx4 v[202:203], off
	v_lshl_add_u64 v[214:215], s[0:1], 0, v[146:147]
	s_mov_b32 m0, s2
	v_lshl_add_u64 v[216:217], s[66:67], 0, v[144:145]
	global_load_lds_dwordx4 v[214:215], off
	s_add_i32 m0, s2, 0x2000
	v_lshl_add_u64 v[214:215], s[0:1], 0, v[144:145]
	global_load_lds_dwordx4 v[214:215], off
	s_mov_b32 m0, s72
	v_lshl_add_u64 v[214:215], s[66:67], 0, v[146:147]
	global_load_lds_dwordx4 v[214:215], off
	s_mov_b32 m0, s73
	s_nop 0
	global_load_lds_dwordx4 v[216:217], off
	s_waitcnt vmcnt(8)
	s_waitcnt lgkmcnt(0)
	s_barrier
	s_setprio 1
	v_mfma_f32_16x16x32_bf16 v[60:63], v[128:131], v[178:181], v[60:63]
	v_mfma_f32_16x16x32_bf16 v[56:59], v[136:139], v[178:181], v[56:59]
	v_mfma_f32_16x16x32_bf16 v[48:51], v[128:131], v[186:189], v[48:51]
	v_mfma_f32_16x16x32_bf16 v[44:47], v[136:139], v[186:189], v[44:47]
	v_mfma_f32_16x16x32_bf16 v[32:35], v[128:131], v[194:197], v[32:35]
	v_mfma_f32_16x16x32_bf16 v[28:31], v[136:139], v[194:197], v[28:31]
	v_mfma_f32_16x16x32_bf16 v[16:19], v[128:131], v[206:209], v[16:19]
	v_mfma_f32_16x16x32_bf16 v[12:15], v[136:139], v[206:209], v[12:15]
	v_mfma_f32_16x16x32_bf16 v[60:63], v[132:135], v[182:185], v[60:63]
	v_mfma_f32_16x16x32_bf16 v[56:59], v[140:143], v[182:185], v[56:59]
	v_mfma_f32_16x16x32_bf16 v[48:51], v[132:135], v[190:193], v[48:51]
	v_mfma_f32_16x16x32_bf16 v[44:47], v[140:143], v[190:193], v[44:47]
	v_mfma_f32_16x16x32_bf16 v[32:35], v[132:135], v[198:201], v[32:35]
	v_mfma_f32_16x16x32_bf16 v[28:31], v[140:143], v[198:201], v[28:31]
	v_mfma_f32_16x16x32_bf16 v[16:19], v[132:135], v[210:213], v[16:19]
	v_mfma_f32_16x16x32_bf16 v[12:15], v[140:143], v[210:213], v[12:15]
	v_mfma_f32_16x16x32_bf16 v[52:55], v[160:163], v[178:181], v[52:55]
	v_mfma_f32_16x16x32_bf16 v[40:43], v[168:171], v[178:181], v[40:43]
	v_mfma_f32_16x16x32_bf16 v[36:39], v[160:163], v[186:189], v[36:39]
	v_mfma_f32_16x16x32_bf16 v[24:27], v[168:171], v[186:189], v[24:27]
	v_mfma_f32_16x16x32_bf16 v[20:23], v[160:163], v[194:197], v[20:23]
	v_mfma_f32_16x16x32_bf16 v[8:11], v[168:171], v[194:197], v[8:11]
	v_mfma_f32_16x16x32_bf16 v[4:7], v[160:163], v[206:209], v[4:7]
	v_mfma_f32_16x16x32_bf16 v[0:3], v[168:171], v[206:209], v[0:3]
	v_mfma_f32_16x16x32_bf16 v[52:55], v[164:167], v[182:185], v[52:55]
	v_mfma_f32_16x16x32_bf16 v[40:43], v[172:175], v[182:185], v[40:43]
	v_mfma_f32_16x16x32_bf16 v[36:39], v[164:167], v[190:193], v[36:39]
	v_mfma_f32_16x16x32_bf16 v[24:27], v[172:175], v[190:193], v[24:27]
	v_mfma_f32_16x16x32_bf16 v[20:23], v[164:167], v[198:201], v[20:23]
	v_mfma_f32_16x16x32_bf16 v[8:11], v[172:175], v[198:201], v[8:11]
	v_mfma_f32_16x16x32_bf16 v[4:7], v[164:167], v[210:213], v[4:7]
	v_mfma_f32_16x16x32_bf16 v[0:3], v[172:175], v[210:213], v[0:3]
	s_setprio 0
	s_barrier
	ds_read_b128 v[178:181], v159 offset:32768
	ds_read_b128 v[182:185], v159 offset:33792
	ds_read_b128 v[186:189], v159 offset:34816
	ds_read_b128 v[190:193], v159 offset:35840
	ds_read_b128 v[194:197], v159 offset:36864
	ds_read_b128 v[198:201], v159 offset:37888
	ds_read_b128 v[206:209], v159 offset:38912
	ds_read_b128 v[210:213], v159 offset:39936
	s_add_i32 s2, 0, 0x18000
	s_add_i32 s3, 0, 0x1c000
	v_add_u32_e32 v140, s2, v156
	v_add_u32_e32 v172, s3, v156
	ds_read_b128 v[128:131], v140
	ds_read_b128 v[132:135], v140 offset:1024
	ds_read_b128 v[136:139], v140 offset:2048
	ds_read_b128 v[140:143], v140 offset:3072
	ds_read_b128 v[160:163], v172
	ds_read_b128 v[164:167], v172 offset:1024
	ds_read_b128 v[168:171], v172 offset:2048
	ds_read_b128 v[172:175], v172 offset:3072
	s_add_u32 s0, s66, 0x80000
	s_addc_u32 s1, s67, 0
	s_mov_b32 m0, s74
	v_lshl_add_u64 v[218:219], s[0:1], 0, v[146:147]
	global_load_lds_dwordx4 v[218:219], off
	s_mov_b32 m0, s75
	v_lshl_add_u64 v[218:219], s[0:1], 0, v[144:145]
	global_load_lds_dwordx4 v[218:219], off
	s_waitcnt vmcnt(8)
	s_waitcnt lgkmcnt(0)
	s_barrier
	s_setprio 1
	v_mfma_f32_16x16x32_bf16 v[124:127], v[128:131], v[178:181], v[124:127]
	v_mfma_f32_16x16x32_bf16 v[120:123], v[136:139], v[178:181], v[120:123]
	v_mfma_f32_16x16x32_bf16 v[112:115], v[128:131], v[186:189], v[112:115]
	v_mfma_f32_16x16x32_bf16 v[108:111], v[136:139], v[186:189], v[108:111]
	v_mfma_f32_16x16x32_bf16 v[96:99], v[128:131], v[194:197], v[96:99]
	v_mfma_f32_16x16x32_bf16 v[92:95], v[136:139], v[194:197], v[92:95]
	v_mfma_f32_16x16x32_bf16 v[80:83], v[128:131], v[206:209], v[80:83]
	v_mfma_f32_16x16x32_bf16 v[76:79], v[136:139], v[206:209], v[76:79]
	v_mfma_f32_16x16x32_bf16 v[124:127], v[132:135], v[182:185], v[124:127]
	v_mfma_f32_16x16x32_bf16 v[120:123], v[140:143], v[182:185], v[120:123]
	v_mfma_f32_16x16x32_bf16 v[112:115], v[132:135], v[190:193], v[112:115]
	v_mfma_f32_16x16x32_bf16 v[108:111], v[140:143], v[190:193], v[108:111]
	v_mfma_f32_16x16x32_bf16 v[96:99], v[132:135], v[198:201], v[96:99]
	v_mfma_f32_16x16x32_bf16 v[92:95], v[140:143], v[198:201], v[92:95]
	v_mfma_f32_16x16x32_bf16 v[80:83], v[132:135], v[210:213], v[80:83]
	v_mfma_f32_16x16x32_bf16 v[76:79], v[140:143], v[210:213], v[76:79]
	v_mfma_f32_16x16x32_bf16 v[116:119], v[160:163], v[178:181], v[116:119]
	v_mfma_f32_16x16x32_bf16 v[104:107], v[168:171], v[178:181], v[104:107]
	v_mfma_f32_16x16x32_bf16 v[100:103], v[160:163], v[186:189], v[100:103]
	v_mfma_f32_16x16x32_bf16 v[88:91], v[168:171], v[186:189], v[88:91]
	v_mfma_f32_16x16x32_bf16 v[84:87], v[160:163], v[194:197], v[84:87]
	v_mfma_f32_16x16x32_bf16 v[72:75], v[168:171], v[194:197], v[72:75]
	v_mfma_f32_16x16x32_bf16 v[68:71], v[160:163], v[206:209], v[68:71]
	v_mfma_f32_16x16x32_bf16 v[64:67], v[168:171], v[206:209], v[64:67]
	v_mfma_f32_16x16x32_bf16 v[116:119], v[164:167], v[182:185], v[116:119]
	v_mfma_f32_16x16x32_bf16 v[104:107], v[172:175], v[182:185], v[104:107]
	v_mfma_f32_16x16x32_bf16 v[100:103], v[164:167], v[190:193], v[100:103]
	v_mfma_f32_16x16x32_bf16 v[88:91], v[172:175], v[190:193], v[88:91]
	v_mfma_f32_16x16x32_bf16 v[84:87], v[164:167], v[198:201], v[84:87]
	v_mfma_f32_16x16x32_bf16 v[72:75], v[172:175], v[198:201], v[72:75]
	v_mfma_f32_16x16x32_bf16 v[68:71], v[164:167], v[210:213], v[68:71]
	v_mfma_f32_16x16x32_bf16 v[64:67], v[172:175], v[210:213], v[64:67]
	s_setprio 0
	s_barrier
	ds_read_b128 v[178:181], v159 offset:49152
	ds_read_b128 v[182:185], v159 offset:50176
	ds_read_b128 v[186:189], v159 offset:51200
	ds_read_b128 v[190:193], v159 offset:52224
	ds_read_b128 v[194:197], v159 offset:53248
	ds_read_b128 v[198:201], v159 offset:54272
	ds_read_b128 v[206:209], v159 offset:55296
	ds_read_b128 v[210:213], v159 offset:56320
	s_add_i32 s0, s2, s71
	s_mov_b32 m0, s0
	v_lshl_add_u64 v[152:153], v[152:153], 0, s[12:13]
	global_load_lds_dwordx4 v[152:153], off
	s_add_i32 m0, s0, 0x2000
	s_add_u32 s0, s64, 0x80080
	v_lshl_add_u64 v[152:153], v[202:203], 0, s[12:13]
	s_addc_u32 s1, s65, 0
	s_add_i32 s2, s3, s71
	global_load_lds_dwordx4 v[152:153], off
	s_mov_b32 m0, s2
	v_lshl_add_u64 v[152:153], s[0:1], 0, v[146:147]
	global_load_lds_dwordx4 v[152:153], off
	s_add_i32 m0, s2, 0x2000
	v_lshl_add_u64 v[152:153], s[0:1], 0, v[144:145]
	global_load_lds_dwordx4 v[152:153], off
	s_mov_b32 m0, s81
	v_lshl_add_u64 v[152:153], v[214:215], 0, s[12:13]
	global_load_lds_dwordx4 v[152:153], off
	s_mov_b32 m0, s82
	v_lshl_add_u64 v[152:153], v[216:217], 0, s[12:13]
	global_load_lds_dwordx4 v[152:153], off
	s_waitcnt vmcnt(8)
	s_waitcnt lgkmcnt(0)
	s_barrier
	s_setprio 1
	v_mfma_f32_16x16x32_bf16 v[60:63], v[128:131], v[178:181], v[60:63]
	v_mfma_f32_16x16x32_bf16 v[56:59], v[136:139], v[178:181], v[56:59]
	v_mfma_f32_16x16x32_bf16 v[48:51], v[128:131], v[186:189], v[48:51]
	v_mfma_f32_16x16x32_bf16 v[44:47], v[136:139], v[186:189], v[44:47]
	v_mfma_f32_16x16x32_bf16 v[32:35], v[128:131], v[194:197], v[32:35]
	v_mfma_f32_16x16x32_bf16 v[28:31], v[136:139], v[194:197], v[28:31]
	v_mfma_f32_16x16x32_bf16 v[16:19], v[128:131], v[206:209], v[16:19]
	v_mfma_f32_16x16x32_bf16 v[12:15], v[136:139], v[206:209], v[12:15]
	v_mfma_f32_16x16x32_bf16 v[60:63], v[132:135], v[182:185], v[60:63]
	v_mfma_f32_16x16x32_bf16 v[56:59], v[140:143], v[182:185], v[56:59]
	v_mfma_f32_16x16x32_bf16 v[48:51], v[132:135], v[190:193], v[48:51]
	v_mfma_f32_16x16x32_bf16 v[44:47], v[140:143], v[190:193], v[44:47]
	v_mfma_f32_16x16x32_bf16 v[32:35], v[132:135], v[198:201], v[32:35]
	v_mfma_f32_16x16x32_bf16 v[28:31], v[140:143], v[198:201], v[28:31]
	v_mfma_f32_16x16x32_bf16 v[16:19], v[132:135], v[210:213], v[16:19]
	v_mfma_f32_16x16x32_bf16 v[12:15], v[140:143], v[210:213], v[12:15]
	v_mfma_f32_16x16x32_bf16 v[52:55], v[160:163], v[178:181], v[52:55]
	v_mfma_f32_16x16x32_bf16 v[40:43], v[168:171], v[178:181], v[40:43]
	v_mfma_f32_16x16x32_bf16 v[36:39], v[160:163], v[186:189], v[36:39]
	v_mfma_f32_16x16x32_bf16 v[24:27], v[168:171], v[186:189], v[24:27]
	v_mfma_f32_16x16x32_bf16 v[20:23], v[160:163], v[194:197], v[20:23]
	v_mfma_f32_16x16x32_bf16 v[8:11], v[168:171], v[194:197], v[8:11]
	v_mfma_f32_16x16x32_bf16 v[4:7], v[160:163], v[206:209], v[4:7]
	v_mfma_f32_16x16x32_bf16 v[0:3], v[168:171], v[206:209], v[0:3]
	v_mfma_f32_16x16x32_bf16 v[52:55], v[164:167], v[182:185], v[52:55]
	v_mfma_f32_16x16x32_bf16 v[40:43], v[172:175], v[182:185], v[40:43]
	v_mfma_f32_16x16x32_bf16 v[36:39], v[164:167], v[190:193], v[36:39]
	v_mfma_f32_16x16x32_bf16 v[24:27], v[172:175], v[190:193], v[24:27]
	v_mfma_f32_16x16x32_bf16 v[20:23], v[164:167], v[198:201], v[20:23]
	v_mfma_f32_16x16x32_bf16 v[8:11], v[172:175], v[198:201], v[8:11]
	v_mfma_f32_16x16x32_bf16 v[4:7], v[164:167], v[210:213], v[4:7]
	v_mfma_f32_16x16x32_bf16 v[0:3], v[172:175], v[210:213], v[0:3]
	s_setprio 0
	s_barrier
	s_add_i32 s89, s89, 2
	s_add_u32 s62, s62, 0x100
	s_addc_u32 s63, s63, 0
	s_add_u32 s69, s69, 0x100
	s_addc_u32 s88, s88, 0
	s_cmp_gt_u32 s89, 29
	s_cbranch_scc0 .LBB0_300
	s_and_b64 vcc, exec, s[16:17]
	s_cbranch_vccz .LBB0_303
	s_barrier

.LBB0_399:
	ds_read_b128 v[128:131], v207
	ds_read_b128 v[132:135], v207 offset:1024
	ds_read_b128 v[136:139], v207 offset:2048
	ds_read_b128 v[140:143], v207 offset:3072
	ds_read_b128 v[144:147], v208
	ds_read_b128 v[148:151], v208 offset:1024
	ds_read_b128 v[152:155], v208 offset:2048
	ds_read_b128 v[156:159], v208 offset:3072
	ds_read_b128 v[160:163], v209
	ds_read_b128 v[164:167], v209 offset:1024
	ds_read_b128 v[168:171], v209 offset:2048
	ds_read_b128 v[172:175], v209 offset:3072
	ds_read_b128 v[190:193], v209 offset:4096
	ds_read_b128 v[194:197], v209 offset:5120
	ds_read_b128 v[198:201], v209 offset:6144
	ds_read_b128 v[210:213], v209 offset:7168
	s_add_u32 s0, s4, 0xfff80080
	s_addc_u32 s1, s5, -1
	s_cmp_eq_u32 vcc_hi, 28
	s_cselect_b32 s11, s7, s1
	s_cselect_b32 s10, s12, s0
	s_cselect_b32 s9, s13, vcc_lo
	s_cselect_b32 s8, s15, s65
	s_add_i32 m0, s81, 0xc000
	v_lshl_add_u64 v[202:203], s[4:5], 0, v[186:187]
	global_load_lds_dwordx4 v[202:203], off
	s_add_i32 m0, s81, 0xe000
	v_lshl_add_u64 v[202:203], s[4:5], 0, v[188:189]
	global_load_lds_dwordx4 v[202:203], off
	s_waitcnt vmcnt(8)
	s_waitcnt lgkmcnt(0)
	s_barrier
	s_setprio 1
	v_mfma_f32_16x16x32_bf16 v[124:127], v[128:131], v[160:163], v[124:127]
	v_mfma_f32_16x16x32_bf16 v[56:59], v[136:139], v[160:163], v[56:59]
	v_mfma_f32_16x16x32_bf16 v[116:119], v[128:131], v[168:171], v[116:119]
	v_mfma_f32_16x16x32_bf16 v[52:55], v[136:139], v[168:171], v[52:55]
	v_mfma_f32_16x16x32_bf16 v[108:111], v[128:131], v[190:193], v[108:111]
	v_mfma_f32_16x16x32_bf16 v[44:47], v[136:139], v[190:193], v[44:47]
	v_mfma_f32_16x16x32_bf16 v[104:107], v[128:131], v[198:201], v[104:107]
	v_mfma_f32_16x16x32_bf16 v[32:35], v[136:139], v[198:201], v[32:35]
	v_mfma_f32_16x16x32_bf16 v[124:127], v[132:135], v[164:167], v[124:127]
	v_mfma_f32_16x16x32_bf16 v[56:59], v[140:143], v[164:167], v[56:59]
	v_mfma_f32_16x16x32_bf16 v[116:119], v[132:135], v[172:175], v[116:119]
	v_mfma_f32_16x16x32_bf16 v[52:55], v[140:143], v[172:175], v[52:55]
	v_mfma_f32_16x16x32_bf16 v[108:111], v[132:135], v[194:197], v[108:111]
	v_mfma_f32_16x16x32_bf16 v[44:47], v[140:143], v[194:197], v[44:47]
	v_mfma_f32_16x16x32_bf16 v[104:107], v[132:135], v[210:213], v[104:107]
	v_mfma_f32_16x16x32_bf16 v[32:35], v[140:143], v[210:213], v[32:35]
	v_mfma_f32_16x16x32_bf16 v[120:123], v[144:147], v[160:163], v[120:123]
	v_mfma_f32_16x16x32_bf16 v[60:63], v[152:155], v[160:163], v[60:63]
	v_mfma_f32_16x16x32_bf16 v[112:115], v[144:147], v[168:171], v[112:115]
	v_mfma_f32_16x16x32_bf16 v[48:51], v[152:155], v[168:171], v[48:51]
	v_mfma_f32_16x16x32_bf16 v[100:103], v[144:147], v[190:193], v[100:103]
	v_mfma_f32_16x16x32_bf16 v[40:43], v[152:155], v[190:193], v[40:43]
	v_mfma_f32_16x16x32_bf16 v[96:99], v[144:147], v[198:201], v[96:99]
	v_mfma_f32_16x16x32_bf16 v[36:39], v[152:155], v[198:201], v[36:39]
	v_mfma_f32_16x16x32_bf16 v[120:123], v[148:151], v[164:167], v[120:123]
	v_mfma_f32_16x16x32_bf16 v[60:63], v[156:159], v[164:167], v[60:63]
	v_mfma_f32_16x16x32_bf16 v[112:115], v[148:151], v[172:175], v[112:115]
	v_mfma_f32_16x16x32_bf16 v[48:51], v[156:159], v[172:175], v[48:51]
	v_mfma_f32_16x16x32_bf16 v[100:103], v[148:151], v[194:197], v[100:103]
	v_mfma_f32_16x16x32_bf16 v[40:43], v[156:159], v[194:197], v[40:43]
	v_mfma_f32_16x16x32_bf16 v[96:99], v[148:151], v[210:213], v[96:99]
	v_mfma_f32_16x16x32_bf16 v[36:39], v[156:159], v[210:213], v[36:39]
	s_setprio 0
	s_barrier
	ds_read_b128 v[160:163], v209 offset:16384
	ds_read_b128 v[164:167], v209 offset:17408
	ds_read_b128 v[168:171], v209 offset:18432
	ds_read_b128 v[172:175], v209 offset:19456
	ds_read_b128 v[190:193], v209 offset:20480
	ds_read_b128 v[194:197], v209 offset:21504
	ds_read_b128 v[198:201], v209 offset:22528
	ds_read_b128 v[210:213], v209 offset:23552
	s_add_i32 s0, s95, s80
	s_mov_b32 m0, s0
	v_lshl_add_u64 v[202:203], s[8:9], 0, v[180:181]
	global_load_lds_dwordx4 v[202:203], off
	s_add_i32 m0, s0, 0x2000
	s_add_u32 s0, s8, 0x80000
	v_lshl_add_u64 v[214:215], s[8:9], 0, v[184:185]
	s_addc_u32 s1, s9, 0
	s_add_i32 s2, s96, s80
	global_load_lds_dwordx4 v[214:215], off
	v_lshl_add_u64 v[216:217], s[0:1], 0, v[180:181]
	s_mov_b32 m0, s2
	v_lshl_add_u64 v[218:219], s[10:11], 0, v[182:183]
	global_load_lds_dwordx4 v[216:217], off
	s_add_i32 m0, s2, 0x2000
	v_lshl_add_u64 v[216:217], s[0:1], 0, v[184:185]
	global_load_lds_dwordx4 v[216:217], off
	s_mov_b32 m0, s81
	v_lshl_add_u64 v[216:217], s[10:11], 0, v[178:179]
	global_load_lds_dwordx4 v[216:217], off
	s_mov_b32 m0, s82
	s_nop 0
	global_load_lds_dwordx4 v[218:219], off
	s_waitcnt vmcnt(8)
	s_waitcnt lgkmcnt(0)
	s_barrier
	s_setprio 1
	v_mfma_f32_16x16x32_bf16 v[92:95], v[128:131], v[160:163], v[92:95]
	v_mfma_f32_16x16x32_bf16 v[24:27], v[136:139], v[160:163], v[24:27]
	v_mfma_f32_16x16x32_bf16 v[84:87], v[128:131], v[168:171], v[84:87]
	v_mfma_f32_16x16x32_bf16 v[20:23], v[136:139], v[168:171], v[20:23]
	v_mfma_f32_16x16x32_bf16 v[76:79], v[128:131], v[190:193], v[76:79]
	v_mfma_f32_16x16x32_bf16 v[12:15], v[136:139], v[190:193], v[12:15]
	v_mfma_f32_16x16x32_bf16 v[72:75], v[128:131], v[198:201], v[72:75]
	v_mfma_f32_16x16x32_bf16 v[0:3], v[136:139], v[198:201], v[0:3]
	v_mfma_f32_16x16x32_bf16 v[92:95], v[132:135], v[164:167], v[92:95]
	v_mfma_f32_16x16x32_bf16 v[24:27], v[140:143], v[164:167], v[24:27]
	v_mfma_f32_16x16x32_bf16 v[84:87], v[132:135], v[172:175], v[84:87]
	v_mfma_f32_16x16x32_bf16 v[20:23], v[140:143], v[172:175], v[20:23]
	v_mfma_f32_16x16x32_bf16 v[76:79], v[132:135], v[194:197], v[76:79]
	v_mfma_f32_16x16x32_bf16 v[12:15], v[140:143], v[194:197], v[12:15]
	v_mfma_f32_16x16x32_bf16 v[72:75], v[132:135], v[210:213], v[72:75]
	v_mfma_f32_16x16x32_bf16 v[0:3], v[140:143], v[210:213], v[0:3]
	v_mfma_f32_16x16x32_bf16 v[88:91], v[144:147], v[160:163], v[88:91]
	v_mfma_f32_16x16x32_bf16 v[28:31], v[152:155], v[160:163], v[28:31]
	v_mfma_f32_16x16x32_bf16 v[80:83], v[144:147], v[168:171], v[80:83]
	v_mfma_f32_16x16x32_bf16 v[16:19], v[152:155], v[168:171], v[16:19]
	v_mfma_f32_16x16x32_bf16 v[68:71], v[144:147], v[190:193], v[68:71]
	v_mfma_f32_16x16x32_bf16 v[8:11], v[152:155], v[190:193], v[8:11]
	v_mfma_f32_16x16x32_bf16 v[64:67], v[144:147], v[198:201], v[64:67]
	v_mfma_f32_16x16x32_bf16 v[4:7], v[152:155], v[198:201], v[4:7]
	v_mfma_f32_16x16x32_bf16 v[88:91], v[148:151], v[164:167], v[88:91]
	v_mfma_f32_16x16x32_bf16 v[28:31], v[156:159], v[164:167], v[28:31]
	v_mfma_f32_16x16x32_bf16 v[80:83], v[148:151], v[172:175], v[80:83]
	v_mfma_f32_16x16x32_bf16 v[16:19], v[156:159], v[172:175], v[16:19]
	v_mfma_f32_16x16x32_bf16 v[68:71], v[148:151], v[194:197], v[68:71]
	v_mfma_f32_16x16x32_bf16 v[8:11], v[156:159], v[194:197], v[8:11]
	v_mfma_f32_16x16x32_bf16 v[64:67], v[148:151], v[210:213], v[64:67]
	v_mfma_f32_16x16x32_bf16 v[4:7], v[156:159], v[210:213], v[4:7]
	s_setprio 0
	s_barrier
	ds_read_b128 v[160:163], v209 offset:32768
	ds_read_b128 v[164:167], v209 offset:33792
	ds_read_b128 v[168:171], v209 offset:34816
	ds_read_b128 v[172:175], v209 offset:35840
	ds_read_b128 v[190:193], v209 offset:36864
	ds_read_b128 v[194:197], v209 offset:37888
	ds_read_b128 v[198:201], v209 offset:38912
	ds_read_b128 v[210:213], v209 offset:39936
	s_add_i32 s2, 0, 0x18000
	s_add_i32 s3, 0, 0x1c000
	v_add_u32_e32 v140, s2, v206
	v_add_u32_e32 v156, s3, v206
	ds_read_b128 v[128:131], v140
	ds_read_b128 v[132:135], v140 offset:1024
	ds_read_b128 v[136:139], v140 offset:2048
	ds_read_b128 v[140:143], v140 offset:3072
	ds_read_b128 v[144:147], v156
	ds_read_b128 v[148:151], v156 offset:1024
	ds_read_b128 v[152:155], v156 offset:2048
	ds_read_b128 v[156:159], v156 offset:3072
	s_add_u32 s0, s10, 0x80000
	s_addc_u32 s1, s11, 0
	s_mov_b32 m0, s83
	v_lshl_add_u64 v[220:221], s[0:1], 0, v[178:179]
	global_load_lds_dwordx4 v[220:221], off
	s_mov_b32 m0, s84
	v_lshl_add_u64 v[220:221], s[0:1], 0, v[182:183]
	global_load_lds_dwordx4 v[220:221], off
	s_waitcnt vmcnt(8)
	s_waitcnt lgkmcnt(0)
	s_barrier
	s_setprio 1
	v_mfma_f32_16x16x32_bf16 v[124:127], v[128:131], v[160:163], v[124:127]
	v_mfma_f32_16x16x32_bf16 v[56:59], v[136:139], v[160:163], v[56:59]
	v_mfma_f32_16x16x32_bf16 v[116:119], v[128:131], v[168:171], v[116:119]
	v_mfma_f32_16x16x32_bf16 v[52:55], v[136:139], v[168:171], v[52:55]
	v_mfma_f32_16x16x32_bf16 v[108:111], v[128:131], v[190:193], v[108:111]
	v_mfma_f32_16x16x32_bf16 v[44:47], v[136:139], v[190:193], v[44:47]
	v_mfma_f32_16x16x32_bf16 v[104:107], v[128:131], v[198:201], v[104:107]
	v_mfma_f32_16x16x32_bf16 v[32:35], v[136:139], v[198:201], v[32:35]
	v_mfma_f32_16x16x32_bf16 v[124:127], v[132:135], v[164:167], v[124:127]
	v_mfma_f32_16x16x32_bf16 v[56:59], v[140:143], v[164:167], v[56:59]
	v_mfma_f32_16x16x32_bf16 v[116:119], v[132:135], v[172:175], v[116:119]
	v_mfma_f32_16x16x32_bf16 v[52:55], v[140:143], v[172:175], v[52:55]
	v_mfma_f32_16x16x32_bf16 v[108:111], v[132:135], v[194:197], v[108:111]
	v_mfma_f32_16x16x32_bf16 v[44:47], v[140:143], v[194:197], v[44:47]
	v_mfma_f32_16x16x32_bf16 v[104:107], v[132:135], v[210:213], v[104:107]
	v_mfma_f32_16x16x32_bf16 v[32:35], v[140:143], v[210:213], v[32:35]
	v_mfma_f32_16x16x32_bf16 v[120:123], v[144:147], v[160:163], v[120:123]
	v_mfma_f32_16x16x32_bf16 v[60:63], v[152:155], v[160:163], v[60:63]
	v_mfma_f32_16x16x32_bf16 v[112:115], v[144:147], v[168:171], v[112:115]
	v_mfma_f32_16x16x32_bf16 v[48:51], v[152:155], v[168:171], v[48:51]
	v_mfma_f32_16x16x32_bf16 v[100:103], v[144:147], v[190:193], v[100:103]
	v_mfma_f32_16x16x32_bf16 v[40:43], v[152:155], v[190:193], v[40:43]
	v_mfma_f32_16x16x32_bf16 v[96:99], v[144:147], v[198:201], v[96:99]
	v_mfma_f32_16x16x32_bf16 v[36:39], v[152:155], v[198:201], v[36:39]
	v_mfma_f32_16x16x32_bf16 v[120:123], v[148:151], v[164:167], v[120:123]
	v_mfma_f32_16x16x32_bf16 v[60:63], v[156:159], v[164:167], v[60:63]
	v_mfma_f32_16x16x32_bf16 v[112:115], v[148:151], v[172:175], v[112:115]
	v_mfma_f32_16x16x32_bf16 v[48:51], v[156:159], v[172:175], v[48:51]
	v_mfma_f32_16x16x32_bf16 v[100:103], v[148:151], v[194:197], v[100:103]
	v_mfma_f32_16x16x32_bf16 v[40:43], v[156:159], v[194:197], v[40:43]
	v_mfma_f32_16x16x32_bf16 v[96:99], v[148:151], v[210:213], v[96:99]
	v_mfma_f32_16x16x32_bf16 v[36:39], v[156:159], v[210:213], v[36:39]
	s_setprio 0
	s_barrier
	ds_read_b128 v[160:163], v209 offset:49152
	ds_read_b128 v[164:167], v209 offset:50176
	ds_read_b128 v[168:171], v209 offset:51200
	ds_read_b128 v[172:175], v209 offset:52224
	ds_read_b128 v[190:193], v209 offset:53248
	ds_read_b128 v[194:197], v209 offset:54272
	ds_read_b128 v[198:201], v209 offset:55296
	ds_read_b128 v[210:213], v209 offset:56320
	s_add_i32 s0, s2, s80
	s_mov_b32 m0, s0
	v_lshl_add_u64 v[202:203], v[202:203], 0, s[24:25]
	global_load_lds_dwordx4 v[202:203], off
	s_add_i32 m0, s0, 0x2000
	s_add_u32 s0, s8, 0x80080
	v_lshl_add_u64 v[202:203], v[214:215], 0, s[24:25]
	s_addc_u32 s1, s9, 0
	s_add_i32 s2, s3, s80
	global_load_lds_dwordx4 v[202:203], off
	s_mov_b32 m0, s2
	v_lshl_add_u64 v[202:203], s[0:1], 0, v[180:181]
	global_load_lds_dwordx4 v[202:203], off
	s_add_i32 m0, s2, 0x2000
	v_lshl_add_u64 v[202:203], s[0:1], 0, v[184:185]
	global_load_lds_dwordx4 v[202:203], off
	s_mov_b32 m0, s90
	v_lshl_add_u64 v[202:203], v[216:217], 0, s[24:25]
	global_load_lds_dwordx4 v[202:203], off
	s_mov_b32 m0, s91
	v_lshl_add_u64 v[202:203], v[218:219], 0, s[24:25]
	global_load_lds_dwordx4 v[202:203], off
	s_waitcnt vmcnt(8)
	s_waitcnt lgkmcnt(0)
	s_barrier
	s_setprio 1
	v_mfma_f32_16x16x32_bf16 v[92:95], v[128:131], v[160:163], v[92:95]
	v_mfma_f32_16x16x32_bf16 v[24:27], v[136:139], v[160:163], v[24:27]
	v_mfma_f32_16x16x32_bf16 v[84:87], v[128:131], v[168:171], v[84:87]
	v_mfma_f32_16x16x32_bf16 v[20:23], v[136:139], v[168:171], v[20:23]
	v_mfma_f32_16x16x32_bf16 v[76:79], v[128:131], v[190:193], v[76:79]
	v_mfma_f32_16x16x32_bf16 v[12:15], v[136:139], v[190:193], v[12:15]
	v_mfma_f32_16x16x32_bf16 v[72:75], v[128:131], v[198:201], v[72:75]
	v_mfma_f32_16x16x32_bf16 v[0:3], v[136:139], v[198:201], v[0:3]
	v_mfma_f32_16x16x32_bf16 v[92:95], v[132:135], v[164:167], v[92:95]
	v_mfma_f32_16x16x32_bf16 v[24:27], v[140:143], v[164:167], v[24:27]
	v_mfma_f32_16x16x32_bf16 v[84:87], v[132:135], v[172:175], v[84:87]
	v_mfma_f32_16x16x32_bf16 v[20:23], v[140:143], v[172:175], v[20:23]
	v_mfma_f32_16x16x32_bf16 v[76:79], v[132:135], v[194:197], v[76:79]
	v_mfma_f32_16x16x32_bf16 v[12:15], v[140:143], v[194:197], v[12:15]
	v_mfma_f32_16x16x32_bf16 v[72:75], v[132:135], v[210:213], v[72:75]
	v_mfma_f32_16x16x32_bf16 v[0:3], v[140:143], v[210:213], v[0:3]
	v_mfma_f32_16x16x32_bf16 v[88:91], v[144:147], v[160:163], v[88:91]
	v_mfma_f32_16x16x32_bf16 v[28:31], v[152:155], v[160:163], v[28:31]
	v_mfma_f32_16x16x32_bf16 v[80:83], v[144:147], v[168:171], v[80:83]
	v_mfma_f32_16x16x32_bf16 v[16:19], v[152:155], v[168:171], v[16:19]
	v_mfma_f32_16x16x32_bf16 v[68:71], v[144:147], v[190:193], v[68:71]
	v_mfma_f32_16x16x32_bf16 v[8:11], v[152:155], v[190:193], v[8:11]
	v_mfma_f32_16x16x32_bf16 v[64:67], v[144:147], v[198:201], v[64:67]
	v_mfma_f32_16x16x32_bf16 v[4:7], v[152:155], v[198:201], v[4:7]
	v_mfma_f32_16x16x32_bf16 v[88:91], v[148:151], v[164:167], v[88:91]
	v_mfma_f32_16x16x32_bf16 v[28:31], v[156:159], v[164:167], v[28:31]
	v_mfma_f32_16x16x32_bf16 v[80:83], v[148:151], v[172:175], v[80:83]
	v_mfma_f32_16x16x32_bf16 v[16:19], v[156:159], v[172:175], v[16:19]
	v_mfma_f32_16x16x32_bf16 v[68:71], v[148:151], v[194:197], v[68:71]
	v_mfma_f32_16x16x32_bf16 v[8:11], v[156:159], v[194:197], v[8:11]
	v_mfma_f32_16x16x32_bf16 v[64:67], v[148:151], v[210:213], v[64:67]
	v_mfma_f32_16x16x32_bf16 v[4:7], v[156:159], v[210:213], v[4:7]
	s_setprio 0
	s_barrier
	s_add_i32 vcc_hi, vcc_hi, 2
	s_add_u32 s4, s4, 0x100
	s_addc_u32 s5, s5, 0
	s_add_u32 s65, s65, 0x100
	s_addc_u32 vcc_lo, vcc_lo, 0
	s_cmp_gt_u32 vcc_hi, 29
	s_cbranch_scc0 .LBB0_399
	s_and_b64 vcc, exec, s[26:27]
	s_cbranch_vccz .LBB0_402
	s_barrier

.LBB0_541:
	ds_read_b128 v[128:131], v157
	ds_read_b128 v[132:135], v157 offset:1024
	ds_read_b128 v[136:139], v157 offset:2048
	ds_read_b128 v[140:143], v157 offset:3072
	ds_read_b128 v[160:163], v158
	ds_read_b128 v[164:167], v158 offset:1024
	ds_read_b128 v[168:171], v158 offset:2048
	ds_read_b128 v[172:175], v158 offset:3072
	ds_read_b128 v[178:181], v159
	ds_read_b128 v[182:185], v159 offset:1024
	ds_read_b128 v[186:189], v159 offset:2048
	ds_read_b128 v[190:193], v159 offset:3072
	ds_read_b128 v[194:197], v159 offset:4096
	ds_read_b128 v[206:209], v159 offset:5120
	ds_read_b128 v[210:213], v159 offset:6144
	ds_read_b128 v[214:217], v159 offset:7168
	s_add_u32 s58, s56, 0x100
	s_addc_u32 s59, s57, 0
	s_cmpk_eq_i32 s89, 0x54
	s_cselect_b32 s63, s12, s59
	s_cselect_b32 s62, s55, s58
	s_cselect_b32 s61, s85, s88
	s_cselect_b32 s60, s86, s87
	s_add_i32 m0, s66, 0xc000
	v_lshl_add_u64 v[152:153], s[56:57], 0, v[148:149]
	global_load_lds_dwordx4 v[152:153], off
	s_add_i32 m0, s66, 0xe000
	v_lshl_add_u64 v[152:153], s[56:57], 0, v[150:151]
	global_load_lds_dwordx4 v[152:153], off
	s_waitcnt vmcnt(8)
	s_waitcnt lgkmcnt(0)
	s_barrier
	s_setprio 1
	v_mfma_f32_16x16x32_bf16 v[124:127], v[128:131], v[178:181], v[124:127]
	v_mfma_f32_16x16x32_bf16 v[120:123], v[136:139], v[178:181], v[120:123]
	v_mfma_f32_16x16x32_bf16 v[112:115], v[128:131], v[186:189], v[112:115]
	v_mfma_f32_16x16x32_bf16 v[108:111], v[136:139], v[186:189], v[108:111]
	v_mfma_f32_16x16x32_bf16 v[96:99], v[128:131], v[194:197], v[96:99]
	v_mfma_f32_16x16x32_bf16 v[92:95], v[136:139], v[194:197], v[92:95]
	v_mfma_f32_16x16x32_bf16 v[80:83], v[128:131], v[210:213], v[80:83]
	v_mfma_f32_16x16x32_bf16 v[76:79], v[136:139], v[210:213], v[76:79]
	v_mfma_f32_16x16x32_bf16 v[124:127], v[132:135], v[182:185], v[124:127]
	v_mfma_f32_16x16x32_bf16 v[120:123], v[140:143], v[182:185], v[120:123]
	v_mfma_f32_16x16x32_bf16 v[112:115], v[132:135], v[190:193], v[112:115]
	v_mfma_f32_16x16x32_bf16 v[108:111], v[140:143], v[190:193], v[108:111]
	v_mfma_f32_16x16x32_bf16 v[96:99], v[132:135], v[206:209], v[96:99]
	v_mfma_f32_16x16x32_bf16 v[92:95], v[140:143], v[206:209], v[92:95]
	v_mfma_f32_16x16x32_bf16 v[80:83], v[132:135], v[214:217], v[80:83]
	v_mfma_f32_16x16x32_bf16 v[76:79], v[140:143], v[214:217], v[76:79]
	v_mfma_f32_16x16x32_bf16 v[116:119], v[160:163], v[178:181], v[116:119]
	v_mfma_f32_16x16x32_bf16 v[104:107], v[168:171], v[178:181], v[104:107]
	v_mfma_f32_16x16x32_bf16 v[100:103], v[160:163], v[186:189], v[100:103]
	v_mfma_f32_16x16x32_bf16 v[88:91], v[168:171], v[186:189], v[88:91]
	v_mfma_f32_16x16x32_bf16 v[84:87], v[160:163], v[194:197], v[84:87]
	v_mfma_f32_16x16x32_bf16 v[72:75], v[168:171], v[194:197], v[72:75]
	v_mfma_f32_16x16x32_bf16 v[68:71], v[160:163], v[210:213], v[68:71]
	v_mfma_f32_16x16x32_bf16 v[64:67], v[168:171], v[210:213], v[64:67]
	v_mfma_f32_16x16x32_bf16 v[116:119], v[164:167], v[182:185], v[116:119]
	v_mfma_f32_16x16x32_bf16 v[104:107], v[172:175], v[182:185], v[104:107]
	v_mfma_f32_16x16x32_bf16 v[100:103], v[164:167], v[190:193], v[100:103]
	v_mfma_f32_16x16x32_bf16 v[88:91], v[172:175], v[190:193], v[88:91]
	v_mfma_f32_16x16x32_bf16 v[84:87], v[164:167], v[206:209], v[84:87]
	v_mfma_f32_16x16x32_bf16 v[72:75], v[172:175], v[206:209], v[72:75]
	v_mfma_f32_16x16x32_bf16 v[68:71], v[164:167], v[214:217], v[68:71]
	v_mfma_f32_16x16x32_bf16 v[64:67], v[172:175], v[214:217], v[64:67]
	s_setprio 0
	s_barrier
	ds_read_b128 v[178:181], v159 offset:16384
	ds_read_b128 v[182:185], v159 offset:17408
	ds_read_b128 v[186:189], v159 offset:18432
	ds_read_b128 v[190:193], v159 offset:19456
	ds_read_b128 v[194:197], v159 offset:20480
	ds_read_b128 v[206:209], v159 offset:21504
	ds_read_b128 v[210:213], v159 offset:22528
	ds_read_b128 v[214:217], v159 offset:23552
	s_add_i32 s0, s79, s65
	s_mov_b32 m0, s0
	v_lshl_add_u64 v[152:153], s[60:61], 0, v[146:147]
	global_load_lds_dwordx4 v[152:153], off
	s_add_i32 m0, s0, 0x2000
	s_add_u32 s0, s60, 0x160000
	v_lshl_add_u64 v[198:199], s[60:61], 0, v[144:145]
	s_addc_u32 s1, s61, 0
	s_add_i32 s2, s80, s65
	global_load_lds_dwordx4 v[198:199], off
	v_lshl_add_u64 v[202:203], s[0:1], 0, v[146:147]
	s_mov_b32 m0, s2
	v_lshl_add_u64 v[218:219], s[62:63], 0, v[144:145]
	global_load_lds_dwordx4 v[202:203], off
	s_add_i32 m0, s2, 0x2000
	v_lshl_add_u64 v[202:203], s[0:1], 0, v[144:145]
	global_load_lds_dwordx4 v[202:203], off
	s_mov_b32 m0, s66
	v_lshl_add_u64 v[202:203], s[62:63], 0, v[146:147]
	global_load_lds_dwordx4 v[202:203], off
	s_mov_b32 m0, s67
	s_nop 0
	global_load_lds_dwordx4 v[218:219], off
	s_waitcnt vmcnt(8)
	s_waitcnt lgkmcnt(0)
	s_barrier
	s_setprio 1
	v_mfma_f32_16x16x32_bf16 v[60:63], v[128:131], v[178:181], v[60:63]
	v_mfma_f32_16x16x32_bf16 v[56:59], v[136:139], v[178:181], v[56:59]
	v_mfma_f32_16x16x32_bf16 v[48:51], v[128:131], v[186:189], v[48:51]
	v_mfma_f32_16x16x32_bf16 v[44:47], v[136:139], v[186:189], v[44:47]
	v_mfma_f32_16x16x32_bf16 v[32:35], v[128:131], v[194:197], v[32:35]
	v_mfma_f32_16x16x32_bf16 v[28:31], v[136:139], v[194:197], v[28:31]
	v_mfma_f32_16x16x32_bf16 v[16:19], v[128:131], v[210:213], v[16:19]
	v_mfma_f32_16x16x32_bf16 v[12:15], v[136:139], v[210:213], v[12:15]
	v_mfma_f32_16x16x32_bf16 v[60:63], v[132:135], v[182:185], v[60:63]
	v_mfma_f32_16x16x32_bf16 v[56:59], v[140:143], v[182:185], v[56:59]
	v_mfma_f32_16x16x32_bf16 v[48:51], v[132:135], v[190:193], v[48:51]
	v_mfma_f32_16x16x32_bf16 v[44:47], v[140:143], v[190:193], v[44:47]
	v_mfma_f32_16x16x32_bf16 v[32:35], v[132:135], v[206:209], v[32:35]
	v_mfma_f32_16x16x32_bf16 v[28:31], v[140:143], v[206:209], v[28:31]
	v_mfma_f32_16x16x32_bf16 v[16:19], v[132:135], v[214:217], v[16:19]
	v_mfma_f32_16x16x32_bf16 v[12:15], v[140:143], v[214:217], v[12:15]
	v_mfma_f32_16x16x32_bf16 v[52:55], v[160:163], v[178:181], v[52:55]
	v_mfma_f32_16x16x32_bf16 v[40:43], v[168:171], v[178:181], v[40:43]
	v_mfma_f32_16x16x32_bf16 v[36:39], v[160:163], v[186:189], v[36:39]
	v_mfma_f32_16x16x32_bf16 v[24:27], v[168:171], v[186:189], v[24:27]
	v_mfma_f32_16x16x32_bf16 v[20:23], v[160:163], v[194:197], v[20:23]
	v_mfma_f32_16x16x32_bf16 v[8:11], v[168:171], v[194:197], v[8:11]
	v_mfma_f32_16x16x32_bf16 v[4:7], v[160:163], v[210:213], v[4:7]
	v_mfma_f32_16x16x32_bf16 v[0:3], v[168:171], v[210:213], v[0:3]
	v_mfma_f32_16x16x32_bf16 v[52:55], v[164:167], v[182:185], v[52:55]
	v_mfma_f32_16x16x32_bf16 v[40:43], v[172:175], v[182:185], v[40:43]
	v_mfma_f32_16x16x32_bf16 v[36:39], v[164:167], v[190:193], v[36:39]
	v_mfma_f32_16x16x32_bf16 v[24:27], v[172:175], v[190:193], v[24:27]
	v_mfma_f32_16x16x32_bf16 v[20:23], v[164:167], v[206:209], v[20:23]
	v_mfma_f32_16x16x32_bf16 v[8:11], v[172:175], v[206:209], v[8:11]
	v_mfma_f32_16x16x32_bf16 v[4:7], v[164:167], v[214:217], v[4:7]
	v_mfma_f32_16x16x32_bf16 v[0:3], v[172:175], v[214:217], v[0:3]
	s_setprio 0
	s_barrier
	ds_read_b128 v[178:181], v159 offset:32768
	ds_read_b128 v[182:185], v159 offset:33792
	ds_read_b128 v[186:189], v159 offset:34816
	ds_read_b128 v[190:193], v159 offset:35840
	ds_read_b128 v[194:197], v159 offset:36864
	ds_read_b128 v[206:209], v159 offset:37888
	ds_read_b128 v[210:213], v159 offset:38912
	ds_read_b128 v[214:217], v159 offset:39936
	s_add_i32 s2, 0, 0x18000
	s_add_i32 s3, 0, 0x1c000
	v_add_u32_e32 v140, s2, v156
	v_add_u32_e32 v172, s3, v156
	ds_read_b128 v[128:131], v140
	ds_read_b128 v[132:135], v140 offset:1024
	ds_read_b128 v[136:139], v140 offset:2048
	ds_read_b128 v[140:143], v140 offset:3072
	ds_read_b128 v[160:163], v172
	ds_read_b128 v[164:167], v172 offset:1024
	ds_read_b128 v[168:171], v172 offset:2048
	ds_read_b128 v[172:175], v172 offset:3072
	s_add_u32 s0, s62, 0x160000
	s_addc_u32 s1, s63, 0
	s_mov_b32 m0, s68
	v_lshl_add_u64 v[220:221], s[0:1], 0, v[146:147]
	global_load_lds_dwordx4 v[220:221], off
	s_mov_b32 m0, s69
	v_lshl_add_u64 v[220:221], s[0:1], 0, v[144:145]
	global_load_lds_dwordx4 v[220:221], off
	s_waitcnt vmcnt(8)
	s_waitcnt lgkmcnt(0)
	s_barrier
	s_setprio 1
	v_mfma_f32_16x16x32_bf16 v[124:127], v[128:131], v[178:181], v[124:127]
	v_mfma_f32_16x16x32_bf16 v[120:123], v[136:139], v[178:181], v[120:123]
	v_mfma_f32_16x16x32_bf16 v[112:115], v[128:131], v[186:189], v[112:115]
	v_mfma_f32_16x16x32_bf16 v[108:111], v[136:139], v[186:189], v[108:111]
	v_mfma_f32_16x16x32_bf16 v[96:99], v[128:131], v[194:197], v[96:99]
	v_mfma_f32_16x16x32_bf16 v[92:95], v[136:139], v[194:197], v[92:95]
	v_mfma_f32_16x16x32_bf16 v[80:83], v[128:131], v[210:213], v[80:83]
	v_mfma_f32_16x16x32_bf16 v[76:79], v[136:139], v[210:213], v[76:79]
	v_mfma_f32_16x16x32_bf16 v[124:127], v[132:135], v[182:185], v[124:127]
	v_mfma_f32_16x16x32_bf16 v[120:123], v[140:143], v[182:185], v[120:123]
	v_mfma_f32_16x16x32_bf16 v[112:115], v[132:135], v[190:193], v[112:115]
	v_mfma_f32_16x16x32_bf16 v[108:111], v[140:143], v[190:193], v[108:111]
	v_mfma_f32_16x16x32_bf16 v[96:99], v[132:135], v[206:209], v[96:99]
	v_mfma_f32_16x16x32_bf16 v[92:95], v[140:143], v[206:209], v[92:95]
	v_mfma_f32_16x16x32_bf16 v[80:83], v[132:135], v[214:217], v[80:83]
	v_mfma_f32_16x16x32_bf16 v[76:79], v[140:143], v[214:217], v[76:79]
	v_mfma_f32_16x16x32_bf16 v[116:119], v[160:163], v[178:181], v[116:119]
	v_mfma_f32_16x16x32_bf16 v[104:107], v[168:171], v[178:181], v[104:107]
	v_mfma_f32_16x16x32_bf16 v[100:103], v[160:163], v[186:189], v[100:103]
	v_mfma_f32_16x16x32_bf16 v[88:91], v[168:171], v[186:189], v[88:91]
	v_mfma_f32_16x16x32_bf16 v[84:87], v[160:163], v[194:197], v[84:87]
	v_mfma_f32_16x16x32_bf16 v[72:75], v[168:171], v[194:197], v[72:75]
	v_mfma_f32_16x16x32_bf16 v[68:71], v[160:163], v[210:213], v[68:71]
	v_mfma_f32_16x16x32_bf16 v[64:67], v[168:171], v[210:213], v[64:67]
	v_mfma_f32_16x16x32_bf16 v[116:119], v[164:167], v[182:185], v[116:119]
	v_mfma_f32_16x16x32_bf16 v[104:107], v[172:175], v[182:185], v[104:107]
	v_mfma_f32_16x16x32_bf16 v[100:103], v[164:167], v[190:193], v[100:103]
	v_mfma_f32_16x16x32_bf16 v[88:91], v[172:175], v[190:193], v[88:91]
	v_mfma_f32_16x16x32_bf16 v[84:87], v[164:167], v[206:209], v[84:87]
	v_mfma_f32_16x16x32_bf16 v[72:75], v[172:175], v[206:209], v[72:75]
	v_mfma_f32_16x16x32_bf16 v[68:71], v[164:167], v[214:217], v[68:71]
	v_mfma_f32_16x16x32_bf16 v[64:67], v[172:175], v[214:217], v[64:67]
	s_setprio 0
	s_barrier
	ds_read_b128 v[178:181], v159 offset:49152
	ds_read_b128 v[182:185], v159 offset:50176
	ds_read_b128 v[186:189], v159 offset:51200
	ds_read_b128 v[190:193], v159 offset:52224
	ds_read_b128 v[194:197], v159 offset:53248
	ds_read_b128 v[206:209], v159 offset:54272
	ds_read_b128 v[210:213], v159 offset:55296
	ds_read_b128 v[214:217], v159 offset:56320
	s_add_i32 s0, s2, s65
	s_mov_b32 m0, s0
	v_lshl_add_u64 v[152:153], v[152:153], 0, s[10:11]
	global_load_lds_dwordx4 v[152:153], off
	s_add_i32 m0, s0, 0x2000
	s_add_u32 s0, s60, 0x160080
	v_lshl_add_u64 v[152:153], v[198:199], 0, s[10:11]
	s_addc_u32 s1, s61, 0
	s_add_i32 s2, s3, s65
	global_load_lds_dwordx4 v[152:153], off
	s_mov_b32 m0, s2
	v_lshl_add_u64 v[152:153], s[0:1], 0, v[146:147]
	global_load_lds_dwordx4 v[152:153], off
	s_add_i32 m0, s2, 0x2000
	v_lshl_add_u64 v[152:153], s[0:1], 0, v[144:145]
	global_load_lds_dwordx4 v[152:153], off
	s_mov_b32 m0, s77
	v_lshl_add_u64 v[152:153], v[202:203], 0, s[10:11]
	global_load_lds_dwordx4 v[152:153], off
	s_mov_b32 m0, s78
	v_lshl_add_u64 v[152:153], v[218:219], 0, s[10:11]
	global_load_lds_dwordx4 v[152:153], off
	s_waitcnt vmcnt(8)
	s_waitcnt lgkmcnt(0)
	s_barrier
	s_setprio 1
	v_mfma_f32_16x16x32_bf16 v[60:63], v[128:131], v[178:181], v[60:63]
	v_mfma_f32_16x16x32_bf16 v[56:59], v[136:139], v[178:181], v[56:59]
	v_mfma_f32_16x16x32_bf16 v[48:51], v[128:131], v[186:189], v[48:51]
	v_mfma_f32_16x16x32_bf16 v[44:47], v[136:139], v[186:189], v[44:47]
	v_mfma_f32_16x16x32_bf16 v[32:35], v[128:131], v[194:197], v[32:35]
	v_mfma_f32_16x16x32_bf16 v[28:31], v[136:139], v[194:197], v[28:31]
	v_mfma_f32_16x16x32_bf16 v[16:19], v[128:131], v[210:213], v[16:19]
	v_mfma_f32_16x16x32_bf16 v[12:15], v[136:139], v[210:213], v[12:15]
	v_mfma_f32_16x16x32_bf16 v[60:63], v[132:135], v[182:185], v[60:63]
	v_mfma_f32_16x16x32_bf16 v[56:59], v[140:143], v[182:185], v[56:59]
	v_mfma_f32_16x16x32_bf16 v[48:51], v[132:135], v[190:193], v[48:51]
	v_mfma_f32_16x16x32_bf16 v[44:47], v[140:143], v[190:193], v[44:47]
	v_mfma_f32_16x16x32_bf16 v[32:35], v[132:135], v[206:209], v[32:35]
	v_mfma_f32_16x16x32_bf16 v[28:31], v[140:143], v[206:209], v[28:31]
	v_mfma_f32_16x16x32_bf16 v[16:19], v[132:135], v[214:217], v[16:19]
	v_mfma_f32_16x16x32_bf16 v[12:15], v[140:143], v[214:217], v[12:15]
	v_mfma_f32_16x16x32_bf16 v[52:55], v[160:163], v[178:181], v[52:55]
	v_mfma_f32_16x16x32_bf16 v[40:43], v[168:171], v[178:181], v[40:43]
	v_mfma_f32_16x16x32_bf16 v[36:39], v[160:163], v[186:189], v[36:39]
	v_mfma_f32_16x16x32_bf16 v[24:27], v[168:171], v[186:189], v[24:27]
	v_mfma_f32_16x16x32_bf16 v[20:23], v[160:163], v[194:197], v[20:23]
	v_mfma_f32_16x16x32_bf16 v[8:11], v[168:171], v[194:197], v[8:11]
	v_mfma_f32_16x16x32_bf16 v[4:7], v[160:163], v[210:213], v[4:7]
	v_mfma_f32_16x16x32_bf16 v[0:3], v[168:171], v[210:213], v[0:3]
	v_mfma_f32_16x16x32_bf16 v[52:55], v[164:167], v[182:185], v[52:55]
	v_mfma_f32_16x16x32_bf16 v[40:43], v[172:175], v[182:185], v[40:43]
	v_mfma_f32_16x16x32_bf16 v[36:39], v[164:167], v[190:193], v[36:39]
	v_mfma_f32_16x16x32_bf16 v[24:27], v[172:175], v[190:193], v[24:27]
	v_mfma_f32_16x16x32_bf16 v[20:23], v[164:167], v[206:209], v[20:23]
	v_mfma_f32_16x16x32_bf16 v[8:11], v[172:175], v[206:209], v[8:11]
	v_mfma_f32_16x16x32_bf16 v[4:7], v[164:167], v[214:217], v[4:7]
	v_mfma_f32_16x16x32_bf16 v[0:3], v[172:175], v[214:217], v[0:3]
	s_setprio 0
	s_barrier
	s_add_i32 s89, s89, 2
	s_add_u32 s87, s87, 0x100
	s_addc_u32 s88, s88, 0
	s_cmpk_gt_u32 s89, 0x55
	s_mov_b64 s[56:57], s[58:59]
	s_cbranch_scc0 .LBB0_541
	s_and_b64 vcc, exec, s[14:15]
	s_cbranch_vccz .LBB0_544
	s_barrier

.LBB0_666:
	ds_read_b128 v[140:143], v147
	ds_read_b128 v[150:153], v147 offset:1024
	ds_read_b128 v[154:157], v147 offset:2048
	ds_read_b128 v[158:161], v147 offset:3072
	ds_read_b128 v[162:165], v148
	ds_read_b128 v[166:169], v148 offset:1024
	ds_read_b128 v[170:173], v148 offset:2048
	ds_read_b128 v[178:181], v148 offset:3072
	ds_read_b128 v[182:185], v149
	ds_read_b128 v[186:189], v149 offset:1024
	ds_read_b128 v[190:193], v149 offset:2048
	ds_read_b128 v[194:197], v149 offset:3072
	ds_read_b128 v[206:209], v149 offset:4096
	ds_read_b128 v[210:213], v149 offset:5120
	ds_read_b128 v[214:217], v149 offset:6144
	ds_read_b128 v[218:221], v149 offset:7168
	s_add_u32 s0, s28, 0xfff80080
	s_addc_u32 s1, s29, -1
	s_cmp_eq_u32 s71, 28
	s_cselect_b32 s35, s15, s1
	s_cselect_b32 s34, s66, s0
	s_cselect_b32 s31, s67, s70
	s_cselect_b32 s30, s68, s69
	s_add_i32 m0, s27, 0xc000
	v_lshl_add_u64 v[174:175], s[28:29], 0, v[136:137]
	global_load_lds_dwordx4 v[174:175], off
	s_add_i32 m0, s27, 0xe000
	v_lshl_add_u64 v[174:175], s[28:29], 0, v[138:139]
	global_load_lds_dwordx4 v[174:175], off
	s_waitcnt vmcnt(8)
	s_waitcnt lgkmcnt(0)
	s_barrier
	s_setprio 1
	v_mfma_f32_16x16x32_bf16 v[124:127], v[140:143], v[182:185], v[124:127]
	v_mfma_f32_16x16x32_bf16 v[120:123], v[154:157], v[182:185], v[120:123]
	v_mfma_f32_16x16x32_bf16 v[116:119], v[140:143], v[190:193], v[116:119]
	v_mfma_f32_16x16x32_bf16 v[108:111], v[154:157], v[190:193], v[108:111]
	v_mfma_f32_16x16x32_bf16 v[100:103], v[140:143], v[206:209], v[100:103]
	v_mfma_f32_16x16x32_bf16 v[92:95], v[154:157], v[206:209], v[92:95]
	v_mfma_f32_16x16x32_bf16 v[84:87], v[140:143], v[214:217], v[84:87]
	v_mfma_f32_16x16x32_bf16 v[76:79], v[154:157], v[214:217], v[76:79]
	v_mfma_f32_16x16x32_bf16 v[124:127], v[150:153], v[186:189], v[124:127]
	v_mfma_f32_16x16x32_bf16 v[120:123], v[158:161], v[186:189], v[120:123]
	v_mfma_f32_16x16x32_bf16 v[116:119], v[150:153], v[194:197], v[116:119]
	v_mfma_f32_16x16x32_bf16 v[108:111], v[158:161], v[194:197], v[108:111]
	v_mfma_f32_16x16x32_bf16 v[100:103], v[150:153], v[210:213], v[100:103]
	v_mfma_f32_16x16x32_bf16 v[92:95], v[158:161], v[210:213], v[92:95]
	v_mfma_f32_16x16x32_bf16 v[84:87], v[150:153], v[218:221], v[84:87]
	v_mfma_f32_16x16x32_bf16 v[76:79], v[158:161], v[218:221], v[76:79]
	v_mfma_f32_16x16x32_bf16 v[112:115], v[162:165], v[182:185], v[112:115]
	v_mfma_f32_16x16x32_bf16 v[104:107], v[170:173], v[182:185], v[104:107]
	v_mfma_f32_16x16x32_bf16 v[96:99], v[162:165], v[190:193], v[96:99]
	v_mfma_f32_16x16x32_bf16 v[88:91], v[170:173], v[190:193], v[88:91]
	v_mfma_f32_16x16x32_bf16 v[80:83], v[162:165], v[206:209], v[80:83]
	v_mfma_f32_16x16x32_bf16 v[72:75], v[170:173], v[206:209], v[72:75]
	v_mfma_f32_16x16x32_bf16 v[68:71], v[162:165], v[214:217], v[68:71]
	v_mfma_f32_16x16x32_bf16 v[64:67], v[170:173], v[214:217], v[64:67]
	v_mfma_f32_16x16x32_bf16 v[112:115], v[166:169], v[186:189], v[112:115]
	v_mfma_f32_16x16x32_bf16 v[104:107], v[178:181], v[186:189], v[104:107]
	v_mfma_f32_16x16x32_bf16 v[96:99], v[166:169], v[194:197], v[96:99]
	v_mfma_f32_16x16x32_bf16 v[88:91], v[178:181], v[194:197], v[88:91]
	v_mfma_f32_16x16x32_bf16 v[80:83], v[166:169], v[210:213], v[80:83]
	v_mfma_f32_16x16x32_bf16 v[72:75], v[178:181], v[210:213], v[72:75]
	v_mfma_f32_16x16x32_bf16 v[68:71], v[166:169], v[218:221], v[68:71]
	v_mfma_f32_16x16x32_bf16 v[64:67], v[178:181], v[218:221], v[64:67]
	s_setprio 0
	s_barrier
	ds_read_b128 v[182:185], v149 offset:16384
	ds_read_b128 v[186:189], v149 offset:17408
	ds_read_b128 v[190:193], v149 offset:18432
	ds_read_b128 v[194:197], v149 offset:19456
	ds_read_b128 v[206:209], v149 offset:20480
	ds_read_b128 v[210:213], v149 offset:21504
	ds_read_b128 v[214:217], v149 offset:22528
	ds_read_b128 v[218:221], v149 offset:23552
	s_add_i32 s0, s62, s53
	s_mov_b32 m0, s0
	v_lshl_add_u64 v[174:175], s[30:31], 0, v[132:133]
	global_load_lds_dwordx4 v[174:175], off
	s_add_i32 m0, s0, 0x2000
	s_add_u32 s0, s30, 0x80000
	v_lshl_add_u64 v[198:199], s[30:31], 0, v[128:129]
	s_addc_u32 s1, s31, 0
	s_add_i32 s2, s63, s53
	global_load_lds_dwordx4 v[198:199], off
	v_lshl_add_u64 v[202:203], s[0:1], 0, v[132:133]
	s_mov_b32 m0, s2
	v_lshl_add_u64 v[222:223], s[34:35], 0, v[130:131]
	global_load_lds_dwordx4 v[202:203], off
	s_add_i32 m0, s2, 0x2000
	v_lshl_add_u64 v[202:203], s[0:1], 0, v[128:129]
	global_load_lds_dwordx4 v[202:203], off
	s_mov_b32 m0, s27
	v_lshl_add_u64 v[202:203], s[34:35], 0, v[134:135]
	global_load_lds_dwordx4 v[202:203], off
	s_mov_b32 m0, s55
	s_nop 0
	global_load_lds_dwordx4 v[222:223], off
	s_waitcnt vmcnt(8)
	s_waitcnt lgkmcnt(0)
	s_barrier
	s_setprio 1
	v_mfma_f32_16x16x32_bf16 v[60:63], v[140:143], v[182:185], v[60:63]
	v_mfma_f32_16x16x32_bf16 v[56:59], v[154:157], v[182:185], v[56:59]
	v_mfma_f32_16x16x32_bf16 v[52:55], v[140:143], v[190:193], v[52:55]
	v_mfma_f32_16x16x32_bf16 v[44:47], v[154:157], v[190:193], v[44:47]
	v_mfma_f32_16x16x32_bf16 v[36:39], v[140:143], v[206:209], v[36:39]
	v_mfma_f32_16x16x32_bf16 v[28:31], v[154:157], v[206:209], v[28:31]
	v_mfma_f32_16x16x32_bf16 v[20:23], v[140:143], v[214:217], v[20:23]
	v_mfma_f32_16x16x32_bf16 v[12:15], v[154:157], v[214:217], v[12:15]
	v_mfma_f32_16x16x32_bf16 v[60:63], v[150:153], v[186:189], v[60:63]
	v_mfma_f32_16x16x32_bf16 v[56:59], v[158:161], v[186:189], v[56:59]
	v_mfma_f32_16x16x32_bf16 v[52:55], v[150:153], v[194:197], v[52:55]
	v_mfma_f32_16x16x32_bf16 v[44:47], v[158:161], v[194:197], v[44:47]
	v_mfma_f32_16x16x32_bf16 v[36:39], v[150:153], v[210:213], v[36:39]
	v_mfma_f32_16x16x32_bf16 v[28:31], v[158:161], v[210:213], v[28:31]
	v_mfma_f32_16x16x32_bf16 v[20:23], v[150:153], v[218:221], v[20:23]
	v_mfma_f32_16x16x32_bf16 v[12:15], v[158:161], v[218:221], v[12:15]
	v_mfma_f32_16x16x32_bf16 v[48:51], v[162:165], v[182:185], v[48:51]
	v_mfma_f32_16x16x32_bf16 v[40:43], v[170:173], v[182:185], v[40:43]
	v_mfma_f32_16x16x32_bf16 v[32:35], v[162:165], v[190:193], v[32:35]
	v_mfma_f32_16x16x32_bf16 v[24:27], v[170:173], v[190:193], v[24:27]
	v_mfma_f32_16x16x32_bf16 v[16:19], v[162:165], v[206:209], v[16:19]
	v_mfma_f32_16x16x32_bf16 v[8:11], v[170:173], v[206:209], v[8:11]
	v_mfma_f32_16x16x32_bf16 v[4:7], v[162:165], v[214:217], v[4:7]
	v_mfma_f32_16x16x32_bf16 v[0:3], v[170:173], v[214:217], v[0:3]
	v_mfma_f32_16x16x32_bf16 v[48:51], v[166:169], v[186:189], v[48:51]
	v_mfma_f32_16x16x32_bf16 v[40:43], v[178:181], v[186:189], v[40:43]
	v_mfma_f32_16x16x32_bf16 v[32:35], v[166:169], v[194:197], v[32:35]
	v_mfma_f32_16x16x32_bf16 v[24:27], v[178:181], v[194:197], v[24:27]
	v_mfma_f32_16x16x32_bf16 v[16:19], v[166:169], v[210:213], v[16:19]
	v_mfma_f32_16x16x32_bf16 v[8:11], v[178:181], v[210:213], v[8:11]
	v_mfma_f32_16x16x32_bf16 v[4:7], v[166:169], v[218:221], v[4:7]
	v_mfma_f32_16x16x32_bf16 v[0:3], v[178:181], v[218:221], v[0:3]
	s_setprio 0
	s_barrier
	ds_read_b128 v[182:185], v149 offset:32768
	ds_read_b128 v[186:189], v149 offset:33792
	ds_read_b128 v[190:193], v149 offset:34816
	ds_read_b128 v[194:197], v149 offset:35840
	ds_read_b128 v[206:209], v149 offset:36864
	ds_read_b128 v[210:213], v149 offset:37888
	ds_read_b128 v[214:217], v149 offset:38912
	ds_read_b128 v[218:221], v149 offset:39936
	s_add_i32 s2, 0, 0x18000
	s_add_i32 s3, 0, 0x1c000
	v_add_u32_e32 v158, s2, v146
	v_add_u32_e32 v177, s3, v146
	ds_read_b128 v[140:143], v158
	ds_read_b128 v[150:153], v158 offset:1024
	ds_read_b128 v[154:157], v158 offset:2048
	ds_read_b128 v[158:161], v158 offset:3072
	ds_read_b128 v[162:165], v177
	ds_read_b128 v[166:169], v177 offset:1024
	ds_read_b128 v[170:173], v177 offset:2048
	ds_read_b128 v[178:181], v177 offset:3072
	s_add_u32 s0, s34, 0x80000
	s_addc_u32 s1, s35, 0
	s_mov_b32 m0, s56
	v_lshl_add_u64 v[224:225], s[0:1], 0, v[134:135]
	global_load_lds_dwordx4 v[224:225], off
	s_mov_b32 m0, s57
	v_lshl_add_u64 v[224:225], s[0:1], 0, v[130:131]
	global_load_lds_dwordx4 v[224:225], off
	s_waitcnt vmcnt(8)
	s_waitcnt lgkmcnt(0)
	s_barrier
	s_setprio 1
	v_mfma_f32_16x16x32_bf16 v[124:127], v[140:143], v[182:185], v[124:127]
	v_mfma_f32_16x16x32_bf16 v[120:123], v[154:157], v[182:185], v[120:123]
	v_mfma_f32_16x16x32_bf16 v[116:119], v[140:143], v[190:193], v[116:119]
	v_mfma_f32_16x16x32_bf16 v[108:111], v[154:157], v[190:193], v[108:111]
	v_mfma_f32_16x16x32_bf16 v[100:103], v[140:143], v[206:209], v[100:103]
	v_mfma_f32_16x16x32_bf16 v[92:95], v[154:157], v[206:209], v[92:95]
	v_mfma_f32_16x16x32_bf16 v[84:87], v[140:143], v[214:217], v[84:87]
	v_mfma_f32_16x16x32_bf16 v[76:79], v[154:157], v[214:217], v[76:79]
	v_mfma_f32_16x16x32_bf16 v[124:127], v[150:153], v[186:189], v[124:127]
	v_mfma_f32_16x16x32_bf16 v[120:123], v[158:161], v[186:189], v[120:123]
	v_mfma_f32_16x16x32_bf16 v[116:119], v[150:153], v[194:197], v[116:119]
	v_mfma_f32_16x16x32_bf16 v[108:111], v[158:161], v[194:197], v[108:111]
	v_mfma_f32_16x16x32_bf16 v[100:103], v[150:153], v[210:213], v[100:103]
	v_mfma_f32_16x16x32_bf16 v[92:95], v[158:161], v[210:213], v[92:95]
	v_mfma_f32_16x16x32_bf16 v[84:87], v[150:153], v[218:221], v[84:87]
	v_mfma_f32_16x16x32_bf16 v[76:79], v[158:161], v[218:221], v[76:79]
	v_mfma_f32_16x16x32_bf16 v[112:115], v[162:165], v[182:185], v[112:115]
	v_mfma_f32_16x16x32_bf16 v[104:107], v[170:173], v[182:185], v[104:107]
	v_mfma_f32_16x16x32_bf16 v[96:99], v[162:165], v[190:193], v[96:99]
	v_mfma_f32_16x16x32_bf16 v[88:91], v[170:173], v[190:193], v[88:91]
	v_mfma_f32_16x16x32_bf16 v[80:83], v[162:165], v[206:209], v[80:83]
	v_mfma_f32_16x16x32_bf16 v[72:75], v[170:173], v[206:209], v[72:75]
	v_mfma_f32_16x16x32_bf16 v[68:71], v[162:165], v[214:217], v[68:71]
	v_mfma_f32_16x16x32_bf16 v[64:67], v[170:173], v[214:217], v[64:67]
	v_mfma_f32_16x16x32_bf16 v[112:115], v[166:169], v[186:189], v[112:115]
	v_mfma_f32_16x16x32_bf16 v[104:107], v[178:181], v[186:189], v[104:107]
	v_mfma_f32_16x16x32_bf16 v[96:99], v[166:169], v[194:197], v[96:99]
	v_mfma_f32_16x16x32_bf16 v[88:91], v[178:181], v[194:197], v[88:91]
	v_mfma_f32_16x16x32_bf16 v[80:83], v[166:169], v[210:213], v[80:83]
	v_mfma_f32_16x16x32_bf16 v[72:75], v[178:181], v[210:213], v[72:75]
	v_mfma_f32_16x16x32_bf16 v[68:71], v[166:169], v[218:221], v[68:71]
	v_mfma_f32_16x16x32_bf16 v[64:67], v[178:181], v[218:221], v[64:67]
	s_setprio 0
	s_barrier
	ds_read_b128 v[182:185], v149 offset:49152
	ds_read_b128 v[186:189], v149 offset:50176
	ds_read_b128 v[190:193], v149 offset:51200
	ds_read_b128 v[194:197], v149 offset:52224
	ds_read_b128 v[206:209], v149 offset:53248
	ds_read_b128 v[210:213], v149 offset:54272
	ds_read_b128 v[214:217], v149 offset:55296
	ds_read_b128 v[218:221], v149 offset:56320
	s_add_i32 s0, s2, s53
	s_mov_b32 m0, s0
	v_lshl_add_u64 v[174:175], v[174:175], 0, s[8:9]
	global_load_lds_dwordx4 v[174:175], off
	s_add_i32 m0, s0, 0x2000
	s_add_u32 s0, s30, 0x80080
	v_lshl_add_u64 v[174:175], v[198:199], 0, s[8:9]
	s_addc_u32 s1, s31, 0
	s_add_i32 s2, s3, s53
	global_load_lds_dwordx4 v[174:175], off
	s_mov_b32 m0, s2
	v_lshl_add_u64 v[174:175], s[0:1], 0, v[132:133]
	global_load_lds_dwordx4 v[174:175], off
	s_add_i32 m0, s2, 0x2000
	v_lshl_add_u64 v[174:175], s[0:1], 0, v[128:129]
	global_load_lds_dwordx4 v[174:175], off
	s_mov_b32 m0, s60
	v_lshl_add_u64 v[174:175], v[202:203], 0, s[8:9]
	global_load_lds_dwordx4 v[174:175], off
	s_mov_b32 m0, s61
	v_lshl_add_u64 v[174:175], v[222:223], 0, s[8:9]
	global_load_lds_dwordx4 v[174:175], off
	s_waitcnt vmcnt(8)
	s_waitcnt lgkmcnt(0)
	s_barrier
	s_setprio 1
	v_mfma_f32_16x16x32_bf16 v[60:63], v[140:143], v[182:185], v[60:63]
	v_mfma_f32_16x16x32_bf16 v[56:59], v[154:157], v[182:185], v[56:59]
	v_mfma_f32_16x16x32_bf16 v[52:55], v[140:143], v[190:193], v[52:55]
	v_mfma_f32_16x16x32_bf16 v[44:47], v[154:157], v[190:193], v[44:47]
	v_mfma_f32_16x16x32_bf16 v[36:39], v[140:143], v[206:209], v[36:39]
	v_mfma_f32_16x16x32_bf16 v[28:31], v[154:157], v[206:209], v[28:31]
	v_mfma_f32_16x16x32_bf16 v[20:23], v[140:143], v[214:217], v[20:23]
	v_mfma_f32_16x16x32_bf16 v[12:15], v[154:157], v[214:217], v[12:15]
	v_mfma_f32_16x16x32_bf16 v[60:63], v[150:153], v[186:189], v[60:63]
	v_mfma_f32_16x16x32_bf16 v[56:59], v[158:161], v[186:189], v[56:59]
	v_mfma_f32_16x16x32_bf16 v[52:55], v[150:153], v[194:197], v[52:55]
	v_mfma_f32_16x16x32_bf16 v[44:47], v[158:161], v[194:197], v[44:47]
	v_mfma_f32_16x16x32_bf16 v[36:39], v[150:153], v[210:213], v[36:39]
	v_mfma_f32_16x16x32_bf16 v[28:31], v[158:161], v[210:213], v[28:31]
	v_mfma_f32_16x16x32_bf16 v[20:23], v[150:153], v[218:221], v[20:23]
	v_mfma_f32_16x16x32_bf16 v[12:15], v[158:161], v[218:221], v[12:15]
	v_mfma_f32_16x16x32_bf16 v[48:51], v[162:165], v[182:185], v[48:51]
	v_mfma_f32_16x16x32_bf16 v[40:43], v[170:173], v[182:185], v[40:43]
	v_mfma_f32_16x16x32_bf16 v[32:35], v[162:165], v[190:193], v[32:35]
	v_mfma_f32_16x16x32_bf16 v[24:27], v[170:173], v[190:193], v[24:27]
	v_mfma_f32_16x16x32_bf16 v[16:19], v[162:165], v[206:209], v[16:19]
	v_mfma_f32_16x16x32_bf16 v[8:11], v[170:173], v[206:209], v[8:11]
	v_mfma_f32_16x16x32_bf16 v[4:7], v[162:165], v[214:217], v[4:7]
	v_mfma_f32_16x16x32_bf16 v[0:3], v[170:173], v[214:217], v[0:3]
	v_mfma_f32_16x16x32_bf16 v[48:51], v[166:169], v[186:189], v[48:51]
	v_mfma_f32_16x16x32_bf16 v[40:43], v[178:181], v[186:189], v[40:43]
	v_mfma_f32_16x16x32_bf16 v[32:35], v[166:169], v[194:197], v[32:35]
	v_mfma_f32_16x16x32_bf16 v[24:27], v[178:181], v[194:197], v[24:27]
	v_mfma_f32_16x16x32_bf16 v[16:19], v[166:169], v[210:213], v[16:19]
	v_mfma_f32_16x16x32_bf16 v[8:11], v[178:181], v[210:213], v[8:11]
	v_mfma_f32_16x16x32_bf16 v[4:7], v[166:169], v[218:221], v[4:7]
	v_mfma_f32_16x16x32_bf16 v[0:3], v[178:181], v[218:221], v[0:3]
	s_setprio 0
	s_barrier
	s_add_i32 s71, s71, 2
	s_add_u32 s28, s28, 0x100
	s_addc_u32 s29, s29, 0
	s_add_u32 s69, s69, 0x100
	s_addc_u32 s70, s70, 0
	s_cmp_gt_u32 s71, 29
	s_cbranch_scc0 .LBB0_666
	s_and_b64 vcc, exec, s[12:13]
	s_cbranch_vccz .LBB0_669
	s_barrier

.LBB0_828:
	ds_read_b128 v[138:141], v145
	ds_read_b128 v[150:153], v145 offset:1024
	ds_read_b128 v[154:157], v145 offset:2048
	ds_read_b128 v[158:161], v145 offset:3072
	ds_read_b128 v[162:165], v146
	ds_read_b128 v[166:169], v146 offset:1024
	ds_read_b128 v[170:173], v146 offset:2048
	ds_read_b128 v[178:181], v146 offset:3072
	ds_read_b128 v[182:185], v147
	ds_read_b128 v[186:189], v147 offset:1024
	ds_read_b128 v[190:193], v147 offset:2048
	ds_read_b128 v[194:197], v147 offset:3072
	ds_read_b128 v[206:209], v147 offset:4096
	ds_read_b128 v[210:213], v147 offset:5120
	ds_read_b128 v[214:217], v147 offset:6144
	ds_read_b128 v[218:221], v147 offset:7168
	s_add_u32 s2, s58, s62
	s_addc_u32 s3, s59, s63
	s_add_u32 s9, s2, 0x100
	s_addc_u32 s38, s3, 0
	s_and_b64 s[0:1], s[60:61], exec
	v_cndmask_b32_e64 v137, 0, 1, s[64:65]
	s_cselect_b32 s65, s23, s38
	s_cselect_b32 s64, s12, s9
	s_add_u32 s0, s56, s62
	s_addc_u32 s1, s57, s63
	s_add_u32 s9, s0, 0x100
	s_addc_u32 s38, s1, 0
	s_and_b64 s[0:1], s[60:61], exec
	s_cselect_b32 s67, s13, s38
	s_cselect_b32 s66, s8, s9
	s_add_u32 s70, s2, 0x80080
	s_addc_u32 s71, s3, 0
	s_add_i32 s39, s87, s79
	s_add_i32 m0, s74, 0xc000
	s_add_i32 s53, s74, 0xe000
	s_add_i32 s50, s39, 0x2000
	s_add_u32 s68, s66, 0x80000
	s_addc_u32 s69, s67, 0
	s_add_i32 s51, s88, s79
	s_add_i32 s38, s51, 0x2000
	s_add_i32 s1, 0, 0x18000
	s_add_i32 s9, 0, 0x1c000
	s_add_u32 s62, s64, 0x80000
	s_addc_u32 s63, s65, 0
	s_add_i32 s3, s1, s79
	s_add_i32 s76, s3, 0x2000
	s_add_u32 s60, s66, 0x80080
	s_addc_u32 s61, s67, 0
	s_add_i32 s2, s9, s79
	s_add_i32 s0, s2, 0x2000
	v_cmp_ne_u32_e32 vcc, 1, v137
	v_lshl_add_u64 v[174:175], s[70:71], 0, v[128:129]
	global_load_lds_dwordx4 v[174:175], off
	s_mov_b32 m0, s53
	v_lshl_add_u64 v[174:175], s[70:71], 0, v[132:133]
	global_load_lds_dwordx4 v[174:175], off
	s_waitcnt vmcnt(8)
	s_waitcnt lgkmcnt(0)
	s_barrier
	s_setprio 1
	v_mfma_f32_16x16x32_bf16 v[124:127], v[138:141], v[182:185], v[124:127]
	v_mfma_f32_16x16x32_bf16 v[120:123], v[154:157], v[182:185], v[120:123]
	v_mfma_f32_16x16x32_bf16 v[108:111], v[138:141], v[190:193], v[108:111]
	v_mfma_f32_16x16x32_bf16 v[104:107], v[154:157], v[190:193], v[104:107]
	v_mfma_f32_16x16x32_bf16 v[92:95], v[138:141], v[206:209], v[92:95]
	v_mfma_f32_16x16x32_bf16 v[88:91], v[154:157], v[206:209], v[88:91]
	v_mfma_f32_16x16x32_bf16 v[76:79], v[138:141], v[214:217], v[76:79]
	v_mfma_f32_16x16x32_bf16 v[72:75], v[154:157], v[214:217], v[72:75]
	v_mfma_f32_16x16x32_bf16 v[124:127], v[150:153], v[186:189], v[124:127]
	v_mfma_f32_16x16x32_bf16 v[120:123], v[158:161], v[186:189], v[120:123]
	v_mfma_f32_16x16x32_bf16 v[108:111], v[150:153], v[194:197], v[108:111]
	v_mfma_f32_16x16x32_bf16 v[104:107], v[158:161], v[194:197], v[104:107]
	v_mfma_f32_16x16x32_bf16 v[92:95], v[150:153], v[210:213], v[92:95]
	v_mfma_f32_16x16x32_bf16 v[88:91], v[158:161], v[210:213], v[88:91]
	v_mfma_f32_16x16x32_bf16 v[76:79], v[150:153], v[218:221], v[76:79]
	v_mfma_f32_16x16x32_bf16 v[72:75], v[158:161], v[218:221], v[72:75]
	v_mfma_f32_16x16x32_bf16 v[116:119], v[162:165], v[182:185], v[116:119]
	v_mfma_f32_16x16x32_bf16 v[112:115], v[170:173], v[182:185], v[112:115]
	v_mfma_f32_16x16x32_bf16 v[100:103], v[162:165], v[190:193], v[100:103]
	v_mfma_f32_16x16x32_bf16 v[96:99], v[170:173], v[190:193], v[96:99]
	v_mfma_f32_16x16x32_bf16 v[84:87], v[162:165], v[206:209], v[84:87]
	v_mfma_f32_16x16x32_bf16 v[80:83], v[170:173], v[206:209], v[80:83]
	v_mfma_f32_16x16x32_bf16 v[68:71], v[162:165], v[214:217], v[68:71]
	v_mfma_f32_16x16x32_bf16 v[64:67], v[170:173], v[214:217], v[64:67]
	v_mfma_f32_16x16x32_bf16 v[116:119], v[166:169], v[186:189], v[116:119]
	v_mfma_f32_16x16x32_bf16 v[112:115], v[178:181], v[186:189], v[112:115]
	v_mfma_f32_16x16x32_bf16 v[100:103], v[166:169], v[194:197], v[100:103]
	v_mfma_f32_16x16x32_bf16 v[96:99], v[178:181], v[194:197], v[96:99]
	v_mfma_f32_16x16x32_bf16 v[84:87], v[166:169], v[210:213], v[84:87]
	v_mfma_f32_16x16x32_bf16 v[80:83], v[178:181], v[210:213], v[80:83]
	v_mfma_f32_16x16x32_bf16 v[68:71], v[166:169], v[218:221], v[68:71]
	v_mfma_f32_16x16x32_bf16 v[64:67], v[178:181], v[218:221], v[64:67]
	s_setprio 0
	s_barrier
	ds_read_b128 v[182:185], v147 offset:16384
	ds_read_b128 v[186:189], v147 offset:17408
	ds_read_b128 v[190:193], v147 offset:18432
	ds_read_b128 v[194:197], v147 offset:19456
	ds_read_b128 v[206:209], v147 offset:20480
	ds_read_b128 v[210:213], v147 offset:21504
	ds_read_b128 v[214:217], v147 offset:22528
	ds_read_b128 v[218:221], v147 offset:23552
	s_mov_b32 m0, s39
	v_lshl_add_u64 v[174:175], s[66:67], 0, v[130:131]
	global_load_lds_dwordx4 v[174:175], off
	v_lshl_add_u64 v[198:199], s[66:67], 0, v[134:135]
	s_mov_b32 m0, s50
	v_lshl_add_u64 v[202:203], s[68:69], 0, v[130:131]
	global_load_lds_dwordx4 v[198:199], off
	s_mov_b32 m0, s51
	v_lshl_add_u64 v[222:223], s[64:65], 0, v[132:133]
	global_load_lds_dwordx4 v[202:203], off
	s_mov_b32 m0, s38
	v_lshl_add_u64 v[202:203], s[68:69], 0, v[134:135]
	global_load_lds_dwordx4 v[202:203], off
	s_mov_b32 m0, s74
	v_lshl_add_u64 v[202:203], s[64:65], 0, v[128:129]
	global_load_lds_dwordx4 v[202:203], off
	s_mov_b32 m0, s55
	s_nop 0
	global_load_lds_dwordx4 v[222:223], off
	s_waitcnt vmcnt(8)
	s_waitcnt lgkmcnt(0)
	s_barrier
	s_setprio 1
	v_mfma_f32_16x16x32_bf16 v[60:63], v[138:141], v[182:185], v[60:63]
	v_mfma_f32_16x16x32_bf16 v[56:59], v[154:157], v[182:185], v[56:59]
	v_mfma_f32_16x16x32_bf16 v[44:47], v[138:141], v[190:193], v[44:47]
	v_mfma_f32_16x16x32_bf16 v[40:43], v[154:157], v[190:193], v[40:43]
	v_mfma_f32_16x16x32_bf16 v[28:31], v[138:141], v[206:209], v[28:31]
	v_mfma_f32_16x16x32_bf16 v[24:27], v[154:157], v[206:209], v[24:27]
	v_mfma_f32_16x16x32_bf16 v[12:15], v[138:141], v[214:217], v[12:15]
	v_mfma_f32_16x16x32_bf16 v[8:11], v[154:157], v[214:217], v[8:11]
	v_mfma_f32_16x16x32_bf16 v[60:63], v[150:153], v[186:189], v[60:63]
	v_mfma_f32_16x16x32_bf16 v[56:59], v[158:161], v[186:189], v[56:59]
	v_mfma_f32_16x16x32_bf16 v[44:47], v[150:153], v[194:197], v[44:47]
	v_mfma_f32_16x16x32_bf16 v[40:43], v[158:161], v[194:197], v[40:43]
	v_mfma_f32_16x16x32_bf16 v[28:31], v[150:153], v[210:213], v[28:31]
	v_mfma_f32_16x16x32_bf16 v[24:27], v[158:161], v[210:213], v[24:27]
	v_mfma_f32_16x16x32_bf16 v[12:15], v[150:153], v[218:221], v[12:15]
	v_mfma_f32_16x16x32_bf16 v[8:11], v[158:161], v[218:221], v[8:11]
	v_mfma_f32_16x16x32_bf16 v[52:55], v[162:165], v[182:185], v[52:55]
	v_mfma_f32_16x16x32_bf16 v[48:51], v[170:173], v[182:185], v[48:51]
	v_mfma_f32_16x16x32_bf16 v[36:39], v[162:165], v[190:193], v[36:39]
	v_mfma_f32_16x16x32_bf16 v[32:35], v[170:173], v[190:193], v[32:35]
	v_mfma_f32_16x16x32_bf16 v[20:23], v[162:165], v[206:209], v[20:23]
	v_mfma_f32_16x16x32_bf16 v[16:19], v[170:173], v[206:209], v[16:19]
	v_mfma_f32_16x16x32_bf16 v[4:7], v[162:165], v[214:217], v[4:7]
	v_mfma_f32_16x16x32_bf16 v[0:3], v[170:173], v[214:217], v[0:3]
	v_mfma_f32_16x16x32_bf16 v[52:55], v[166:169], v[186:189], v[52:55]
	v_mfma_f32_16x16x32_bf16 v[48:51], v[178:181], v[186:189], v[48:51]
	v_mfma_f32_16x16x32_bf16 v[36:39], v[166:169], v[194:197], v[36:39]
	v_mfma_f32_16x16x32_bf16 v[32:35], v[178:181], v[194:197], v[32:35]
	v_mfma_f32_16x16x32_bf16 v[20:23], v[166:169], v[210:213], v[20:23]
	v_mfma_f32_16x16x32_bf16 v[16:19], v[178:181], v[210:213], v[16:19]
	v_mfma_f32_16x16x32_bf16 v[4:7], v[166:169], v[218:221], v[4:7]
	v_mfma_f32_16x16x32_bf16 v[0:3], v[178:181], v[218:221], v[0:3]
	s_setprio 0
	s_barrier
	ds_read_b128 v[182:185], v147 offset:32768
	ds_read_b128 v[186:189], v147 offset:33792
	ds_read_b128 v[190:193], v147 offset:34816
	ds_read_b128 v[194:197], v147 offset:35840
	ds_read_b128 v[206:209], v147 offset:36864
	ds_read_b128 v[210:213], v147 offset:37888
	ds_read_b128 v[214:217], v147 offset:38912
	ds_read_b128 v[218:221], v147 offset:39936
	v_add_u32_e32 v137, s1, v144
	ds_read_b128 v[138:141], v137
	ds_read_b128 v[150:153], v137 offset:1024
	ds_read_b128 v[154:157], v137 offset:2048
	ds_read_b128 v[158:161], v137 offset:3072
	v_add_u32_e32 v137, s9, v144
	ds_read_b128 v[162:165], v137
	ds_read_b128 v[166:169], v137 offset:1024
	ds_read_b128 v[170:173], v137 offset:2048
	ds_read_b128 v[178:181], v137 offset:3072
	s_mov_b32 m0, s80
	v_lshl_add_u64 v[224:225], s[62:63], 0, v[128:129]
	global_load_lds_dwordx4 v[224:225], off
	s_mov_b32 m0, s81
	v_lshl_add_u64 v[224:225], s[62:63], 0, v[132:133]
	global_load_lds_dwordx4 v[224:225], off
	s_waitcnt vmcnt(8)
	s_waitcnt lgkmcnt(0)
	s_barrier
	s_setprio 1
	v_mfma_f32_16x16x32_bf16 v[124:127], v[138:141], v[182:185], v[124:127]
	v_mfma_f32_16x16x32_bf16 v[120:123], v[154:157], v[182:185], v[120:123]
	v_mfma_f32_16x16x32_bf16 v[108:111], v[138:141], v[190:193], v[108:111]
	v_mfma_f32_16x16x32_bf16 v[104:107], v[154:157], v[190:193], v[104:107]
	v_mfma_f32_16x16x32_bf16 v[92:95], v[138:141], v[206:209], v[92:95]
	v_mfma_f32_16x16x32_bf16 v[88:91], v[154:157], v[206:209], v[88:91]
	v_mfma_f32_16x16x32_bf16 v[76:79], v[138:141], v[214:217], v[76:79]
	v_mfma_f32_16x16x32_bf16 v[72:75], v[154:157], v[214:217], v[72:75]
	v_mfma_f32_16x16x32_bf16 v[124:127], v[150:153], v[186:189], v[124:127]
	v_mfma_f32_16x16x32_bf16 v[120:123], v[158:161], v[186:189], v[120:123]
	v_mfma_f32_16x16x32_bf16 v[108:111], v[150:153], v[194:197], v[108:111]
	v_mfma_f32_16x16x32_bf16 v[104:107], v[158:161], v[194:197], v[104:107]
	v_mfma_f32_16x16x32_bf16 v[92:95], v[150:153], v[210:213], v[92:95]
	v_mfma_f32_16x16x32_bf16 v[88:91], v[158:161], v[210:213], v[88:91]
	v_mfma_f32_16x16x32_bf16 v[76:79], v[150:153], v[218:221], v[76:79]
	v_mfma_f32_16x16x32_bf16 v[72:75], v[158:161], v[218:221], v[72:75]
	v_mfma_f32_16x16x32_bf16 v[116:119], v[162:165], v[182:185], v[116:119]
	v_mfma_f32_16x16x32_bf16 v[112:115], v[170:173], v[182:185], v[112:115]
	v_mfma_f32_16x16x32_bf16 v[100:103], v[162:165], v[190:193], v[100:103]
	v_mfma_f32_16x16x32_bf16 v[96:99], v[170:173], v[190:193], v[96:99]
	v_mfma_f32_16x16x32_bf16 v[84:87], v[162:165], v[206:209], v[84:87]
	v_mfma_f32_16x16x32_bf16 v[80:83], v[170:173], v[206:209], v[80:83]
	v_mfma_f32_16x16x32_bf16 v[68:71], v[162:165], v[214:217], v[68:71]
	v_mfma_f32_16x16x32_bf16 v[64:67], v[170:173], v[214:217], v[64:67]
	v_mfma_f32_16x16x32_bf16 v[116:119], v[166:169], v[186:189], v[116:119]
	v_mfma_f32_16x16x32_bf16 v[112:115], v[178:181], v[186:189], v[112:115]
	v_mfma_f32_16x16x32_bf16 v[100:103], v[166:169], v[194:197], v[100:103]
	v_mfma_f32_16x16x32_bf16 v[96:99], v[178:181], v[194:197], v[96:99]
	v_mfma_f32_16x16x32_bf16 v[84:87], v[166:169], v[210:213], v[84:87]
	v_mfma_f32_16x16x32_bf16 v[80:83], v[178:181], v[210:213], v[80:83]
	v_mfma_f32_16x16x32_bf16 v[68:71], v[166:169], v[218:221], v[68:71]
	v_mfma_f32_16x16x32_bf16 v[64:67], v[178:181], v[218:221], v[64:67]
	s_setprio 0
	s_barrier
	ds_read_b128 v[182:185], v147 offset:49152
	ds_read_b128 v[186:189], v147 offset:50176
	ds_read_b128 v[190:193], v147 offset:51200
	ds_read_b128 v[194:197], v147 offset:52224
	ds_read_b128 v[206:209], v147 offset:53248
	ds_read_b128 v[210:213], v147 offset:54272
	ds_read_b128 v[214:217], v147 offset:55296
	ds_read_b128 v[218:221], v147 offset:56320
	s_mov_b32 m0, s3
	v_lshl_add_u64 v[174:175], v[174:175], 0, s[16:17]
	global_load_lds_dwordx4 v[174:175], off
	s_mov_b32 m0, s76
	v_lshl_add_u64 v[174:175], v[198:199], 0, s[16:17]
	global_load_lds_dwordx4 v[174:175], off
	s_mov_b32 m0, s2
	v_lshl_add_u64 v[174:175], s[60:61], 0, v[130:131]
	global_load_lds_dwordx4 v[174:175], off
	s_mov_b32 m0, s0
	v_lshl_add_u64 v[174:175], s[60:61], 0, v[134:135]
	global_load_lds_dwordx4 v[174:175], off
	s_mov_b32 m0, s85
	v_lshl_add_u64 v[174:175], v[202:203], 0, s[16:17]
	global_load_lds_dwordx4 v[174:175], off
	s_mov_b32 m0, s86
	v_lshl_add_u64 v[174:175], v[222:223], 0, s[16:17]
	global_load_lds_dwordx4 v[174:175], off
	s_waitcnt vmcnt(8)
	s_waitcnt lgkmcnt(0)
	s_barrier
	s_setprio 1
	v_mfma_f32_16x16x32_bf16 v[60:63], v[138:141], v[182:185], v[60:63]
	v_mfma_f32_16x16x32_bf16 v[56:59], v[154:157], v[182:185], v[56:59]
	v_mfma_f32_16x16x32_bf16 v[44:47], v[138:141], v[190:193], v[44:47]
	v_mfma_f32_16x16x32_bf16 v[40:43], v[154:157], v[190:193], v[40:43]
	v_mfma_f32_16x16x32_bf16 v[28:31], v[138:141], v[206:209], v[28:31]
	v_mfma_f32_16x16x32_bf16 v[24:27], v[154:157], v[206:209], v[24:27]
	v_mfma_f32_16x16x32_bf16 v[12:15], v[138:141], v[214:217], v[12:15]
	v_mfma_f32_16x16x32_bf16 v[8:11], v[154:157], v[214:217], v[8:11]
	v_mfma_f32_16x16x32_bf16 v[60:63], v[150:153], v[186:189], v[60:63]
	v_mfma_f32_16x16x32_bf16 v[56:59], v[158:161], v[186:189], v[56:59]
	v_mfma_f32_16x16x32_bf16 v[44:47], v[150:153], v[194:197], v[44:47]
	v_mfma_f32_16x16x32_bf16 v[40:43], v[158:161], v[194:197], v[40:43]
	v_mfma_f32_16x16x32_bf16 v[28:31], v[150:153], v[210:213], v[28:31]
	v_mfma_f32_16x16x32_bf16 v[24:27], v[158:161], v[210:213], v[24:27]
	v_mfma_f32_16x16x32_bf16 v[12:15], v[150:153], v[218:221], v[12:15]
	v_mfma_f32_16x16x32_bf16 v[8:11], v[158:161], v[218:221], v[8:11]
	v_mfma_f32_16x16x32_bf16 v[52:55], v[162:165], v[182:185], v[52:55]
	v_mfma_f32_16x16x32_bf16 v[48:51], v[170:173], v[182:185], v[48:51]
	v_mfma_f32_16x16x32_bf16 v[36:39], v[162:165], v[190:193], v[36:39]
	v_mfma_f32_16x16x32_bf16 v[32:35], v[170:173], v[190:193], v[32:35]
	v_mfma_f32_16x16x32_bf16 v[20:23], v[162:165], v[206:209], v[20:23]
	v_mfma_f32_16x16x32_bf16 v[16:19], v[170:173], v[206:209], v[16:19]
	v_mfma_f32_16x16x32_bf16 v[4:7], v[162:165], v[214:217], v[4:7]
	v_mfma_f32_16x16x32_bf16 v[0:3], v[170:173], v[214:217], v[0:3]
	v_mfma_f32_16x16x32_bf16 v[52:55], v[166:169], v[186:189], v[52:55]
	v_mfma_f32_16x16x32_bf16 v[48:51], v[178:181], v[186:189], v[48:51]
	v_mfma_f32_16x16x32_bf16 v[36:39], v[166:169], v[194:197], v[36:39]
	v_mfma_f32_16x16x32_bf16 v[32:35], v[178:181], v[194:197], v[32:35]
	v_mfma_f32_16x16x32_bf16 v[20:23], v[166:169], v[210:213], v[20:23]
	v_mfma_f32_16x16x32_bf16 v[16:19], v[178:181], v[210:213], v[16:19]
	v_mfma_f32_16x16x32_bf16 v[4:7], v[166:169], v[218:221], v[4:7]
	v_mfma_f32_16x16x32_bf16 v[0:3], v[178:181], v[218:221], v[0:3]
	s_setprio 0
	s_barrier
	s_mov_b64 s[64:65], 0
	s_mov_b64 s[60:61], -1
	s_mov_b64 s[62:63], 0x100
	s_cbranch_vccz .LBB0_828
	s_and_b64 vcc, exec, s[18:19]
	s_cbranch_vccz .LBB0_831
	s_barrier

.LBB0_849:
	ds_read_b128 v[138:141], v147
	ds_read_b128 v[152:155], v147 offset:1024
	ds_read_b128 v[156:159], v147 offset:2048
	ds_read_b128 v[160:163], v147 offset:3072
	ds_read_b128 v[164:167], v148
	ds_read_b128 v[168:171], v148 offset:1024
	ds_read_b128 v[172:175], v148 offset:2048
	ds_read_b128 v[178:181], v148 offset:3072
	ds_read_b128 v[182:185], v149
	ds_read_b128 v[186:189], v149 offset:1024
	ds_read_b128 v[190:193], v149 offset:2048
	ds_read_b128 v[194:197], v149 offset:3072
	ds_read_b128 v[206:209], v149 offset:4096
	ds_read_b128 v[210:213], v149 offset:5120
	ds_read_b128 v[214:217], v149 offset:6144
	ds_read_b128 v[218:221], v149 offset:7168
	s_add_u32 s2, s30, s52
	s_addc_u32 s3, s31, s53
	s_add_u32 s9, s2, 0x100
	s_addc_u32 s38, s3, 0
	s_and_b64 s[0:1], s[34:35], exec
	v_cndmask_b32_e64 v137, 0, 1, s[54:55]
	s_cselect_b32 s55, s27, s38
	s_cselect_b32 s54, s89, s9
	s_add_u32 s0, s28, s52
	s_addc_u32 s1, s29, s53
	s_add_u32 s9, s0, 0x100
	s_addc_u32 s38, s1, 0
	s_and_b64 s[0:1], s[34:35], exec
	s_cselect_b32 s57, s90, s38
	s_cselect_b32 s56, s8, s9
	s_add_u32 s60, s2, 0x80080
	s_addc_u32 s61, s3, 0
	s_add_i32 s39, s79, s36
	s_add_i32 m0, s63, 0xc000
	s_add_i32 s74, s63, 0xe000
	s_add_i32 s50, s39, 0x2000
	s_add_u32 s58, s56, 0x80000
	s_addc_u32 s59, s57, 0
	s_add_i32 s38, s80, s36
	s_add_i32 s51, s38, 0x2000
	s_add_i32 s76, 0, 0x18000
	s_add_i32 s0, 0, 0x1c000
	s_add_u32 s52, s54, 0x80000
	s_addc_u32 s53, s55, 0
	s_add_i32 s3, s76, s36
	s_add_i32 s1, s3, 0x2000
	s_add_u32 s34, s56, 0x80080
	s_addc_u32 s35, s57, 0
	s_add_i32 s2, s0, s36
	s_add_i32 s9, s2, 0x2000
	v_cmp_ne_u32_e32 vcc, 1, v137
	v_lshl_add_u64 v[142:143], s[60:61], 0, v[134:135]
	global_load_lds_dwordx4 v[142:143], off
	s_mov_b32 m0, s74
	v_lshl_add_u64 v[142:143], s[60:61], 0, v[130:131]
	global_load_lds_dwordx4 v[142:143], off
	s_waitcnt vmcnt(8)
	s_waitcnt lgkmcnt(0)
	s_barrier
	s_setprio 1
	v_mfma_f32_16x16x32_bf16 v[124:127], v[138:141], v[182:185], v[124:127]
	v_mfma_f32_16x16x32_bf16 v[120:123], v[156:159], v[182:185], v[120:123]
	v_mfma_f32_16x16x32_bf16 v[108:111], v[138:141], v[190:193], v[108:111]
	v_mfma_f32_16x16x32_bf16 v[104:107], v[156:159], v[190:193], v[104:107]
	v_mfma_f32_16x16x32_bf16 v[92:95], v[138:141], v[206:209], v[92:95]
	v_mfma_f32_16x16x32_bf16 v[88:91], v[156:159], v[206:209], v[88:91]
	v_mfma_f32_16x16x32_bf16 v[76:79], v[138:141], v[214:217], v[76:79]
	v_mfma_f32_16x16x32_bf16 v[72:75], v[156:159], v[214:217], v[72:75]
	v_mfma_f32_16x16x32_bf16 v[124:127], v[152:155], v[186:189], v[124:127]
	v_mfma_f32_16x16x32_bf16 v[120:123], v[160:163], v[186:189], v[120:123]
	v_mfma_f32_16x16x32_bf16 v[108:111], v[152:155], v[194:197], v[108:111]
	v_mfma_f32_16x16x32_bf16 v[104:107], v[160:163], v[194:197], v[104:107]
	v_mfma_f32_16x16x32_bf16 v[92:95], v[152:155], v[210:213], v[92:95]
	v_mfma_f32_16x16x32_bf16 v[88:91], v[160:163], v[210:213], v[88:91]
	v_mfma_f32_16x16x32_bf16 v[76:79], v[152:155], v[218:221], v[76:79]
	v_mfma_f32_16x16x32_bf16 v[72:75], v[160:163], v[218:221], v[72:75]
	v_mfma_f32_16x16x32_bf16 v[116:119], v[164:167], v[182:185], v[116:119]
	v_mfma_f32_16x16x32_bf16 v[112:115], v[172:175], v[182:185], v[112:115]
	v_mfma_f32_16x16x32_bf16 v[100:103], v[164:167], v[190:193], v[100:103]
	v_mfma_f32_16x16x32_bf16 v[96:99], v[172:175], v[190:193], v[96:99]
	v_mfma_f32_16x16x32_bf16 v[84:87], v[164:167], v[206:209], v[84:87]
	v_mfma_f32_16x16x32_bf16 v[80:83], v[172:175], v[206:209], v[80:83]
	v_mfma_f32_16x16x32_bf16 v[68:71], v[164:167], v[214:217], v[68:71]
	v_mfma_f32_16x16x32_bf16 v[64:67], v[172:175], v[214:217], v[64:67]
	v_mfma_f32_16x16x32_bf16 v[116:119], v[168:171], v[186:189], v[116:119]
	v_mfma_f32_16x16x32_bf16 v[112:115], v[178:181], v[186:189], v[112:115]
	v_mfma_f32_16x16x32_bf16 v[100:103], v[168:171], v[194:197], v[100:103]
	v_mfma_f32_16x16x32_bf16 v[96:99], v[178:181], v[194:197], v[96:99]
	v_mfma_f32_16x16x32_bf16 v[84:87], v[168:171], v[210:213], v[84:87]
	v_mfma_f32_16x16x32_bf16 v[80:83], v[178:181], v[210:213], v[80:83]
	v_mfma_f32_16x16x32_bf16 v[68:71], v[168:171], v[218:221], v[68:71]
	v_mfma_f32_16x16x32_bf16 v[64:67], v[178:181], v[218:221], v[64:67]
	s_setprio 0
	s_barrier
	ds_read_b128 v[182:185], v149 offset:16384
	ds_read_b128 v[186:189], v149 offset:17408
	ds_read_b128 v[190:193], v149 offset:18432
	ds_read_b128 v[194:197], v149 offset:19456
	ds_read_b128 v[206:209], v149 offset:20480
	ds_read_b128 v[210:213], v149 offset:21504
	ds_read_b128 v[214:217], v149 offset:22528
	ds_read_b128 v[218:221], v149 offset:23552
	s_mov_b32 m0, s39
	v_lshl_add_u64 v[142:143], s[56:57], 0, v[132:133]
	global_load_lds_dwordx4 v[142:143], off
	v_lshl_add_u64 v[198:199], s[56:57], 0, v[128:129]
	s_mov_b32 m0, s50
	v_lshl_add_u64 v[202:203], s[58:59], 0, v[132:133]
	global_load_lds_dwordx4 v[198:199], off
	s_mov_b32 m0, s38
	v_lshl_add_u64 v[222:223], s[54:55], 0, v[130:131]
	global_load_lds_dwordx4 v[202:203], off
	s_mov_b32 m0, s51
	v_lshl_add_u64 v[202:203], s[58:59], 0, v[128:129]
	global_load_lds_dwordx4 v[202:203], off
	s_mov_b32 m0, s63
	v_lshl_add_u64 v[202:203], s[54:55], 0, v[134:135]
	global_load_lds_dwordx4 v[202:203], off
	s_mov_b32 m0, s64
	s_nop 0
	global_load_lds_dwordx4 v[222:223], off
	s_waitcnt vmcnt(8)
	s_waitcnt lgkmcnt(0)
	s_barrier
	s_setprio 1
	v_mfma_f32_16x16x32_bf16 v[60:63], v[138:141], v[182:185], v[60:63]
	v_mfma_f32_16x16x32_bf16 v[56:59], v[156:159], v[182:185], v[56:59]
	v_mfma_f32_16x16x32_bf16 v[44:47], v[138:141], v[190:193], v[44:47]
	v_mfma_f32_16x16x32_bf16 v[40:43], v[156:159], v[190:193], v[40:43]
	v_mfma_f32_16x16x32_bf16 v[28:31], v[138:141], v[206:209], v[28:31]
	v_mfma_f32_16x16x32_bf16 v[24:27], v[156:159], v[206:209], v[24:27]
	v_mfma_f32_16x16x32_bf16 v[12:15], v[138:141], v[214:217], v[12:15]
	v_mfma_f32_16x16x32_bf16 v[8:11], v[156:159], v[214:217], v[8:11]
	v_mfma_f32_16x16x32_bf16 v[60:63], v[152:155], v[186:189], v[60:63]
	v_mfma_f32_16x16x32_bf16 v[56:59], v[160:163], v[186:189], v[56:59]
	v_mfma_f32_16x16x32_bf16 v[44:47], v[152:155], v[194:197], v[44:47]
	v_mfma_f32_16x16x32_bf16 v[40:43], v[160:163], v[194:197], v[40:43]
	v_mfma_f32_16x16x32_bf16 v[28:31], v[152:155], v[210:213], v[28:31]
	v_mfma_f32_16x16x32_bf16 v[24:27], v[160:163], v[210:213], v[24:27]
	v_mfma_f32_16x16x32_bf16 v[12:15], v[152:155], v[218:221], v[12:15]
	v_mfma_f32_16x16x32_bf16 v[8:11], v[160:163], v[218:221], v[8:11]
	v_mfma_f32_16x16x32_bf16 v[52:55], v[164:167], v[182:185], v[52:55]
	v_mfma_f32_16x16x32_bf16 v[48:51], v[172:175], v[182:185], v[48:51]
	v_mfma_f32_16x16x32_bf16 v[36:39], v[164:167], v[190:193], v[36:39]
	v_mfma_f32_16x16x32_bf16 v[32:35], v[172:175], v[190:193], v[32:35]
	v_mfma_f32_16x16x32_bf16 v[20:23], v[164:167], v[206:209], v[20:23]
	v_mfma_f32_16x16x32_bf16 v[16:19], v[172:175], v[206:209], v[16:19]
	v_mfma_f32_16x16x32_bf16 v[4:7], v[164:167], v[214:217], v[4:7]
	v_mfma_f32_16x16x32_bf16 v[0:3], v[172:175], v[214:217], v[0:3]
	v_mfma_f32_16x16x32_bf16 v[52:55], v[168:171], v[186:189], v[52:55]
	v_mfma_f32_16x16x32_bf16 v[48:51], v[178:181], v[186:189], v[48:51]
	v_mfma_f32_16x16x32_bf16 v[36:39], v[168:171], v[194:197], v[36:39]
	v_mfma_f32_16x16x32_bf16 v[32:35], v[178:181], v[194:197], v[32:35]
	v_mfma_f32_16x16x32_bf16 v[20:23], v[168:171], v[210:213], v[20:23]
	v_mfma_f32_16x16x32_bf16 v[16:19], v[178:181], v[210:213], v[16:19]
	v_mfma_f32_16x16x32_bf16 v[4:7], v[168:171], v[218:221], v[4:7]
	v_mfma_f32_16x16x32_bf16 v[0:3], v[178:181], v[218:221], v[0:3]
	s_setprio 0
	s_barrier
	ds_read_b128 v[182:185], v149 offset:32768
	ds_read_b128 v[186:189], v149 offset:33792
	ds_read_b128 v[190:193], v149 offset:34816
	ds_read_b128 v[194:197], v149 offset:35840
	ds_read_b128 v[206:209], v149 offset:36864
	ds_read_b128 v[210:213], v149 offset:37888
	ds_read_b128 v[214:217], v149 offset:38912
	ds_read_b128 v[218:221], v149 offset:39936
	v_add_u32_e32 v137, s76, v146
	ds_read_b128 v[138:141], v137
	ds_read_b128 v[152:155], v137 offset:1024
	ds_read_b128 v[156:159], v137 offset:2048
	ds_read_b128 v[160:163], v137 offset:3072
	v_add_u32_e32 v137, s0, v146
	ds_read_b128 v[164:167], v137
	ds_read_b128 v[168:171], v137 offset:1024
	ds_read_b128 v[172:175], v137 offset:2048
	ds_read_b128 v[178:181], v137 offset:3072
	s_mov_b32 m0, s65
	v_lshl_add_u64 v[224:225], s[52:53], 0, v[134:135]
	global_load_lds_dwordx4 v[224:225], off
	s_mov_b32 m0, s66
	v_lshl_add_u64 v[224:225], s[52:53], 0, v[130:131]
	global_load_lds_dwordx4 v[224:225], off
	s_waitcnt vmcnt(8)
	s_waitcnt lgkmcnt(0)
	s_barrier
	s_setprio 1
	v_mfma_f32_16x16x32_bf16 v[124:127], v[138:141], v[182:185], v[124:127]
	v_mfma_f32_16x16x32_bf16 v[120:123], v[156:159], v[182:185], v[120:123]
	v_mfma_f32_16x16x32_bf16 v[108:111], v[138:141], v[190:193], v[108:111]
	v_mfma_f32_16x16x32_bf16 v[104:107], v[156:159], v[190:193], v[104:107]
	v_mfma_f32_16x16x32_bf16 v[92:95], v[138:141], v[206:209], v[92:95]
	v_mfma_f32_16x16x32_bf16 v[88:91], v[156:159], v[206:209], v[88:91]
	v_mfma_f32_16x16x32_bf16 v[76:79], v[138:141], v[214:217], v[76:79]
	v_mfma_f32_16x16x32_bf16 v[72:75], v[156:159], v[214:217], v[72:75]
	v_mfma_f32_16x16x32_bf16 v[124:127], v[152:155], v[186:189], v[124:127]
	v_mfma_f32_16x16x32_bf16 v[120:123], v[160:163], v[186:189], v[120:123]
	v_mfma_f32_16x16x32_bf16 v[108:111], v[152:155], v[194:197], v[108:111]
	v_mfma_f32_16x16x32_bf16 v[104:107], v[160:163], v[194:197], v[104:107]
	v_mfma_f32_16x16x32_bf16 v[92:95], v[152:155], v[210:213], v[92:95]
	v_mfma_f32_16x16x32_bf16 v[88:91], v[160:163], v[210:213], v[88:91]
	v_mfma_f32_16x16x32_bf16 v[76:79], v[152:155], v[218:221], v[76:79]
	v_mfma_f32_16x16x32_bf16 v[72:75], v[160:163], v[218:221], v[72:75]
	v_mfma_f32_16x16x32_bf16 v[116:119], v[164:167], v[182:185], v[116:119]
	v_mfma_f32_16x16x32_bf16 v[112:115], v[172:175], v[182:185], v[112:115]
	v_mfma_f32_16x16x32_bf16 v[100:103], v[164:167], v[190:193], v[100:103]
	v_mfma_f32_16x16x32_bf16 v[96:99], v[172:175], v[190:193], v[96:99]
	v_mfma_f32_16x16x32_bf16 v[84:87], v[164:167], v[206:209], v[84:87]
	v_mfma_f32_16x16x32_bf16 v[80:83], v[172:175], v[206:209], v[80:83]
	v_mfma_f32_16x16x32_bf16 v[68:71], v[164:167], v[214:217], v[68:71]
	v_mfma_f32_16x16x32_bf16 v[64:67], v[172:175], v[214:217], v[64:67]
	v_mfma_f32_16x16x32_bf16 v[116:119], v[168:171], v[186:189], v[116:119]
	v_mfma_f32_16x16x32_bf16 v[112:115], v[178:181], v[186:189], v[112:115]
	v_mfma_f32_16x16x32_bf16 v[100:103], v[168:171], v[194:197], v[100:103]
	v_mfma_f32_16x16x32_bf16 v[96:99], v[178:181], v[194:197], v[96:99]
	v_mfma_f32_16x16x32_bf16 v[84:87], v[168:171], v[210:213], v[84:87]
	v_mfma_f32_16x16x32_bf16 v[80:83], v[178:181], v[210:213], v[80:83]
	v_mfma_f32_16x16x32_bf16 v[68:71], v[168:171], v[218:221], v[68:71]
	v_mfma_f32_16x16x32_bf16 v[64:67], v[178:181], v[218:221], v[64:67]
	s_setprio 0
	s_barrier
	ds_read_b128 v[182:185], v149 offset:49152
	ds_read_b128 v[186:189], v149 offset:50176
	ds_read_b128 v[190:193], v149 offset:51200
	ds_read_b128 v[194:197], v149 offset:52224
	ds_read_b128 v[206:209], v149 offset:53248
	ds_read_b128 v[210:213], v149 offset:54272
	ds_read_b128 v[214:217], v149 offset:55296
	ds_read_b128 v[218:221], v149 offset:56320
	s_mov_b32 m0, s3
	v_lshl_add_u64 v[142:143], v[142:143], 0, s[14:15]
	global_load_lds_dwordx4 v[142:143], off
	s_mov_b32 m0, s1
	v_lshl_add_u64 v[142:143], v[198:199], 0, s[14:15]
	global_load_lds_dwordx4 v[142:143], off
	s_mov_b32 m0, s2
	v_lshl_add_u64 v[142:143], s[34:35], 0, v[132:133]
	global_load_lds_dwordx4 v[142:143], off
	s_mov_b32 m0, s9
	v_lshl_add_u64 v[142:143], s[34:35], 0, v[128:129]
	global_load_lds_dwordx4 v[142:143], off
	s_mov_b32 m0, s77
	v_lshl_add_u64 v[142:143], v[202:203], 0, s[14:15]
	global_load_lds_dwordx4 v[142:143], off
	s_mov_b32 m0, s78
	v_lshl_add_u64 v[142:143], v[222:223], 0, s[14:15]
	global_load_lds_dwordx4 v[142:143], off
	s_waitcnt vmcnt(8)
	s_waitcnt lgkmcnt(0)
	s_barrier
	s_setprio 1
	v_mfma_f32_16x16x32_bf16 v[60:63], v[138:141], v[182:185], v[60:63]
	v_mfma_f32_16x16x32_bf16 v[56:59], v[156:159], v[182:185], v[56:59]
	v_mfma_f32_16x16x32_bf16 v[44:47], v[138:141], v[190:193], v[44:47]
	v_mfma_f32_16x16x32_bf16 v[40:43], v[156:159], v[190:193], v[40:43]
	v_mfma_f32_16x16x32_bf16 v[28:31], v[138:141], v[206:209], v[28:31]
	v_mfma_f32_16x16x32_bf16 v[24:27], v[156:159], v[206:209], v[24:27]
	v_mfma_f32_16x16x32_bf16 v[12:15], v[138:141], v[214:217], v[12:15]
	v_mfma_f32_16x16x32_bf16 v[8:11], v[156:159], v[214:217], v[8:11]
	v_mfma_f32_16x16x32_bf16 v[60:63], v[152:155], v[186:189], v[60:63]
	v_mfma_f32_16x16x32_bf16 v[56:59], v[160:163], v[186:189], v[56:59]
	v_mfma_f32_16x16x32_bf16 v[44:47], v[152:155], v[194:197], v[44:47]
	v_mfma_f32_16x16x32_bf16 v[40:43], v[160:163], v[194:197], v[40:43]
	v_mfma_f32_16x16x32_bf16 v[28:31], v[152:155], v[210:213], v[28:31]
	v_mfma_f32_16x16x32_bf16 v[24:27], v[160:163], v[210:213], v[24:27]
	v_mfma_f32_16x16x32_bf16 v[12:15], v[152:155], v[218:221], v[12:15]
	v_mfma_f32_16x16x32_bf16 v[8:11], v[160:163], v[218:221], v[8:11]
	v_mfma_f32_16x16x32_bf16 v[52:55], v[164:167], v[182:185], v[52:55]
	v_mfma_f32_16x16x32_bf16 v[48:51], v[172:175], v[182:185], v[48:51]
	v_mfma_f32_16x16x32_bf16 v[36:39], v[164:167], v[190:193], v[36:39]
	v_mfma_f32_16x16x32_bf16 v[32:35], v[172:175], v[190:193], v[32:35]
	v_mfma_f32_16x16x32_bf16 v[20:23], v[164:167], v[206:209], v[20:23]
	v_mfma_f32_16x16x32_bf16 v[16:19], v[172:175], v[206:209], v[16:19]
	v_mfma_f32_16x16x32_bf16 v[4:7], v[164:167], v[214:217], v[4:7]
	v_mfma_f32_16x16x32_bf16 v[0:3], v[172:175], v[214:217], v[0:3]
	v_mfma_f32_16x16x32_bf16 v[52:55], v[168:171], v[186:189], v[52:55]
	v_mfma_f32_16x16x32_bf16 v[48:51], v[178:181], v[186:189], v[48:51]
	v_mfma_f32_16x16x32_bf16 v[36:39], v[168:171], v[194:197], v[36:39]
	v_mfma_f32_16x16x32_bf16 v[32:35], v[178:181], v[194:197], v[32:35]
	v_mfma_f32_16x16x32_bf16 v[20:23], v[168:171], v[210:213], v[20:23]
	v_mfma_f32_16x16x32_bf16 v[16:19], v[178:181], v[210:213], v[16:19]
	v_mfma_f32_16x16x32_bf16 v[4:7], v[168:171], v[218:221], v[4:7]
	v_mfma_f32_16x16x32_bf16 v[0:3], v[178:181], v[218:221], v[0:3]
	s_setprio 0
	s_barrier
	s_mov_b64 s[54:55], 0
	s_mov_b64 s[34:35], -1
	s_mov_b64 s[52:53], 0x100
	s_cbranch_vccz .LBB0_849
	s_and_b64 vcc, exec, s[16:17]
	s_cbranch_vccz .LBB0_852
	s_barrier

.LBB0_877:
	ds_read_b128 v[142:145], v135 offset:1024
	ds_read_b128 v[146:149], v135 offset:2048
	ds_read_b128 v[150:153], v135 offset:3072
	ds_read_b128 v[154:157], v136
	ds_read_b128 v[158:161], v136 offset:1024
	ds_read_b128 v[162:165], v136 offset:2048
	ds_read_b128 v[166:169], v136 offset:3072
	ds_read_b128 v[170:173], v137
	ds_read_b128 v[178:181], v137 offset:1024
	ds_read_b128 v[182:185], v137 offset:2048
	ds_read_b128 v[186:189], v137 offset:3072
	ds_read_b128 v[190:193], v137 offset:4096
	ds_read_b128 v[194:197], v137 offset:5120
	ds_read_b128 v[206:209], v137 offset:6144
	ds_read_b128 v[210:213], v137 offset:7168
	s_add_u32 s2, s54, s64
	s_addc_u32 s3, s55, s65
	s_add_u32 s8, s2, 0x100
	s_addc_u32 s9, s3, 0
	s_and_b64 s[0:1], s[62:63], exec
	v_cndmask_b32_e64 v138, 0, 1, s[66:67]
	s_cselect_b32 s67, s21, s9
	s_cselect_b32 s66, s23, s8
	s_add_u32 s0, s30, s64
	s_addc_u32 s1, s31, s65
	s_add_u32 s8, s0, 0x100
	s_addc_u32 s9, s1, 0
	s_and_b64 s[0:1], s[62:63], exec
	s_cselect_b32 s69, s95, s9
	s_cselect_b32 s68, s96, s8
	s_add_u32 s72, s2, 0x10080
	v_cmp_ne_u32_e32 vcc, 1, v138
	ds_read_b128 v[138:141], v135
	s_addc_u32 s73, s3, 0
	s_add_i32 s19, s91, s77
	s_add_i32 m0, s80, 0xc000
	s_add_i32 s38, s80, 0xe000
	s_add_i32 s0, s19, 0x2000
	s_add_u32 s70, s68, 0x10000
	s_addc_u32 s71, s69, 0
	s_add_i32 s76, s92, s77
	s_add_i32 s18, s76, 0x2000
	s_add_i32 s3, 0, 0x18000
	s_add_i32 s2, 0, 0x1c000
	s_add_u32 s64, s66, 0x10000
	s_addc_u32 s65, s67, 0
	s_add_i32 s1, s3, s77
	s_add_i32 s9, s1, 0x2000
	s_add_u32 s62, s68, 0x10080
	s_addc_u32 s63, s69, 0
	s_add_i32 s97, s2, s77
	s_add_i32 s8, s97, 0x2000
	v_lshl_add_u64 v[174:175], s[72:73], 0, v[128:129]
	global_load_lds_dwordx4 v[174:175], off
	s_mov_b32 m0, s38
	v_lshl_add_u64 v[174:175], s[72:73], 0, v[130:131]
	global_load_lds_dwordx4 v[174:175], off
	s_waitcnt vmcnt(8)
	s_waitcnt lgkmcnt(0)
	s_barrier
	s_setprio 1
	v_mfma_f32_16x16x32_bf16 v[124:127], v[138:141], v[170:173], v[124:127]
	v_mfma_f32_16x16x32_bf16 v[120:123], v[146:149], v[170:173], v[120:123]
	v_mfma_f32_16x16x32_bf16 v[116:119], v[138:141], v[182:185], v[116:119]
	v_mfma_f32_16x16x32_bf16 v[112:115], v[146:149], v[182:185], v[112:115]
	v_mfma_f32_16x16x32_bf16 v[104:107], v[138:141], v[190:193], v[104:107]
	v_mfma_f32_16x16x32_bf16 v[96:99], v[146:149], v[190:193], v[96:99]
	v_mfma_f32_16x16x32_bf16 v[88:91], v[138:141], v[206:209], v[88:91]
	v_mfma_f32_16x16x32_bf16 v[80:83], v[146:149], v[206:209], v[80:83]
	v_mfma_f32_16x16x32_bf16 v[124:127], v[142:145], v[178:181], v[124:127]
	v_mfma_f32_16x16x32_bf16 v[120:123], v[150:153], v[178:181], v[120:123]
	v_mfma_f32_16x16x32_bf16 v[116:119], v[142:145], v[186:189], v[116:119]
	v_mfma_f32_16x16x32_bf16 v[112:115], v[150:153], v[186:189], v[112:115]
	v_mfma_f32_16x16x32_bf16 v[104:107], v[142:145], v[194:197], v[104:107]
	v_mfma_f32_16x16x32_bf16 v[96:99], v[150:153], v[194:197], v[96:99]
	v_mfma_f32_16x16x32_bf16 v[88:91], v[142:145], v[210:213], v[88:91]
	v_mfma_f32_16x16x32_bf16 v[80:83], v[150:153], v[210:213], v[80:83]
	v_mfma_f32_16x16x32_bf16 v[108:111], v[154:157], v[170:173], v[108:111]
	v_mfma_f32_16x16x32_bf16 v[100:103], v[162:165], v[170:173], v[100:103]
	v_mfma_f32_16x16x32_bf16 v[92:95], v[154:157], v[182:185], v[92:95]
	v_mfma_f32_16x16x32_bf16 v[84:87], v[162:165], v[182:185], v[84:87]
	v_mfma_f32_16x16x32_bf16 v[76:79], v[154:157], v[190:193], v[76:79]
	v_mfma_f32_16x16x32_bf16 v[72:75], v[162:165], v[190:193], v[72:75]
	v_mfma_f32_16x16x32_bf16 v[68:71], v[154:157], v[206:209], v[68:71]
	v_mfma_f32_16x16x32_bf16 v[64:67], v[162:165], v[206:209], v[64:67]
	v_mfma_f32_16x16x32_bf16 v[108:111], v[158:161], v[178:181], v[108:111]
	v_mfma_f32_16x16x32_bf16 v[100:103], v[166:169], v[178:181], v[100:103]
	v_mfma_f32_16x16x32_bf16 v[92:95], v[158:161], v[186:189], v[92:95]
	v_mfma_f32_16x16x32_bf16 v[84:87], v[166:169], v[186:189], v[84:87]
	v_mfma_f32_16x16x32_bf16 v[76:79], v[158:161], v[194:197], v[76:79]
	v_mfma_f32_16x16x32_bf16 v[72:75], v[166:169], v[194:197], v[72:75]
	v_mfma_f32_16x16x32_bf16 v[68:71], v[158:161], v[210:213], v[68:71]
	v_mfma_f32_16x16x32_bf16 v[64:67], v[166:169], v[210:213], v[64:67]
	s_setprio 0
	s_barrier
	ds_read_b128 v[170:173], v137 offset:16384
	ds_read_b128 v[178:181], v137 offset:17408
	ds_read_b128 v[182:185], v137 offset:18432
	ds_read_b128 v[186:189], v137 offset:19456
	ds_read_b128 v[190:193], v137 offset:20480
	ds_read_b128 v[194:197], v137 offset:21504
	ds_read_b128 v[206:209], v137 offset:22528
	ds_read_b128 v[210:213], v137 offset:23552
	s_mov_b32 m0, s19
	v_lshl_add_u64 v[174:175], s[68:69], 0, v[128:129]
	global_load_lds_dwordx4 v[174:175], off
	v_lshl_add_u64 v[198:199], s[68:69], 0, v[130:131]
	s_mov_b32 m0, s0
	v_lshl_add_u64 v[202:203], s[70:71], 0, v[128:129]
	global_load_lds_dwordx4 v[198:199], off
	s_mov_b32 m0, s76
	v_lshl_add_u64 v[214:215], s[66:67], 0, v[130:131]
	global_load_lds_dwordx4 v[202:203], off
	s_mov_b32 m0, s18
	v_lshl_add_u64 v[202:203], s[70:71], 0, v[130:131]
	global_load_lds_dwordx4 v[202:203], off
	s_mov_b32 m0, s80
	v_lshl_add_u64 v[202:203], s[66:67], 0, v[128:129]
	global_load_lds_dwordx4 v[202:203], off
	s_mov_b32 m0, s81
	s_nop 0
	global_load_lds_dwordx4 v[214:215], off
	s_waitcnt vmcnt(8)
	s_waitcnt lgkmcnt(0)
	s_barrier
	s_setprio 1
	v_mfma_f32_16x16x32_bf16 v[60:63], v[138:141], v[170:173], v[60:63]
	v_mfma_f32_16x16x32_bf16 v[56:59], v[146:149], v[170:173], v[56:59]
	v_mfma_f32_16x16x32_bf16 v[52:55], v[138:141], v[182:185], v[52:55]
	v_mfma_f32_16x16x32_bf16 v[48:51], v[146:149], v[182:185], v[48:51]
	v_mfma_f32_16x16x32_bf16 v[40:43], v[138:141], v[190:193], v[40:43]
	v_mfma_f32_16x16x32_bf16 v[32:35], v[146:149], v[190:193], v[32:35]
	v_mfma_f32_16x16x32_bf16 v[24:27], v[138:141], v[206:209], v[24:27]
	v_mfma_f32_16x16x32_bf16 v[16:19], v[146:149], v[206:209], v[16:19]
	v_mfma_f32_16x16x32_bf16 v[60:63], v[142:145], v[178:181], v[60:63]
	v_mfma_f32_16x16x32_bf16 v[56:59], v[150:153], v[178:181], v[56:59]
	v_mfma_f32_16x16x32_bf16 v[52:55], v[142:145], v[186:189], v[52:55]
	v_mfma_f32_16x16x32_bf16 v[48:51], v[150:153], v[186:189], v[48:51]
	v_mfma_f32_16x16x32_bf16 v[40:43], v[142:145], v[194:197], v[40:43]
	v_mfma_f32_16x16x32_bf16 v[32:35], v[150:153], v[194:197], v[32:35]
	v_mfma_f32_16x16x32_bf16 v[24:27], v[142:145], v[210:213], v[24:27]
	v_mfma_f32_16x16x32_bf16 v[16:19], v[150:153], v[210:213], v[16:19]
	v_mfma_f32_16x16x32_bf16 v[44:47], v[154:157], v[170:173], v[44:47]
	v_mfma_f32_16x16x32_bf16 v[36:39], v[162:165], v[170:173], v[36:39]
	v_mfma_f32_16x16x32_bf16 v[28:31], v[154:157], v[182:185], v[28:31]
	v_mfma_f32_16x16x32_bf16 v[20:23], v[162:165], v[182:185], v[20:23]
	v_mfma_f32_16x16x32_bf16 v[12:15], v[154:157], v[190:193], v[12:15]
	v_mfma_f32_16x16x32_bf16 v[8:11], v[162:165], v[190:193], v[8:11]
	v_mfma_f32_16x16x32_bf16 v[4:7], v[154:157], v[206:209], v[4:7]
	v_mfma_f32_16x16x32_bf16 v[0:3], v[162:165], v[206:209], v[0:3]
	v_mfma_f32_16x16x32_bf16 v[44:47], v[158:161], v[178:181], v[44:47]
	v_mfma_f32_16x16x32_bf16 v[36:39], v[166:169], v[178:181], v[36:39]
	v_mfma_f32_16x16x32_bf16 v[28:31], v[158:161], v[186:189], v[28:31]
	v_mfma_f32_16x16x32_bf16 v[20:23], v[166:169], v[186:189], v[20:23]
	v_mfma_f32_16x16x32_bf16 v[12:15], v[158:161], v[194:197], v[12:15]
	v_mfma_f32_16x16x32_bf16 v[8:11], v[166:169], v[194:197], v[8:11]
	v_mfma_f32_16x16x32_bf16 v[4:7], v[158:161], v[210:213], v[4:7]
	v_mfma_f32_16x16x32_bf16 v[0:3], v[166:169], v[210:213], v[0:3]
	s_setprio 0
	s_barrier
	ds_read_b128 v[170:173], v137 offset:32768
	ds_read_b128 v[178:181], v137 offset:33792
	ds_read_b128 v[182:185], v137 offset:34816
	ds_read_b128 v[186:189], v137 offset:35840
	ds_read_b128 v[190:193], v137 offset:36864
	ds_read_b128 v[194:197], v137 offset:37888
	ds_read_b128 v[206:209], v137 offset:38912
	ds_read_b128 v[210:213], v137 offset:39936
	v_add_u32_e32 v150, s3, v134
	v_add_u32_e32 v166, s2, v134
	ds_read_b128 v[138:141], v150
	ds_read_b128 v[142:145], v150 offset:1024
	ds_read_b128 v[146:149], v150 offset:2048
	ds_read_b128 v[150:153], v150 offset:3072
	ds_read_b128 v[154:157], v166
	ds_read_b128 v[158:161], v166 offset:1024
	ds_read_b128 v[162:165], v166 offset:2048
	ds_read_b128 v[166:169], v166 offset:3072
	s_mov_b32 m0, s82
	v_lshl_add_u64 v[216:217], s[64:65], 0, v[128:129]
	global_load_lds_dwordx4 v[216:217], off
	s_mov_b32 m0, s83
	v_lshl_add_u64 v[216:217], s[64:65], 0, v[130:131]
	global_load_lds_dwordx4 v[216:217], off
	s_waitcnt vmcnt(8)
	s_waitcnt lgkmcnt(0)
	s_barrier
	s_setprio 1
	v_mfma_f32_16x16x32_bf16 v[124:127], v[138:141], v[170:173], v[124:127]
	v_mfma_f32_16x16x32_bf16 v[120:123], v[146:149], v[170:173], v[120:123]
	v_mfma_f32_16x16x32_bf16 v[116:119], v[138:141], v[182:185], v[116:119]
	v_mfma_f32_16x16x32_bf16 v[112:115], v[146:149], v[182:185], v[112:115]
	v_mfma_f32_16x16x32_bf16 v[104:107], v[138:141], v[190:193], v[104:107]
	v_mfma_f32_16x16x32_bf16 v[96:99], v[146:149], v[190:193], v[96:99]
	v_mfma_f32_16x16x32_bf16 v[88:91], v[138:141], v[206:209], v[88:91]
	v_mfma_f32_16x16x32_bf16 v[80:83], v[146:149], v[206:209], v[80:83]
	v_mfma_f32_16x16x32_bf16 v[124:127], v[142:145], v[178:181], v[124:127]
	v_mfma_f32_16x16x32_bf16 v[120:123], v[150:153], v[178:181], v[120:123]
	v_mfma_f32_16x16x32_bf16 v[116:119], v[142:145], v[186:189], v[116:119]
	v_mfma_f32_16x16x32_bf16 v[112:115], v[150:153], v[186:189], v[112:115]
	v_mfma_f32_16x16x32_bf16 v[104:107], v[142:145], v[194:197], v[104:107]
	v_mfma_f32_16x16x32_bf16 v[96:99], v[150:153], v[194:197], v[96:99]
	v_mfma_f32_16x16x32_bf16 v[88:91], v[142:145], v[210:213], v[88:91]
	v_mfma_f32_16x16x32_bf16 v[80:83], v[150:153], v[210:213], v[80:83]
	v_mfma_f32_16x16x32_bf16 v[108:111], v[154:157], v[170:173], v[108:111]
	v_mfma_f32_16x16x32_bf16 v[100:103], v[162:165], v[170:173], v[100:103]
	v_mfma_f32_16x16x32_bf16 v[92:95], v[154:157], v[182:185], v[92:95]
	v_mfma_f32_16x16x32_bf16 v[84:87], v[162:165], v[182:185], v[84:87]
	v_mfma_f32_16x16x32_bf16 v[76:79], v[154:157], v[190:193], v[76:79]
	v_mfma_f32_16x16x32_bf16 v[72:75], v[162:165], v[190:193], v[72:75]
	v_mfma_f32_16x16x32_bf16 v[68:71], v[154:157], v[206:209], v[68:71]
	v_mfma_f32_16x16x32_bf16 v[64:67], v[162:165], v[206:209], v[64:67]
	v_mfma_f32_16x16x32_bf16 v[108:111], v[158:161], v[178:181], v[108:111]
	v_mfma_f32_16x16x32_bf16 v[100:103], v[166:169], v[178:181], v[100:103]
	v_mfma_f32_16x16x32_bf16 v[92:95], v[158:161], v[186:189], v[92:95]
	v_mfma_f32_16x16x32_bf16 v[84:87], v[166:169], v[186:189], v[84:87]
	v_mfma_f32_16x16x32_bf16 v[76:79], v[158:161], v[194:197], v[76:79]
	v_mfma_f32_16x16x32_bf16 v[72:75], v[166:169], v[194:197], v[72:75]
	v_mfma_f32_16x16x32_bf16 v[68:71], v[158:161], v[210:213], v[68:71]
	v_mfma_f32_16x16x32_bf16 v[64:67], v[166:169], v[210:213], v[64:67]
	s_setprio 0
	s_barrier
	ds_read_b128 v[170:173], v137 offset:49152
	ds_read_b128 v[178:181], v137 offset:50176
	ds_read_b128 v[182:185], v137 offset:51200
	ds_read_b128 v[186:189], v137 offset:52224
	ds_read_b128 v[190:193], v137 offset:53248
	ds_read_b128 v[194:197], v137 offset:54272
	ds_read_b128 v[206:209], v137 offset:55296
	ds_read_b128 v[210:213], v137 offset:56320
	s_mov_b32 m0, s1
	v_lshl_add_u64 v[174:175], v[174:175], 0, s[26:27]
	global_load_lds_dwordx4 v[174:175], off
	s_mov_b32 m0, s9
	v_lshl_add_u64 v[174:175], v[198:199], 0, s[26:27]
	global_load_lds_dwordx4 v[174:175], off
	s_mov_b32 m0, s97
	v_lshl_add_u64 v[174:175], s[62:63], 0, v[128:129]
	global_load_lds_dwordx4 v[174:175], off
	s_mov_b32 m0, s8
	v_lshl_add_u64 v[174:175], s[62:63], 0, v[130:131]
	global_load_lds_dwordx4 v[174:175], off
	s_mov_b32 m0, s89
	v_lshl_add_u64 v[174:175], v[202:203], 0, s[26:27]
	global_load_lds_dwordx4 v[174:175], off
	s_mov_b32 m0, s90
	v_lshl_add_u64 v[174:175], v[214:215], 0, s[26:27]
	global_load_lds_dwordx4 v[174:175], off
	s_waitcnt vmcnt(8)
	s_waitcnt lgkmcnt(0)
	s_barrier
	s_setprio 1
	v_mfma_f32_16x16x32_bf16 v[60:63], v[138:141], v[170:173], v[60:63]
	v_mfma_f32_16x16x32_bf16 v[56:59], v[146:149], v[170:173], v[56:59]
	v_mfma_f32_16x16x32_bf16 v[52:55], v[138:141], v[182:185], v[52:55]
	v_mfma_f32_16x16x32_bf16 v[48:51], v[146:149], v[182:185], v[48:51]
	v_mfma_f32_16x16x32_bf16 v[40:43], v[138:141], v[190:193], v[40:43]
	v_mfma_f32_16x16x32_bf16 v[32:35], v[146:149], v[190:193], v[32:35]
	v_mfma_f32_16x16x32_bf16 v[24:27], v[138:141], v[206:209], v[24:27]
	v_mfma_f32_16x16x32_bf16 v[16:19], v[146:149], v[206:209], v[16:19]
	v_mfma_f32_16x16x32_bf16 v[60:63], v[142:145], v[178:181], v[60:63]
	v_mfma_f32_16x16x32_bf16 v[56:59], v[150:153], v[178:181], v[56:59]
	v_mfma_f32_16x16x32_bf16 v[52:55], v[142:145], v[186:189], v[52:55]
	v_mfma_f32_16x16x32_bf16 v[48:51], v[150:153], v[186:189], v[48:51]
	v_mfma_f32_16x16x32_bf16 v[40:43], v[142:145], v[194:197], v[40:43]
	v_mfma_f32_16x16x32_bf16 v[32:35], v[150:153], v[194:197], v[32:35]
	v_mfma_f32_16x16x32_bf16 v[24:27], v[142:145], v[210:213], v[24:27]
	v_mfma_f32_16x16x32_bf16 v[16:19], v[150:153], v[210:213], v[16:19]
	v_mfma_f32_16x16x32_bf16 v[44:47], v[154:157], v[170:173], v[44:47]
	v_mfma_f32_16x16x32_bf16 v[36:39], v[162:165], v[170:173], v[36:39]
	v_mfma_f32_16x16x32_bf16 v[28:31], v[154:157], v[182:185], v[28:31]
	v_mfma_f32_16x16x32_bf16 v[20:23], v[162:165], v[182:185], v[20:23]
	v_mfma_f32_16x16x32_bf16 v[12:15], v[154:157], v[190:193], v[12:15]
	v_mfma_f32_16x16x32_bf16 v[8:11], v[162:165], v[190:193], v[8:11]
	v_mfma_f32_16x16x32_bf16 v[4:7], v[154:157], v[206:209], v[4:7]
	v_mfma_f32_16x16x32_bf16 v[0:3], v[162:165], v[206:209], v[0:3]
	v_mfma_f32_16x16x32_bf16 v[44:47], v[158:161], v[178:181], v[44:47]
	v_mfma_f32_16x16x32_bf16 v[36:39], v[166:169], v[178:181], v[36:39]
	v_mfma_f32_16x16x32_bf16 v[28:31], v[158:161], v[186:189], v[28:31]
	v_mfma_f32_16x16x32_bf16 v[20:23], v[166:169], v[186:189], v[20:23]
	v_mfma_f32_16x16x32_bf16 v[12:15], v[158:161], v[194:197], v[12:15]
	v_mfma_f32_16x16x32_bf16 v[8:11], v[166:169], v[194:197], v[8:11]
	v_mfma_f32_16x16x32_bf16 v[4:7], v[158:161], v[210:213], v[4:7]
	v_mfma_f32_16x16x32_bf16 v[0:3], v[166:169], v[210:213], v[0:3]
	s_setprio 0
	s_barrier
	s_mov_b64 s[66:67], 0
	s_mov_b64 s[62:63], -1
	s_mov_b64 s[64:65], 0x100
	s_cbranch_vccz .LBB0_877
	s_and_b64 vcc, exec, s[28:29]
	s_cbranch_vccz .LBB0_880
	s_barrier

.LBB0_904:
	ds_read_b128 v[142:145], v135 offset:1024
	ds_read_b128 v[146:149], v135 offset:2048
	ds_read_b128 v[150:153], v135 offset:3072
	ds_read_b128 v[154:157], v136
	ds_read_b128 v[158:161], v136 offset:1024
	ds_read_b128 v[162:165], v136 offset:2048
	ds_read_b128 v[166:169], v136 offset:3072
	ds_read_b128 v[170:173], v137
	ds_read_b128 v[178:181], v137 offset:1024
	ds_read_b128 v[182:185], v137 offset:2048
	ds_read_b128 v[186:189], v137 offset:3072
	ds_read_b128 v[190:193], v137 offset:4096
	ds_read_b128 v[194:197], v137 offset:5120
	ds_read_b128 v[206:209], v137 offset:6144
	ds_read_b128 v[210:213], v137 offset:7168
	s_add_u32 s2, s28, s56
	s_addc_u32 s3, s29, s57
	s_add_u32 s8, s2, 0x100
	s_addc_u32 s9, s3, 0
	s_and_b64 s[0:1], s[54:55], exec
	v_cndmask_b32_e64 v138, 0, 1, s[58:59]
	s_cselect_b32 s59, s13, s9
	s_cselect_b32 s58, s15, s8
	s_add_u32 s0, s22, s56
	s_addc_u32 s1, s23, s57
	s_add_u32 s8, s0, 0x100
	s_addc_u32 s9, s1, 0
	s_and_b64 s[0:1], s[54:55], exec
	s_cselect_b32 s61, s87, s9
	s_cselect_b32 s60, s88, s8
	s_add_u32 s64, s2, 0x10080
	v_cmp_ne_u32_e32 vcc, 1, v138
	ds_read_b128 v[138:141], v135
	s_addc_u32 s65, s3, 0
	s_add_i32 s38, s83, s66
	s_add_i32 m0, s69, 0xc000
	s_add_i32 s39, s69, 0xe000
	s_add_i32 s0, s38, 0x2000
	s_add_u32 s62, s60, 0x10000
	s_addc_u32 s63, s61, 0
	s_add_i32 s90, s84, s66
	s_add_i32 s76, s90, 0x2000
	s_add_i32 s3, 0, 0x18000
	s_add_i32 s2, 0, 0x1c000
	s_add_u32 s56, s58, 0x10000
	s_addc_u32 s57, s59, 0
	s_add_i32 s1, s3, s66
	s_add_i32 s9, s1, 0x2000
	s_add_u32 s54, s60, 0x10080
	s_addc_u32 s55, s61, 0
	s_add_i32 s89, s2, s66
	s_add_i32 s8, s89, 0x2000
	v_lshl_add_u64 v[174:175], s[64:65], 0, v[128:129]
	global_load_lds_dwordx4 v[174:175], off
	s_mov_b32 m0, s39
	v_lshl_add_u64 v[174:175], s[64:65], 0, v[130:131]
	global_load_lds_dwordx4 v[174:175], off
	s_waitcnt vmcnt(8)
	s_waitcnt lgkmcnt(0)
	s_barrier
	s_setprio 1
	v_mfma_f32_16x16x32_bf16 v[124:127], v[138:141], v[170:173], v[124:127]
	v_mfma_f32_16x16x32_bf16 v[120:123], v[146:149], v[170:173], v[120:123]
	v_mfma_f32_16x16x32_bf16 v[116:119], v[138:141], v[182:185], v[116:119]
	v_mfma_f32_16x16x32_bf16 v[112:115], v[146:149], v[182:185], v[112:115]
	v_mfma_f32_16x16x32_bf16 v[104:107], v[138:141], v[190:193], v[104:107]
	v_mfma_f32_16x16x32_bf16 v[96:99], v[146:149], v[190:193], v[96:99]
	v_mfma_f32_16x16x32_bf16 v[88:91], v[138:141], v[206:209], v[88:91]
	v_mfma_f32_16x16x32_bf16 v[80:83], v[146:149], v[206:209], v[80:83]
	v_mfma_f32_16x16x32_bf16 v[124:127], v[142:145], v[178:181], v[124:127]
	v_mfma_f32_16x16x32_bf16 v[120:123], v[150:153], v[178:181], v[120:123]
	v_mfma_f32_16x16x32_bf16 v[116:119], v[142:145], v[186:189], v[116:119]
	v_mfma_f32_16x16x32_bf16 v[112:115], v[150:153], v[186:189], v[112:115]
	v_mfma_f32_16x16x32_bf16 v[104:107], v[142:145], v[194:197], v[104:107]
	v_mfma_f32_16x16x32_bf16 v[96:99], v[150:153], v[194:197], v[96:99]
	v_mfma_f32_16x16x32_bf16 v[88:91], v[142:145], v[210:213], v[88:91]
	v_mfma_f32_16x16x32_bf16 v[80:83], v[150:153], v[210:213], v[80:83]
	v_mfma_f32_16x16x32_bf16 v[108:111], v[154:157], v[170:173], v[108:111]
	v_mfma_f32_16x16x32_bf16 v[100:103], v[162:165], v[170:173], v[100:103]
	v_mfma_f32_16x16x32_bf16 v[92:95], v[154:157], v[182:185], v[92:95]
	v_mfma_f32_16x16x32_bf16 v[84:87], v[162:165], v[182:185], v[84:87]
	v_mfma_f32_16x16x32_bf16 v[76:79], v[154:157], v[190:193], v[76:79]
	v_mfma_f32_16x16x32_bf16 v[72:75], v[162:165], v[190:193], v[72:75]
	v_mfma_f32_16x16x32_bf16 v[68:71], v[154:157], v[206:209], v[68:71]
	v_mfma_f32_16x16x32_bf16 v[64:67], v[162:165], v[206:209], v[64:67]
	v_mfma_f32_16x16x32_bf16 v[108:111], v[158:161], v[178:181], v[108:111]
	v_mfma_f32_16x16x32_bf16 v[100:103], v[166:169], v[178:181], v[100:103]
	v_mfma_f32_16x16x32_bf16 v[92:95], v[158:161], v[186:189], v[92:95]
	v_mfma_f32_16x16x32_bf16 v[84:87], v[166:169], v[186:189], v[84:87]
	v_mfma_f32_16x16x32_bf16 v[76:79], v[158:161], v[194:197], v[76:79]
	v_mfma_f32_16x16x32_bf16 v[72:75], v[166:169], v[194:197], v[72:75]
	v_mfma_f32_16x16x32_bf16 v[68:71], v[158:161], v[210:213], v[68:71]
	v_mfma_f32_16x16x32_bf16 v[64:67], v[166:169], v[210:213], v[64:67]
	s_setprio 0
	s_barrier
	ds_read_b128 v[170:173], v137 offset:16384
	ds_read_b128 v[178:181], v137 offset:17408
	ds_read_b128 v[182:185], v137 offset:18432
	ds_read_b128 v[186:189], v137 offset:19456
	ds_read_b128 v[190:193], v137 offset:20480
	ds_read_b128 v[194:197], v137 offset:21504
	ds_read_b128 v[206:209], v137 offset:22528
	ds_read_b128 v[210:213], v137 offset:23552
	s_mov_b32 m0, s38
	v_lshl_add_u64 v[174:175], s[60:61], 0, v[128:129]
	global_load_lds_dwordx4 v[174:175], off
	v_lshl_add_u64 v[198:199], s[60:61], 0, v[130:131]
	s_mov_b32 m0, s0
	v_lshl_add_u64 v[202:203], s[62:63], 0, v[128:129]
	global_load_lds_dwordx4 v[198:199], off
	s_mov_b32 m0, s90
	v_lshl_add_u64 v[214:215], s[58:59], 0, v[130:131]
	global_load_lds_dwordx4 v[202:203], off
	s_mov_b32 m0, s76
	v_lshl_add_u64 v[202:203], s[62:63], 0, v[130:131]
	global_load_lds_dwordx4 v[202:203], off
	s_mov_b32 m0, s69
	v_lshl_add_u64 v[202:203], s[58:59], 0, v[128:129]
	global_load_lds_dwordx4 v[202:203], off
	s_mov_b32 m0, s70
	s_nop 0
	global_load_lds_dwordx4 v[214:215], off
	s_waitcnt vmcnt(8)
	s_waitcnt lgkmcnt(0)
	s_barrier
	s_setprio 1
	v_mfma_f32_16x16x32_bf16 v[60:63], v[138:141], v[170:173], v[60:63]
	v_mfma_f32_16x16x32_bf16 v[56:59], v[146:149], v[170:173], v[56:59]
	v_mfma_f32_16x16x32_bf16 v[52:55], v[138:141], v[182:185], v[52:55]
	v_mfma_f32_16x16x32_bf16 v[48:51], v[146:149], v[182:185], v[48:51]
	v_mfma_f32_16x16x32_bf16 v[40:43], v[138:141], v[190:193], v[40:43]
	v_mfma_f32_16x16x32_bf16 v[32:35], v[146:149], v[190:193], v[32:35]
	v_mfma_f32_16x16x32_bf16 v[24:27], v[138:141], v[206:209], v[24:27]
	v_mfma_f32_16x16x32_bf16 v[16:19], v[146:149], v[206:209], v[16:19]
	v_mfma_f32_16x16x32_bf16 v[60:63], v[142:145], v[178:181], v[60:63]
	v_mfma_f32_16x16x32_bf16 v[56:59], v[150:153], v[178:181], v[56:59]
	v_mfma_f32_16x16x32_bf16 v[52:55], v[142:145], v[186:189], v[52:55]
	v_mfma_f32_16x16x32_bf16 v[48:51], v[150:153], v[186:189], v[48:51]
	v_mfma_f32_16x16x32_bf16 v[40:43], v[142:145], v[194:197], v[40:43]
	v_mfma_f32_16x16x32_bf16 v[32:35], v[150:153], v[194:197], v[32:35]
	v_mfma_f32_16x16x32_bf16 v[24:27], v[142:145], v[210:213], v[24:27]
	v_mfma_f32_16x16x32_bf16 v[16:19], v[150:153], v[210:213], v[16:19]
	v_mfma_f32_16x16x32_bf16 v[44:47], v[154:157], v[170:173], v[44:47]
	v_mfma_f32_16x16x32_bf16 v[36:39], v[162:165], v[170:173], v[36:39]
	v_mfma_f32_16x16x32_bf16 v[28:31], v[154:157], v[182:185], v[28:31]
	v_mfma_f32_16x16x32_bf16 v[20:23], v[162:165], v[182:185], v[20:23]
	v_mfma_f32_16x16x32_bf16 v[12:15], v[154:157], v[190:193], v[12:15]
	v_mfma_f32_16x16x32_bf16 v[8:11], v[162:165], v[190:193], v[8:11]
	v_mfma_f32_16x16x32_bf16 v[4:7], v[154:157], v[206:209], v[4:7]
	v_mfma_f32_16x16x32_bf16 v[0:3], v[162:165], v[206:209], v[0:3]
	v_mfma_f32_16x16x32_bf16 v[44:47], v[158:161], v[178:181], v[44:47]
	v_mfma_f32_16x16x32_bf16 v[36:39], v[166:169], v[178:181], v[36:39]
	v_mfma_f32_16x16x32_bf16 v[28:31], v[158:161], v[186:189], v[28:31]
	v_mfma_f32_16x16x32_bf16 v[20:23], v[166:169], v[186:189], v[20:23]
	v_mfma_f32_16x16x32_bf16 v[12:15], v[158:161], v[194:197], v[12:15]
	v_mfma_f32_16x16x32_bf16 v[8:11], v[166:169], v[194:197], v[8:11]
	v_mfma_f32_16x16x32_bf16 v[4:7], v[158:161], v[210:213], v[4:7]
	v_mfma_f32_16x16x32_bf16 v[0:3], v[166:169], v[210:213], v[0:3]
	s_setprio 0
	s_barrier
	ds_read_b128 v[170:173], v137 offset:32768
	ds_read_b128 v[178:181], v137 offset:33792
	ds_read_b128 v[182:185], v137 offset:34816
	ds_read_b128 v[186:189], v137 offset:35840
	ds_read_b128 v[190:193], v137 offset:36864
	ds_read_b128 v[194:197], v137 offset:37888
	ds_read_b128 v[206:209], v137 offset:38912
	ds_read_b128 v[210:213], v137 offset:39936
	v_add_u32_e32 v150, s3, v134
	v_add_u32_e32 v166, s2, v134
	ds_read_b128 v[138:141], v150
	ds_read_b128 v[142:145], v150 offset:1024
	ds_read_b128 v[146:149], v150 offset:2048
	ds_read_b128 v[150:153], v150 offset:3072
	ds_read_b128 v[154:157], v166
	ds_read_b128 v[158:161], v166 offset:1024
	ds_read_b128 v[162:165], v166 offset:2048
	ds_read_b128 v[166:169], v166 offset:3072
	s_mov_b32 m0, s71
	v_lshl_add_u64 v[216:217], s[56:57], 0, v[128:129]
	global_load_lds_dwordx4 v[216:217], off
	s_mov_b32 m0, s72
	v_lshl_add_u64 v[216:217], s[56:57], 0, v[130:131]
	global_load_lds_dwordx4 v[216:217], off
	s_waitcnt vmcnt(8)
	s_waitcnt lgkmcnt(0)
	s_barrier
	s_setprio 1
	v_mfma_f32_16x16x32_bf16 v[124:127], v[138:141], v[170:173], v[124:127]
	v_mfma_f32_16x16x32_bf16 v[120:123], v[146:149], v[170:173], v[120:123]
	v_mfma_f32_16x16x32_bf16 v[116:119], v[138:141], v[182:185], v[116:119]
	v_mfma_f32_16x16x32_bf16 v[112:115], v[146:149], v[182:185], v[112:115]
	v_mfma_f32_16x16x32_bf16 v[104:107], v[138:141], v[190:193], v[104:107]
	v_mfma_f32_16x16x32_bf16 v[96:99], v[146:149], v[190:193], v[96:99]
	v_mfma_f32_16x16x32_bf16 v[88:91], v[138:141], v[206:209], v[88:91]
	v_mfma_f32_16x16x32_bf16 v[80:83], v[146:149], v[206:209], v[80:83]
	v_mfma_f32_16x16x32_bf16 v[124:127], v[142:145], v[178:181], v[124:127]
	v_mfma_f32_16x16x32_bf16 v[120:123], v[150:153], v[178:181], v[120:123]
	v_mfma_f32_16x16x32_bf16 v[116:119], v[142:145], v[186:189], v[116:119]
	v_mfma_f32_16x16x32_bf16 v[112:115], v[150:153], v[186:189], v[112:115]
	v_mfma_f32_16x16x32_bf16 v[104:107], v[142:145], v[194:197], v[104:107]
	v_mfma_f32_16x16x32_bf16 v[96:99], v[150:153], v[194:197], v[96:99]
	v_mfma_f32_16x16x32_bf16 v[88:91], v[142:145], v[210:213], v[88:91]
	v_mfma_f32_16x16x32_bf16 v[80:83], v[150:153], v[210:213], v[80:83]
	v_mfma_f32_16x16x32_bf16 v[108:111], v[154:157], v[170:173], v[108:111]
	v_mfma_f32_16x16x32_bf16 v[100:103], v[162:165], v[170:173], v[100:103]
	v_mfma_f32_16x16x32_bf16 v[92:95], v[154:157], v[182:185], v[92:95]
	v_mfma_f32_16x16x32_bf16 v[84:87], v[162:165], v[182:185], v[84:87]
	v_mfma_f32_16x16x32_bf16 v[76:79], v[154:157], v[190:193], v[76:79]
	v_mfma_f32_16x16x32_bf16 v[72:75], v[162:165], v[190:193], v[72:75]
	v_mfma_f32_16x16x32_bf16 v[68:71], v[154:157], v[206:209], v[68:71]
	v_mfma_f32_16x16x32_bf16 v[64:67], v[162:165], v[206:209], v[64:67]
	v_mfma_f32_16x16x32_bf16 v[108:111], v[158:161], v[178:181], v[108:111]
	v_mfma_f32_16x16x32_bf16 v[100:103], v[166:169], v[178:181], v[100:103]
	v_mfma_f32_16x16x32_bf16 v[92:95], v[158:161], v[186:189], v[92:95]
	v_mfma_f32_16x16x32_bf16 v[84:87], v[166:169], v[186:189], v[84:87]
	v_mfma_f32_16x16x32_bf16 v[76:79], v[158:161], v[194:197], v[76:79]
	v_mfma_f32_16x16x32_bf16 v[72:75], v[166:169], v[194:197], v[72:75]
	v_mfma_f32_16x16x32_bf16 v[68:71], v[158:161], v[210:213], v[68:71]
	v_mfma_f32_16x16x32_bf16 v[64:67], v[166:169], v[210:213], v[64:67]
	s_setprio 0
	s_barrier
	ds_read_b128 v[170:173], v137 offset:49152
	ds_read_b128 v[178:181], v137 offset:50176
	ds_read_b128 v[182:185], v137 offset:51200
	ds_read_b128 v[186:189], v137 offset:52224
	ds_read_b128 v[190:193], v137 offset:53248
	ds_read_b128 v[194:197], v137 offset:54272
	ds_read_b128 v[206:209], v137 offset:55296
	ds_read_b128 v[210:213], v137 offset:56320
	s_mov_b32 m0, s1
	v_lshl_add_u64 v[174:175], v[174:175], 0, s[18:19]
	global_load_lds_dwordx4 v[174:175], off
	s_mov_b32 m0, s9
	v_lshl_add_u64 v[174:175], v[198:199], 0, s[18:19]
	global_load_lds_dwordx4 v[174:175], off
	s_mov_b32 m0, s89
	v_lshl_add_u64 v[174:175], s[54:55], 0, v[128:129]
	global_load_lds_dwordx4 v[174:175], off
	s_mov_b32 m0, s8
	v_lshl_add_u64 v[174:175], s[54:55], 0, v[130:131]
	global_load_lds_dwordx4 v[174:175], off
	s_mov_b32 m0, s81
	v_lshl_add_u64 v[174:175], v[202:203], 0, s[18:19]
	global_load_lds_dwordx4 v[174:175], off
	s_mov_b32 m0, s82
	v_lshl_add_u64 v[174:175], v[214:215], 0, s[18:19]
	global_load_lds_dwordx4 v[174:175], off
	s_waitcnt vmcnt(8)
	s_waitcnt lgkmcnt(0)
	s_barrier
	s_setprio 1
	v_mfma_f32_16x16x32_bf16 v[60:63], v[138:141], v[170:173], v[60:63]
	v_mfma_f32_16x16x32_bf16 v[56:59], v[146:149], v[170:173], v[56:59]
	v_mfma_f32_16x16x32_bf16 v[52:55], v[138:141], v[182:185], v[52:55]
	v_mfma_f32_16x16x32_bf16 v[48:51], v[146:149], v[182:185], v[48:51]
	v_mfma_f32_16x16x32_bf16 v[40:43], v[138:141], v[190:193], v[40:43]
	v_mfma_f32_16x16x32_bf16 v[32:35], v[146:149], v[190:193], v[32:35]
	v_mfma_f32_16x16x32_bf16 v[24:27], v[138:141], v[206:209], v[24:27]
	v_mfma_f32_16x16x32_bf16 v[16:19], v[146:149], v[206:209], v[16:19]
	v_mfma_f32_16x16x32_bf16 v[60:63], v[142:145], v[178:181], v[60:63]
	v_mfma_f32_16x16x32_bf16 v[56:59], v[150:153], v[178:181], v[56:59]
	v_mfma_f32_16x16x32_bf16 v[52:55], v[142:145], v[186:189], v[52:55]
	v_mfma_f32_16x16x32_bf16 v[48:51], v[150:153], v[186:189], v[48:51]
	v_mfma_f32_16x16x32_bf16 v[40:43], v[142:145], v[194:197], v[40:43]
	v_mfma_f32_16x16x32_bf16 v[32:35], v[150:153], v[194:197], v[32:35]
	v_mfma_f32_16x16x32_bf16 v[24:27], v[142:145], v[210:213], v[24:27]
	v_mfma_f32_16x16x32_bf16 v[16:19], v[150:153], v[210:213], v[16:19]
	v_mfma_f32_16x16x32_bf16 v[44:47], v[154:157], v[170:173], v[44:47]
	v_mfma_f32_16x16x32_bf16 v[36:39], v[162:165], v[170:173], v[36:39]
	v_mfma_f32_16x16x32_bf16 v[28:31], v[154:157], v[182:185], v[28:31]
	v_mfma_f32_16x16x32_bf16 v[20:23], v[162:165], v[182:185], v[20:23]
	v_mfma_f32_16x16x32_bf16 v[12:15], v[154:157], v[190:193], v[12:15]
	v_mfma_f32_16x16x32_bf16 v[8:11], v[162:165], v[190:193], v[8:11]
	v_mfma_f32_16x16x32_bf16 v[4:7], v[154:157], v[206:209], v[4:7]
	v_mfma_f32_16x16x32_bf16 v[0:3], v[162:165], v[206:209], v[0:3]
	v_mfma_f32_16x16x32_bf16 v[44:47], v[158:161], v[178:181], v[44:47]
	v_mfma_f32_16x16x32_bf16 v[36:39], v[166:169], v[178:181], v[36:39]
	v_mfma_f32_16x16x32_bf16 v[28:31], v[158:161], v[186:189], v[28:31]
	v_mfma_f32_16x16x32_bf16 v[20:23], v[166:169], v[186:189], v[20:23]
	v_mfma_f32_16x16x32_bf16 v[12:15], v[158:161], v[194:197], v[12:15]
	v_mfma_f32_16x16x32_bf16 v[8:11], v[166:169], v[194:197], v[8:11]
	v_mfma_f32_16x16x32_bf16 v[4:7], v[158:161], v[210:213], v[4:7]
	v_mfma_f32_16x16x32_bf16 v[0:3], v[166:169], v[210:213], v[0:3]
	s_setprio 0
	s_barrier
	s_mov_b64 s[58:59], 0
	s_mov_b64 s[54:55], -1
	s_mov_b64 s[56:57], 0x100
	s_cbranch_vccz .LBB0_904
	s_and_b64 vcc, exec, s[20:21]
	s_cbranch_vccz .LBB0_907
	s_barrier

.LBB0_953:
	ds_read_b128 v[148:151], v145
	ds_read_b128 v[152:155], v145 offset:1024
	ds_read_b128 v[156:159], v145 offset:2048
	ds_read_b128 v[160:163], v145 offset:3072
	ds_read_b128 v[164:167], v146
	ds_read_b128 v[168:171], v146 offset:1024
	ds_read_b128 v[172:175], v146 offset:2048
	ds_read_b128 v[178:181], v146 offset:3072
	ds_read_b128 v[182:185], v147
	ds_read_b128 v[186:189], v147 offset:1024
	ds_read_b128 v[190:193], v147 offset:2048
	ds_read_b128 v[194:197], v147 offset:3072
	ds_read_b128 v[206:209], v147 offset:4096
	ds_read_b128 v[210:213], v147 offset:5120
	ds_read_b128 v[214:217], v147 offset:6144
	ds_read_b128 v[218:221], v147 offset:7168
	s_add_u32 s56, s54, 0x100
	s_addc_u32 s57, s55, 0
	s_cmp_eq_u32 vcc_hi, 20
	s_cselect_b32 s61, s93, s57
	s_cselect_b32 s60, s94, s56
	s_cselect_b32 s59, s95, vcc_lo
	s_cselect_b32 s58, s96, s97
	s_add_i32 m0, s67, 0xc000
	v_lshl_add_u64 v[140:141], s[54:55], 0, v[136:137]
	global_load_lds_dwordx4 v[140:141], off
	s_add_i32 m0, s67, 0xe000
	v_lshl_add_u64 v[140:141], s[54:55], 0, v[138:139]
	global_load_lds_dwordx4 v[140:141], off
	s_waitcnt vmcnt(8)
	s_waitcnt lgkmcnt(0)
	s_barrier
	s_setprio 1
	v_mfma_f32_16x16x32_bf16 v[124:127], v[148:151], v[182:185], v[124:127]
	v_mfma_f32_16x16x32_bf16 v[120:123], v[156:159], v[182:185], v[120:123]
	v_mfma_f32_16x16x32_bf16 v[116:119], v[148:151], v[190:193], v[116:119]
	v_mfma_f32_16x16x32_bf16 v[108:111], v[156:159], v[190:193], v[108:111]
	v_mfma_f32_16x16x32_bf16 v[100:103], v[148:151], v[206:209], v[100:103]
	v_mfma_f32_16x16x32_bf16 v[92:95], v[156:159], v[206:209], v[92:95]
	v_mfma_f32_16x16x32_bf16 v[84:87], v[148:151], v[214:217], v[84:87]
	v_mfma_f32_16x16x32_bf16 v[76:79], v[156:159], v[214:217], v[76:79]
	v_mfma_f32_16x16x32_bf16 v[124:127], v[152:155], v[186:189], v[124:127]
	v_mfma_f32_16x16x32_bf16 v[120:123], v[160:163], v[186:189], v[120:123]
	v_mfma_f32_16x16x32_bf16 v[116:119], v[152:155], v[194:197], v[116:119]
	v_mfma_f32_16x16x32_bf16 v[108:111], v[160:163], v[194:197], v[108:111]
	v_mfma_f32_16x16x32_bf16 v[100:103], v[152:155], v[210:213], v[100:103]
	v_mfma_f32_16x16x32_bf16 v[92:95], v[160:163], v[210:213], v[92:95]
	v_mfma_f32_16x16x32_bf16 v[84:87], v[152:155], v[218:221], v[84:87]
	v_mfma_f32_16x16x32_bf16 v[76:79], v[160:163], v[218:221], v[76:79]
	v_mfma_f32_16x16x32_bf16 v[112:115], v[164:167], v[182:185], v[112:115]
	v_mfma_f32_16x16x32_bf16 v[104:107], v[172:175], v[182:185], v[104:107]
	v_mfma_f32_16x16x32_bf16 v[96:99], v[164:167], v[190:193], v[96:99]
	v_mfma_f32_16x16x32_bf16 v[88:91], v[172:175], v[190:193], v[88:91]
	v_mfma_f32_16x16x32_bf16 v[80:83], v[164:167], v[206:209], v[80:83]
	v_mfma_f32_16x16x32_bf16 v[72:75], v[172:175], v[206:209], v[72:75]
	v_mfma_f32_16x16x32_bf16 v[68:71], v[164:167], v[214:217], v[68:71]
	v_mfma_f32_16x16x32_bf16 v[64:67], v[172:175], v[214:217], v[64:67]
	v_mfma_f32_16x16x32_bf16 v[112:115], v[168:171], v[186:189], v[112:115]
	v_mfma_f32_16x16x32_bf16 v[104:107], v[178:181], v[186:189], v[104:107]
	v_mfma_f32_16x16x32_bf16 v[96:99], v[168:171], v[194:197], v[96:99]
	v_mfma_f32_16x16x32_bf16 v[88:91], v[178:181], v[194:197], v[88:91]
	v_mfma_f32_16x16x32_bf16 v[80:83], v[168:171], v[210:213], v[80:83]
	v_mfma_f32_16x16x32_bf16 v[72:75], v[178:181], v[210:213], v[72:75]
	v_mfma_f32_16x16x32_bf16 v[68:71], v[168:171], v[218:221], v[68:71]
	v_mfma_f32_16x16x32_bf16 v[64:67], v[178:181], v[218:221], v[64:67]
	s_setprio 0
	s_barrier
	ds_read_b128 v[182:185], v147 offset:16384
	ds_read_b128 v[186:189], v147 offset:17408
	ds_read_b128 v[190:193], v147 offset:18432
	ds_read_b128 v[194:197], v147 offset:19456
	ds_read_b128 v[206:209], v147 offset:20480
	ds_read_b128 v[210:213], v147 offset:21504
	ds_read_b128 v[214:217], v147 offset:22528
	ds_read_b128 v[218:221], v147 offset:23552
	s_add_i32 s0, s79, s66
	s_mov_b32 m0, s0
	v_lshl_add_u64 v[140:141], s[58:59], 0, v[130:131]
	global_load_lds_dwordx4 v[140:141], off
	s_add_i32 m0, s0, 0x2000
	s_add_u32 s0, s58, 0x60000
	v_lshl_add_u64 v[198:199], s[58:59], 0, v[134:135]
	s_addc_u32 s1, s59, 0
	s_add_i32 s2, s80, s66
	global_load_lds_dwordx4 v[198:199], off
	v_lshl_add_u64 v[202:203], s[0:1], 0, v[130:131]
	s_mov_b32 m0, s2
	v_lshl_add_u64 v[222:223], s[60:61], 0, v[132:133]
	global_load_lds_dwordx4 v[202:203], off
	s_add_i32 m0, s2, 0x2000
	v_lshl_add_u64 v[202:203], s[0:1], 0, v[134:135]
	global_load_lds_dwordx4 v[202:203], off
	s_mov_b32 m0, s67
	v_lshl_add_u64 v[202:203], s[60:61], 0, v[128:129]
	global_load_lds_dwordx4 v[202:203], off
	s_mov_b32 m0, s68
	s_nop 0
	global_load_lds_dwordx4 v[222:223], off
	s_waitcnt vmcnt(8)
	s_waitcnt lgkmcnt(0)
	s_barrier
	s_setprio 1
	v_mfma_f32_16x16x32_bf16 v[60:63], v[148:151], v[182:185], v[60:63]
	v_mfma_f32_16x16x32_bf16 v[56:59], v[156:159], v[182:185], v[56:59]
	v_mfma_f32_16x16x32_bf16 v[52:55], v[148:151], v[190:193], v[52:55]
	v_mfma_f32_16x16x32_bf16 v[44:47], v[156:159], v[190:193], v[44:47]
	v_mfma_f32_16x16x32_bf16 v[36:39], v[148:151], v[206:209], v[36:39]
	v_mfma_f32_16x16x32_bf16 v[28:31], v[156:159], v[206:209], v[28:31]
	v_mfma_f32_16x16x32_bf16 v[20:23], v[148:151], v[214:217], v[20:23]
	v_mfma_f32_16x16x32_bf16 v[12:15], v[156:159], v[214:217], v[12:15]
	v_mfma_f32_16x16x32_bf16 v[60:63], v[152:155], v[186:189], v[60:63]
	v_mfma_f32_16x16x32_bf16 v[56:59], v[160:163], v[186:189], v[56:59]
	v_mfma_f32_16x16x32_bf16 v[52:55], v[152:155], v[194:197], v[52:55]
	v_mfma_f32_16x16x32_bf16 v[44:47], v[160:163], v[194:197], v[44:47]
	v_mfma_f32_16x16x32_bf16 v[36:39], v[152:155], v[210:213], v[36:39]
	v_mfma_f32_16x16x32_bf16 v[28:31], v[160:163], v[210:213], v[28:31]
	v_mfma_f32_16x16x32_bf16 v[20:23], v[152:155], v[218:221], v[20:23]
	v_mfma_f32_16x16x32_bf16 v[12:15], v[160:163], v[218:221], v[12:15]
	v_mfma_f32_16x16x32_bf16 v[48:51], v[164:167], v[182:185], v[48:51]
	v_mfma_f32_16x16x32_bf16 v[40:43], v[172:175], v[182:185], v[40:43]
	v_mfma_f32_16x16x32_bf16 v[32:35], v[164:167], v[190:193], v[32:35]
	v_mfma_f32_16x16x32_bf16 v[24:27], v[172:175], v[190:193], v[24:27]
	v_mfma_f32_16x16x32_bf16 v[16:19], v[164:167], v[206:209], v[16:19]
	v_mfma_f32_16x16x32_bf16 v[8:11], v[172:175], v[206:209], v[8:11]
	v_mfma_f32_16x16x32_bf16 v[4:7], v[164:167], v[214:217], v[4:7]
	v_mfma_f32_16x16x32_bf16 v[0:3], v[172:175], v[214:217], v[0:3]
	v_mfma_f32_16x16x32_bf16 v[48:51], v[168:171], v[186:189], v[48:51]
	v_mfma_f32_16x16x32_bf16 v[40:43], v[178:181], v[186:189], v[40:43]
	v_mfma_f32_16x16x32_bf16 v[32:35], v[168:171], v[194:197], v[32:35]
	v_mfma_f32_16x16x32_bf16 v[24:27], v[178:181], v[194:197], v[24:27]
	v_mfma_f32_16x16x32_bf16 v[16:19], v[168:171], v[210:213], v[16:19]
	v_mfma_f32_16x16x32_bf16 v[8:11], v[178:181], v[210:213], v[8:11]
	v_mfma_f32_16x16x32_bf16 v[4:7], v[168:171], v[218:221], v[4:7]
	v_mfma_f32_16x16x32_bf16 v[0:3], v[178:181], v[218:221], v[0:3]
	s_setprio 0
	s_barrier
	ds_read_b128 v[182:185], v147 offset:32768
	ds_read_b128 v[186:189], v147 offset:33792
	ds_read_b128 v[190:193], v147 offset:34816
	ds_read_b128 v[194:197], v147 offset:35840
	ds_read_b128 v[206:209], v147 offset:36864
	ds_read_b128 v[210:213], v147 offset:37888
	ds_read_b128 v[214:217], v147 offset:38912
	ds_read_b128 v[218:221], v147 offset:39936
	s_add_i32 s2, 0, 0x18000
	s_add_i32 s3, 0, 0x1c000
	v_add_u32_e32 v160, s2, v144
	v_add_u32_e32 v177, s3, v144
	ds_read_b128 v[148:151], v160
	ds_read_b128 v[152:155], v160 offset:1024
	ds_read_b128 v[156:159], v160 offset:2048
	ds_read_b128 v[160:163], v160 offset:3072
	ds_read_b128 v[164:167], v177
	ds_read_b128 v[168:171], v177 offset:1024
	ds_read_b128 v[172:175], v177 offset:2048
	ds_read_b128 v[178:181], v177 offset:3072
	s_add_u32 s0, s60, 0x60000
	s_addc_u32 s1, s61, 0
	s_mov_b32 m0, s69
	v_lshl_add_u64 v[224:225], s[0:1], 0, v[128:129]
	global_load_lds_dwordx4 v[224:225], off
	s_mov_b32 m0, s70
	v_lshl_add_u64 v[224:225], s[0:1], 0, v[132:133]
	global_load_lds_dwordx4 v[224:225], off
	s_waitcnt vmcnt(8)
	s_waitcnt lgkmcnt(0)
	s_barrier
	s_setprio 1
	v_mfma_f32_16x16x32_bf16 v[124:127], v[148:151], v[182:185], v[124:127]
	v_mfma_f32_16x16x32_bf16 v[120:123], v[156:159], v[182:185], v[120:123]
	v_mfma_f32_16x16x32_bf16 v[116:119], v[148:151], v[190:193], v[116:119]
	v_mfma_f32_16x16x32_bf16 v[108:111], v[156:159], v[190:193], v[108:111]
	v_mfma_f32_16x16x32_bf16 v[100:103], v[148:151], v[206:209], v[100:103]
	v_mfma_f32_16x16x32_bf16 v[92:95], v[156:159], v[206:209], v[92:95]
	v_mfma_f32_16x16x32_bf16 v[84:87], v[148:151], v[214:217], v[84:87]
	v_mfma_f32_16x16x32_bf16 v[76:79], v[156:159], v[214:217], v[76:79]
	v_mfma_f32_16x16x32_bf16 v[124:127], v[152:155], v[186:189], v[124:127]
	v_mfma_f32_16x16x32_bf16 v[120:123], v[160:163], v[186:189], v[120:123]
	v_mfma_f32_16x16x32_bf16 v[116:119], v[152:155], v[194:197], v[116:119]
	v_mfma_f32_16x16x32_bf16 v[108:111], v[160:163], v[194:197], v[108:111]
	v_mfma_f32_16x16x32_bf16 v[100:103], v[152:155], v[210:213], v[100:103]
	v_mfma_f32_16x16x32_bf16 v[92:95], v[160:163], v[210:213], v[92:95]
	v_mfma_f32_16x16x32_bf16 v[84:87], v[152:155], v[218:221], v[84:87]
	v_mfma_f32_16x16x32_bf16 v[76:79], v[160:163], v[218:221], v[76:79]
	v_mfma_f32_16x16x32_bf16 v[112:115], v[164:167], v[182:185], v[112:115]
	v_mfma_f32_16x16x32_bf16 v[104:107], v[172:175], v[182:185], v[104:107]
	v_mfma_f32_16x16x32_bf16 v[96:99], v[164:167], v[190:193], v[96:99]
	v_mfma_f32_16x16x32_bf16 v[88:91], v[172:175], v[190:193], v[88:91]
	v_mfma_f32_16x16x32_bf16 v[80:83], v[164:167], v[206:209], v[80:83]
	v_mfma_f32_16x16x32_bf16 v[72:75], v[172:175], v[206:209], v[72:75]
	v_mfma_f32_16x16x32_bf16 v[68:71], v[164:167], v[214:217], v[68:71]
	v_mfma_f32_16x16x32_bf16 v[64:67], v[172:175], v[214:217], v[64:67]
	v_mfma_f32_16x16x32_bf16 v[112:115], v[168:171], v[186:189], v[112:115]
	v_mfma_f32_16x16x32_bf16 v[104:107], v[178:181], v[186:189], v[104:107]
	v_mfma_f32_16x16x32_bf16 v[96:99], v[168:171], v[194:197], v[96:99]
	v_mfma_f32_16x16x32_bf16 v[88:91], v[178:181], v[194:197], v[88:91]
	v_mfma_f32_16x16x32_bf16 v[80:83], v[168:171], v[210:213], v[80:83]
	v_mfma_f32_16x16x32_bf16 v[72:75], v[178:181], v[210:213], v[72:75]
	v_mfma_f32_16x16x32_bf16 v[68:71], v[168:171], v[218:221], v[68:71]
	v_mfma_f32_16x16x32_bf16 v[64:67], v[178:181], v[218:221], v[64:67]
	s_setprio 0
	s_barrier
	ds_read_b128 v[182:185], v147 offset:49152
	ds_read_b128 v[186:189], v147 offset:50176
	ds_read_b128 v[190:193], v147 offset:51200
	ds_read_b128 v[194:197], v147 offset:52224
	ds_read_b128 v[206:209], v147 offset:53248
	ds_read_b128 v[210:213], v147 offset:54272
	ds_read_b128 v[214:217], v147 offset:55296
	ds_read_b128 v[218:221], v147 offset:56320
	s_add_i32 s0, s2, s66
	s_mov_b32 m0, s0
	v_lshl_add_u64 v[140:141], v[140:141], 0, s[12:13]
	global_load_lds_dwordx4 v[140:141], off
	s_add_i32 m0, s0, 0x2000
	s_add_u32 s0, s58, 0x60080
	v_lshl_add_u64 v[140:141], v[198:199], 0, s[12:13]
	s_addc_u32 s1, s59, 0
	s_add_i32 s2, s3, s66
	global_load_lds_dwordx4 v[140:141], off
	s_mov_b32 m0, s2
	v_lshl_add_u64 v[140:141], s[0:1], 0, v[130:131]
	global_load_lds_dwordx4 v[140:141], off
	s_add_i32 m0, s2, 0x2000
	v_lshl_add_u64 v[140:141], s[0:1], 0, v[134:135]
	global_load_lds_dwordx4 v[140:141], off
	s_mov_b32 m0, s77
	v_lshl_add_u64 v[140:141], v[202:203], 0, s[12:13]
	global_load_lds_dwordx4 v[140:141], off
	s_mov_b32 m0, s78
	v_lshl_add_u64 v[140:141], v[222:223], 0, s[12:13]
	global_load_lds_dwordx4 v[140:141], off
	s_waitcnt vmcnt(8)
	s_waitcnt lgkmcnt(0)
	s_barrier
	s_setprio 1
	v_mfma_f32_16x16x32_bf16 v[60:63], v[148:151], v[182:185], v[60:63]
	v_mfma_f32_16x16x32_bf16 v[56:59], v[156:159], v[182:185], v[56:59]
	v_mfma_f32_16x16x32_bf16 v[52:55], v[148:151], v[190:193], v[52:55]
	v_mfma_f32_16x16x32_bf16 v[44:47], v[156:159], v[190:193], v[44:47]
	v_mfma_f32_16x16x32_bf16 v[36:39], v[148:151], v[206:209], v[36:39]
	v_mfma_f32_16x16x32_bf16 v[28:31], v[156:159], v[206:209], v[28:31]
	v_mfma_f32_16x16x32_bf16 v[20:23], v[148:151], v[214:217], v[20:23]
	v_mfma_f32_16x16x32_bf16 v[12:15], v[156:159], v[214:217], v[12:15]
	v_mfma_f32_16x16x32_bf16 v[60:63], v[152:155], v[186:189], v[60:63]
	v_mfma_f32_16x16x32_bf16 v[56:59], v[160:163], v[186:189], v[56:59]
	v_mfma_f32_16x16x32_bf16 v[52:55], v[152:155], v[194:197], v[52:55]
	v_mfma_f32_16x16x32_bf16 v[44:47], v[160:163], v[194:197], v[44:47]
	v_mfma_f32_16x16x32_bf16 v[36:39], v[152:155], v[210:213], v[36:39]
	v_mfma_f32_16x16x32_bf16 v[28:31], v[160:163], v[210:213], v[28:31]
	v_mfma_f32_16x16x32_bf16 v[20:23], v[152:155], v[218:221], v[20:23]
	v_mfma_f32_16x16x32_bf16 v[12:15], v[160:163], v[218:221], v[12:15]
	v_mfma_f32_16x16x32_bf16 v[48:51], v[164:167], v[182:185], v[48:51]
	v_mfma_f32_16x16x32_bf16 v[40:43], v[172:175], v[182:185], v[40:43]
	v_mfma_f32_16x16x32_bf16 v[32:35], v[164:167], v[190:193], v[32:35]
	v_mfma_f32_16x16x32_bf16 v[24:27], v[172:175], v[190:193], v[24:27]
	v_mfma_f32_16x16x32_bf16 v[16:19], v[164:167], v[206:209], v[16:19]
	v_mfma_f32_16x16x32_bf16 v[8:11], v[172:175], v[206:209], v[8:11]
	v_mfma_f32_16x16x32_bf16 v[4:7], v[164:167], v[214:217], v[4:7]
	v_mfma_f32_16x16x32_bf16 v[0:3], v[172:175], v[214:217], v[0:3]
	v_mfma_f32_16x16x32_bf16 v[48:51], v[168:171], v[186:189], v[48:51]
	v_mfma_f32_16x16x32_bf16 v[40:43], v[178:181], v[186:189], v[40:43]
	v_mfma_f32_16x16x32_bf16 v[32:35], v[168:171], v[194:197], v[32:35]
	v_mfma_f32_16x16x32_bf16 v[24:27], v[178:181], v[194:197], v[24:27]
	v_mfma_f32_16x16x32_bf16 v[16:19], v[168:171], v[210:213], v[16:19]
	v_mfma_f32_16x16x32_bf16 v[8:11], v[178:181], v[210:213], v[8:11]
	v_mfma_f32_16x16x32_bf16 v[4:7], v[168:171], v[218:221], v[4:7]
	v_mfma_f32_16x16x32_bf16 v[0:3], v[178:181], v[218:221], v[0:3]
	s_setprio 0
	s_barrier
	s_add_i32 vcc_hi, vcc_hi, 2
	s_add_u32 s97, s97, 0x100
	s_addc_u32 vcc_lo, vcc_lo, 0
	s_cmp_gt_u32 vcc_hi, 21
	s_mov_b64 s[54:55], s[56:57]
	s_cbranch_scc0 .LBB0_953
	s_and_b64 vcc, exec, s[14:15]
	s_cbranch_vccz .LBB0_956
	s_barrier

.LBB0_979:
	ds_read_b128 v[144:147], v141
	ds_read_b128 v[148:151], v141 offset:1024
	ds_read_b128 v[152:155], v141 offset:2048
	ds_read_b128 v[156:159], v141 offset:3072
	ds_read_b128 v[160:163], v142
	ds_read_b128 v[164:167], v142 offset:1024
	ds_read_b128 v[168:171], v142 offset:2048
	ds_read_b128 v[172:175], v142 offset:3072
	ds_read_b128 v[178:181], v143
	ds_read_b128 v[182:185], v143 offset:1024
	ds_read_b128 v[186:189], v143 offset:2048
	ds_read_b128 v[190:193], v143 offset:3072
	ds_read_b128 v[194:197], v143 offset:4096
	ds_read_b128 v[206:209], v143 offset:5120
	ds_read_b128 v[210:213], v143 offset:6144
	ds_read_b128 v[214:217], v143 offset:7168
	s_add_u32 s2, s46, s58
	s_addc_u32 s3, s47, 0
	s_add_u32 s38, s2, 0x100
	s_addc_u32 s39, s3, 0
	s_and_b64 s[0:1], s[52:53], exec
	s_cselect_b32 s57, s23, s39
	s_cselect_b32 s56, s85, s38
	s_add_u32 s0, s34, s58
	s_addc_u32 s1, s35, 0
	s_add_u32 s38, s0, 0x100
	s_addc_u32 s39, s1, 0
	s_and_b64 s[0:1], s[52:53], exec
	s_cselect_b32 s59, s86, s39
	s_cselect_b32 s58, s87, s38
	s_add_u32 s62, s2, 0x10080
	s_addc_u32 s63, s3, 0
	s_add_i32 s38, s78, s66
	s_add_i32 m0, s25, 0xc000
	s_add_i32 s39, s25, 0xe000
	s_add_i32 s0, s38, 0x2000
	s_add_u32 s60, s58, 0x10000
	s_addc_u32 s61, s59, 0
	s_add_i32 s91, s79, s66
	s_add_i32 s76, s91, 0x2000
	s_add_i32 s3, 0, 0x18000
	s_add_i32 s2, 0, 0x1c000
	v_cndmask_b32_e64 v136, 0, 1, s[54:55]
	s_add_u32 s54, s56, 0x10000
	s_addc_u32 s55, s57, 0
	s_add_i32 s1, s3, s66
	s_add_i32 s89, s1, 0x2000
	s_add_u32 s52, s58, 0x10080
	s_addc_u32 s53, s59, 0
	s_add_i32 s90, s2, s66
	s_add_i32 s88, s90, 0x2000
	v_cmp_ne_u32_e32 vcc, 1, v136
	v_lshl_add_u64 v[136:137], s[62:63], 0, v[128:129]
	global_load_lds_dwordx4 v[136:137], off
	s_mov_b32 m0, s39
	v_lshl_add_u64 v[136:137], s[62:63], 0, v[132:133]
	global_load_lds_dwordx4 v[136:137], off
	s_waitcnt vmcnt(8)
	s_waitcnt lgkmcnt(0)
	s_barrier
	s_setprio 1
	v_mfma_f32_16x16x32_bf16 v[124:127], v[144:147], v[178:181], v[124:127]
	v_mfma_f32_16x16x32_bf16 v[120:123], v[152:155], v[178:181], v[120:123]
	v_mfma_f32_16x16x32_bf16 v[116:119], v[144:147], v[186:189], v[116:119]
	v_mfma_f32_16x16x32_bf16 v[108:111], v[152:155], v[186:189], v[108:111]
	v_mfma_f32_16x16x32_bf16 v[100:103], v[144:147], v[194:197], v[100:103]
	v_mfma_f32_16x16x32_bf16 v[92:95], v[152:155], v[194:197], v[92:95]
	v_mfma_f32_16x16x32_bf16 v[84:87], v[144:147], v[210:213], v[84:87]
	v_mfma_f32_16x16x32_bf16 v[76:79], v[152:155], v[210:213], v[76:79]
	v_mfma_f32_16x16x32_bf16 v[124:127], v[148:151], v[182:185], v[124:127]
	v_mfma_f32_16x16x32_bf16 v[120:123], v[156:159], v[182:185], v[120:123]
	v_mfma_f32_16x16x32_bf16 v[116:119], v[148:151], v[190:193], v[116:119]
	v_mfma_f32_16x16x32_bf16 v[108:111], v[156:159], v[190:193], v[108:111]
	v_mfma_f32_16x16x32_bf16 v[100:103], v[148:151], v[206:209], v[100:103]
	v_mfma_f32_16x16x32_bf16 v[92:95], v[156:159], v[206:209], v[92:95]
	v_mfma_f32_16x16x32_bf16 v[84:87], v[148:151], v[214:217], v[84:87]
	v_mfma_f32_16x16x32_bf16 v[76:79], v[156:159], v[214:217], v[76:79]
	v_mfma_f32_16x16x32_bf16 v[112:115], v[160:163], v[178:181], v[112:115]
	v_mfma_f32_16x16x32_bf16 v[104:107], v[168:171], v[178:181], v[104:107]
	v_mfma_f32_16x16x32_bf16 v[96:99], v[160:163], v[186:189], v[96:99]
	v_mfma_f32_16x16x32_bf16 v[88:91], v[168:171], v[186:189], v[88:91]
	v_mfma_f32_16x16x32_bf16 v[80:83], v[160:163], v[194:197], v[80:83]
	v_mfma_f32_16x16x32_bf16 v[72:75], v[168:171], v[194:197], v[72:75]
	v_mfma_f32_16x16x32_bf16 v[68:71], v[160:163], v[210:213], v[68:71]
	v_mfma_f32_16x16x32_bf16 v[64:67], v[168:171], v[210:213], v[64:67]
	v_mfma_f32_16x16x32_bf16 v[112:115], v[164:167], v[182:185], v[112:115]
	v_mfma_f32_16x16x32_bf16 v[104:107], v[172:175], v[182:185], v[104:107]
	v_mfma_f32_16x16x32_bf16 v[96:99], v[164:167], v[190:193], v[96:99]
	v_mfma_f32_16x16x32_bf16 v[88:91], v[172:175], v[190:193], v[88:91]
	v_mfma_f32_16x16x32_bf16 v[80:83], v[164:167], v[206:209], v[80:83]
	v_mfma_f32_16x16x32_bf16 v[72:75], v[172:175], v[206:209], v[72:75]
	v_mfma_f32_16x16x32_bf16 v[68:71], v[164:167], v[214:217], v[68:71]
	v_mfma_f32_16x16x32_bf16 v[64:67], v[172:175], v[214:217], v[64:67]
	s_setprio 0
	s_barrier
	ds_read_b128 v[178:181], v143 offset:16384
	ds_read_b128 v[182:185], v143 offset:17408
	ds_read_b128 v[186:189], v143 offset:18432
	ds_read_b128 v[190:193], v143 offset:19456
	ds_read_b128 v[194:197], v143 offset:20480
	ds_read_b128 v[206:209], v143 offset:21504
	ds_read_b128 v[210:213], v143 offset:22528
	ds_read_b128 v[214:217], v143 offset:23552
	s_mov_b32 m0, s38
	v_lshl_add_u64 v[136:137], s[58:59], 0, v[130:131]
	global_load_lds_dwordx4 v[136:137], off
	v_lshl_add_u64 v[198:199], s[58:59], 0, v[134:135]
	s_mov_b32 m0, s0
	v_lshl_add_u64 v[202:203], s[60:61], 0, v[130:131]
	global_load_lds_dwordx4 v[198:199], off
	s_mov_b32 m0, s91
	v_lshl_add_u64 v[218:219], s[56:57], 0, v[132:133]
	global_load_lds_dwordx4 v[202:203], off
	s_mov_b32 m0, s76
	v_lshl_add_u64 v[202:203], s[60:61], 0, v[134:135]
	global_load_lds_dwordx4 v[202:203], off
	s_mov_b32 m0, s25
	v_lshl_add_u64 v[202:203], s[56:57], 0, v[128:129]
	global_load_lds_dwordx4 v[202:203], off
	s_mov_b32 m0, s69
	s_nop 0
	global_load_lds_dwordx4 v[218:219], off
	s_waitcnt vmcnt(8)
	s_waitcnt lgkmcnt(0)
	s_barrier
	s_setprio 1
	v_mfma_f32_16x16x32_bf16 v[60:63], v[144:147], v[178:181], v[60:63]
	v_mfma_f32_16x16x32_bf16 v[56:59], v[152:155], v[178:181], v[56:59]
	v_mfma_f32_16x16x32_bf16 v[52:55], v[144:147], v[186:189], v[52:55]
	v_mfma_f32_16x16x32_bf16 v[44:47], v[152:155], v[186:189], v[44:47]
	v_mfma_f32_16x16x32_bf16 v[36:39], v[144:147], v[194:197], v[36:39]
	v_mfma_f32_16x16x32_bf16 v[28:31], v[152:155], v[194:197], v[28:31]
	v_mfma_f32_16x16x32_bf16 v[20:23], v[144:147], v[210:213], v[20:23]
	v_mfma_f32_16x16x32_bf16 v[12:15], v[152:155], v[210:213], v[12:15]
	v_mfma_f32_16x16x32_bf16 v[60:63], v[148:151], v[182:185], v[60:63]
	v_mfma_f32_16x16x32_bf16 v[56:59], v[156:159], v[182:185], v[56:59]
	v_mfma_f32_16x16x32_bf16 v[52:55], v[148:151], v[190:193], v[52:55]
	v_mfma_f32_16x16x32_bf16 v[44:47], v[156:159], v[190:193], v[44:47]
	v_mfma_f32_16x16x32_bf16 v[36:39], v[148:151], v[206:209], v[36:39]
	v_mfma_f32_16x16x32_bf16 v[28:31], v[156:159], v[206:209], v[28:31]
	v_mfma_f32_16x16x32_bf16 v[20:23], v[148:151], v[214:217], v[20:23]
	v_mfma_f32_16x16x32_bf16 v[12:15], v[156:159], v[214:217], v[12:15]
	v_mfma_f32_16x16x32_bf16 v[48:51], v[160:163], v[178:181], v[48:51]
	v_mfma_f32_16x16x32_bf16 v[40:43], v[168:171], v[178:181], v[40:43]
	v_mfma_f32_16x16x32_bf16 v[32:35], v[160:163], v[186:189], v[32:35]
	v_mfma_f32_16x16x32_bf16 v[24:27], v[168:171], v[186:189], v[24:27]
	v_mfma_f32_16x16x32_bf16 v[16:19], v[160:163], v[194:197], v[16:19]
	v_mfma_f32_16x16x32_bf16 v[8:11], v[168:171], v[194:197], v[8:11]
	v_mfma_f32_16x16x32_bf16 v[4:7], v[160:163], v[210:213], v[4:7]
	v_mfma_f32_16x16x32_bf16 v[0:3], v[168:171], v[210:213], v[0:3]
	v_mfma_f32_16x16x32_bf16 v[48:51], v[164:167], v[182:185], v[48:51]
	v_mfma_f32_16x16x32_bf16 v[40:43], v[172:175], v[182:185], v[40:43]
	v_mfma_f32_16x16x32_bf16 v[32:35], v[164:167], v[190:193], v[32:35]
	v_mfma_f32_16x16x32_bf16 v[24:27], v[172:175], v[190:193], v[24:27]
	v_mfma_f32_16x16x32_bf16 v[16:19], v[164:167], v[206:209], v[16:19]
	v_mfma_f32_16x16x32_bf16 v[8:11], v[172:175], v[206:209], v[8:11]
	v_mfma_f32_16x16x32_bf16 v[4:7], v[164:167], v[214:217], v[4:7]
	v_mfma_f32_16x16x32_bf16 v[0:3], v[172:175], v[214:217], v[0:3]
	s_setprio 0
	s_barrier
	ds_read_b128 v[178:181], v143 offset:32768
	ds_read_b128 v[182:185], v143 offset:33792
	ds_read_b128 v[186:189], v143 offset:34816
	ds_read_b128 v[190:193], v143 offset:35840
	ds_read_b128 v[194:197], v143 offset:36864
	ds_read_b128 v[206:209], v143 offset:37888
	ds_read_b128 v[210:213], v143 offset:38912
	ds_read_b128 v[214:217], v143 offset:39936
	v_add_u32_e32 v156, s3, v140
	v_add_u32_e32 v172, s2, v140
	ds_read_b128 v[144:147], v156
	ds_read_b128 v[148:151], v156 offset:1024
	ds_read_b128 v[152:155], v156 offset:2048
	ds_read_b128 v[156:159], v156 offset:3072
	ds_read_b128 v[160:163], v172
	ds_read_b128 v[164:167], v172 offset:1024
	ds_read_b128 v[168:171], v172 offset:2048
	ds_read_b128 v[172:175], v172 offset:3072
	s_mov_b32 m0, s70
	v_lshl_add_u64 v[220:221], s[54:55], 0, v[128:129]
	global_load_lds_dwordx4 v[220:221], off
	s_mov_b32 m0, s71
	v_lshl_add_u64 v[220:221], s[54:55], 0, v[132:133]
	global_load_lds_dwordx4 v[220:221], off
	s_waitcnt vmcnt(8)
	s_waitcnt lgkmcnt(0)
	s_barrier
	s_setprio 1
	v_mfma_f32_16x16x32_bf16 v[124:127], v[144:147], v[178:181], v[124:127]
	v_mfma_f32_16x16x32_bf16 v[120:123], v[152:155], v[178:181], v[120:123]
	v_mfma_f32_16x16x32_bf16 v[116:119], v[144:147], v[186:189], v[116:119]
	v_mfma_f32_16x16x32_bf16 v[108:111], v[152:155], v[186:189], v[108:111]
	v_mfma_f32_16x16x32_bf16 v[100:103], v[144:147], v[194:197], v[100:103]
	v_mfma_f32_16x16x32_bf16 v[92:95], v[152:155], v[194:197], v[92:95]
	v_mfma_f32_16x16x32_bf16 v[84:87], v[144:147], v[210:213], v[84:87]
	v_mfma_f32_16x16x32_bf16 v[76:79], v[152:155], v[210:213], v[76:79]
	v_mfma_f32_16x16x32_bf16 v[124:127], v[148:151], v[182:185], v[124:127]
	v_mfma_f32_16x16x32_bf16 v[120:123], v[156:159], v[182:185], v[120:123]
	v_mfma_f32_16x16x32_bf16 v[116:119], v[148:151], v[190:193], v[116:119]
	v_mfma_f32_16x16x32_bf16 v[108:111], v[156:159], v[190:193], v[108:111]
	v_mfma_f32_16x16x32_bf16 v[100:103], v[148:151], v[206:209], v[100:103]
	v_mfma_f32_16x16x32_bf16 v[92:95], v[156:159], v[206:209], v[92:95]
	v_mfma_f32_16x16x32_bf16 v[84:87], v[148:151], v[214:217], v[84:87]
	v_mfma_f32_16x16x32_bf16 v[76:79], v[156:159], v[214:217], v[76:79]
	v_mfma_f32_16x16x32_bf16 v[112:115], v[160:163], v[178:181], v[112:115]
	v_mfma_f32_16x16x32_bf16 v[104:107], v[168:171], v[178:181], v[104:107]
	v_mfma_f32_16x16x32_bf16 v[96:99], v[160:163], v[186:189], v[96:99]
	v_mfma_f32_16x16x32_bf16 v[88:91], v[168:171], v[186:189], v[88:91]
	v_mfma_f32_16x16x32_bf16 v[80:83], v[160:163], v[194:197], v[80:83]
	v_mfma_f32_16x16x32_bf16 v[72:75], v[168:171], v[194:197], v[72:75]
	v_mfma_f32_16x16x32_bf16 v[68:71], v[160:163], v[210:213], v[68:71]
	v_mfma_f32_16x16x32_bf16 v[64:67], v[168:171], v[210:213], v[64:67]
	v_mfma_f32_16x16x32_bf16 v[112:115], v[164:167], v[182:185], v[112:115]
	v_mfma_f32_16x16x32_bf16 v[104:107], v[172:175], v[182:185], v[104:107]
	v_mfma_f32_16x16x32_bf16 v[96:99], v[164:167], v[190:193], v[96:99]
	v_mfma_f32_16x16x32_bf16 v[88:91], v[172:175], v[190:193], v[88:91]
	v_mfma_f32_16x16x32_bf16 v[80:83], v[164:167], v[206:209], v[80:83]
	v_mfma_f32_16x16x32_bf16 v[72:75], v[172:175], v[206:209], v[72:75]
	v_mfma_f32_16x16x32_bf16 v[68:71], v[164:167], v[214:217], v[68:71]
	v_mfma_f32_16x16x32_bf16 v[64:67], v[172:175], v[214:217], v[64:67]
	s_setprio 0
	s_barrier
	ds_read_b128 v[178:181], v143 offset:49152
	ds_read_b128 v[182:185], v143 offset:50176
	ds_read_b128 v[186:189], v143 offset:51200
	ds_read_b128 v[190:193], v143 offset:52224
	ds_read_b128 v[194:197], v143 offset:53248
	ds_read_b128 v[206:209], v143 offset:54272
	ds_read_b128 v[210:213], v143 offset:55296
	ds_read_b128 v[214:217], v143 offset:56320
	s_mov_b32 m0, s1
	v_lshl_add_u64 v[136:137], v[136:137], 0, s[10:11]
	global_load_lds_dwordx4 v[136:137], off
	s_mov_b32 m0, s89
	v_lshl_add_u64 v[136:137], v[198:199], 0, s[10:11]
	global_load_lds_dwordx4 v[136:137], off
	s_mov_b32 m0, s90
	v_lshl_add_u64 v[136:137], s[52:53], 0, v[130:131]
	global_load_lds_dwordx4 v[136:137], off
	s_mov_b32 m0, s88
	v_lshl_add_u64 v[136:137], s[52:53], 0, v[134:135]
	global_load_lds_dwordx4 v[136:137], off
	s_mov_b32 m0, s75
	v_lshl_add_u64 v[136:137], v[202:203], 0, s[10:11]
	global_load_lds_dwordx4 v[136:137], off
	s_mov_b32 m0, s77
	v_lshl_add_u64 v[136:137], v[218:219], 0, s[10:11]
	global_load_lds_dwordx4 v[136:137], off
	s_waitcnt vmcnt(8)
	s_waitcnt lgkmcnt(0)
	s_barrier
	s_setprio 1
	v_mfma_f32_16x16x32_bf16 v[60:63], v[144:147], v[178:181], v[60:63]
	v_mfma_f32_16x16x32_bf16 v[56:59], v[152:155], v[178:181], v[56:59]
	v_mfma_f32_16x16x32_bf16 v[52:55], v[144:147], v[186:189], v[52:55]
	v_mfma_f32_16x16x32_bf16 v[44:47], v[152:155], v[186:189], v[44:47]
	v_mfma_f32_16x16x32_bf16 v[36:39], v[144:147], v[194:197], v[36:39]
	v_mfma_f32_16x16x32_bf16 v[28:31], v[152:155], v[194:197], v[28:31]
	v_mfma_f32_16x16x32_bf16 v[20:23], v[144:147], v[210:213], v[20:23]
	v_mfma_f32_16x16x32_bf16 v[12:15], v[152:155], v[210:213], v[12:15]
	v_mfma_f32_16x16x32_bf16 v[60:63], v[148:151], v[182:185], v[60:63]
	v_mfma_f32_16x16x32_bf16 v[56:59], v[156:159], v[182:185], v[56:59]
	v_mfma_f32_16x16x32_bf16 v[52:55], v[148:151], v[190:193], v[52:55]
	v_mfma_f32_16x16x32_bf16 v[44:47], v[156:159], v[190:193], v[44:47]
	v_mfma_f32_16x16x32_bf16 v[36:39], v[148:151], v[206:209], v[36:39]
	v_mfma_f32_16x16x32_bf16 v[28:31], v[156:159], v[206:209], v[28:31]
	v_mfma_f32_16x16x32_bf16 v[20:23], v[148:151], v[214:217], v[20:23]
	v_mfma_f32_16x16x32_bf16 v[12:15], v[156:159], v[214:217], v[12:15]
	v_mfma_f32_16x16x32_bf16 v[48:51], v[160:163], v[178:181], v[48:51]
	v_mfma_f32_16x16x32_bf16 v[40:43], v[168:171], v[178:181], v[40:43]
	v_mfma_f32_16x16x32_bf16 v[32:35], v[160:163], v[186:189], v[32:35]
	v_mfma_f32_16x16x32_bf16 v[24:27], v[168:171], v[186:189], v[24:27]
	v_mfma_f32_16x16x32_bf16 v[16:19], v[160:163], v[194:197], v[16:19]
	v_mfma_f32_16x16x32_bf16 v[8:11], v[168:171], v[194:197], v[8:11]
	v_mfma_f32_16x16x32_bf16 v[4:7], v[160:163], v[210:213], v[4:7]
	v_mfma_f32_16x16x32_bf16 v[0:3], v[168:171], v[210:213], v[0:3]
	v_mfma_f32_16x16x32_bf16 v[48:51], v[164:167], v[182:185], v[48:51]
	v_mfma_f32_16x16x32_bf16 v[40:43], v[172:175], v[182:185], v[40:43]
	v_mfma_f32_16x16x32_bf16 v[32:35], v[164:167], v[190:193], v[32:35]
	v_mfma_f32_16x16x32_bf16 v[24:27], v[172:175], v[190:193], v[24:27]
	v_mfma_f32_16x16x32_bf16 v[16:19], v[164:167], v[206:209], v[16:19]
	v_mfma_f32_16x16x32_bf16 v[8:11], v[172:175], v[206:209], v[8:11]
	v_mfma_f32_16x16x32_bf16 v[4:7], v[164:167], v[214:217], v[4:7]
	v_mfma_f32_16x16x32_bf16 v[0:3], v[172:175], v[214:217], v[0:3]
	s_setprio 0
	s_barrier
	s_movk_i32 s58, 0x100
	s_mov_b64 s[54:55], 0
	s_mov_b64 s[52:53], -1
	s_cbranch_vccz .LBB0_979
	s_and_b64 vcc, exec, s[12:13]
	s_cbranch_vccz .LBB0_982
	s_barrier

.LBB0_1037:
	ds_read_b128 v[128:131], v157
	ds_read_b128 v[132:135], v157 offset:1024
	ds_read_b128 v[136:139], v157 offset:2048
	ds_read_b128 v[140:143], v157 offset:3072
	ds_read_b128 v[160:163], v158
	ds_read_b128 v[164:167], v158 offset:1024
	ds_read_b128 v[168:171], v158 offset:2048
	ds_read_b128 v[172:175], v158 offset:3072
	ds_read_b128 v[178:181], v159
	ds_read_b128 v[182:185], v159 offset:1024
	ds_read_b128 v[186:189], v159 offset:2048
	ds_read_b128 v[190:193], v159 offset:3072
	ds_read_b128 v[194:197], v159 offset:4096
	ds_read_b128 v[206:209], v159 offset:5120
	ds_read_b128 v[210:213], v159 offset:6144
	ds_read_b128 v[214:217], v159 offset:7168
	s_add_u32 s0, s58, 0xfff00080
	s_addc_u32 s1, s59, -1
	s_cmp_eq_u32 s87, 60
	s_cselect_b32 s63, s12, s1
	s_cselect_b32 s62, s29, s0
	s_cselect_b32 s61, s57, s86
	s_cselect_b32 s60, s64, s65
	s_add_i32 m0, s68, 0xc000
	v_lshl_add_u64 v[152:153], s[58:59], 0, v[148:149]
	global_load_lds_dwordx4 v[152:153], off
	s_add_i32 m0, s68, 0xe000
	v_lshl_add_u64 v[152:153], s[58:59], 0, v[150:151]
	global_load_lds_dwordx4 v[152:153], off
	s_waitcnt vmcnt(8)
	s_waitcnt lgkmcnt(0)
	s_barrier
	s_setprio 1
	v_mfma_f32_16x16x32_bf16 v[124:127], v[128:131], v[178:181], v[124:127]
	v_mfma_f32_16x16x32_bf16 v[120:123], v[136:139], v[178:181], v[120:123]
	v_mfma_f32_16x16x32_bf16 v[112:115], v[128:131], v[186:189], v[112:115]
	v_mfma_f32_16x16x32_bf16 v[108:111], v[136:139], v[186:189], v[108:111]
	v_mfma_f32_16x16x32_bf16 v[96:99], v[128:131], v[194:197], v[96:99]
	v_mfma_f32_16x16x32_bf16 v[92:95], v[136:139], v[194:197], v[92:95]
	v_mfma_f32_16x16x32_bf16 v[80:83], v[128:131], v[210:213], v[80:83]
	v_mfma_f32_16x16x32_bf16 v[76:79], v[136:139], v[210:213], v[76:79]
	v_mfma_f32_16x16x32_bf16 v[124:127], v[132:135], v[182:185], v[124:127]
	v_mfma_f32_16x16x32_bf16 v[120:123], v[140:143], v[182:185], v[120:123]
	v_mfma_f32_16x16x32_bf16 v[112:115], v[132:135], v[190:193], v[112:115]
	v_mfma_f32_16x16x32_bf16 v[108:111], v[140:143], v[190:193], v[108:111]
	v_mfma_f32_16x16x32_bf16 v[96:99], v[132:135], v[206:209], v[96:99]
	v_mfma_f32_16x16x32_bf16 v[92:95], v[140:143], v[206:209], v[92:95]
	v_mfma_f32_16x16x32_bf16 v[80:83], v[132:135], v[214:217], v[80:83]
	v_mfma_f32_16x16x32_bf16 v[76:79], v[140:143], v[214:217], v[76:79]
	v_mfma_f32_16x16x32_bf16 v[116:119], v[160:163], v[178:181], v[116:119]
	v_mfma_f32_16x16x32_bf16 v[104:107], v[168:171], v[178:181], v[104:107]
	v_mfma_f32_16x16x32_bf16 v[100:103], v[160:163], v[186:189], v[100:103]
	v_mfma_f32_16x16x32_bf16 v[88:91], v[168:171], v[186:189], v[88:91]
	v_mfma_f32_16x16x32_bf16 v[84:87], v[160:163], v[194:197], v[84:87]
	v_mfma_f32_16x16x32_bf16 v[72:75], v[168:171], v[194:197], v[72:75]
	v_mfma_f32_16x16x32_bf16 v[68:71], v[160:163], v[210:213], v[68:71]
	v_mfma_f32_16x16x32_bf16 v[64:67], v[168:171], v[210:213], v[64:67]
	v_mfma_f32_16x16x32_bf16 v[116:119], v[164:167], v[182:185], v[116:119]
	v_mfma_f32_16x16x32_bf16 v[104:107], v[172:175], v[182:185], v[104:107]
	v_mfma_f32_16x16x32_bf16 v[100:103], v[164:167], v[190:193], v[100:103]
	v_mfma_f32_16x16x32_bf16 v[88:91], v[172:175], v[190:193], v[88:91]
	v_mfma_f32_16x16x32_bf16 v[84:87], v[164:167], v[206:209], v[84:87]
	v_mfma_f32_16x16x32_bf16 v[72:75], v[172:175], v[206:209], v[72:75]
	v_mfma_f32_16x16x32_bf16 v[68:71], v[164:167], v[214:217], v[68:71]
	v_mfma_f32_16x16x32_bf16 v[64:67], v[172:175], v[214:217], v[64:67]
	s_setprio 0
	s_barrier
	ds_read_b128 v[178:181], v159 offset:16384
	ds_read_b128 v[182:185], v159 offset:17408
	ds_read_b128 v[186:189], v159 offset:18432
	ds_read_b128 v[190:193], v159 offset:19456
	ds_read_b128 v[194:197], v159 offset:20480
	ds_read_b128 v[206:209], v159 offset:21504
	ds_read_b128 v[210:213], v159 offset:22528
	ds_read_b128 v[214:217], v159 offset:23552
	s_add_i32 s0, s81, s67
	s_mov_b32 m0, s0
	v_lshl_add_u64 v[152:153], s[60:61], 0, v[146:147]
	global_load_lds_dwordx4 v[152:153], off
	s_add_i32 m0, s0, 0x2000
	s_add_u32 s0, s60, 0x100000
	v_lshl_add_u64 v[198:199], s[60:61], 0, v[144:145]
	s_addc_u32 s1, s61, 0
	s_add_i32 s2, s82, s67
	global_load_lds_dwordx4 v[198:199], off
	v_lshl_add_u64 v[202:203], s[0:1], 0, v[146:147]
	s_mov_b32 m0, s2
	v_lshl_add_u64 v[218:219], s[62:63], 0, v[144:145]
	global_load_lds_dwordx4 v[202:203], off
	s_add_i32 m0, s2, 0x2000
	v_lshl_add_u64 v[202:203], s[0:1], 0, v[144:145]
	global_load_lds_dwordx4 v[202:203], off
	s_mov_b32 m0, s68
	v_lshl_add_u64 v[202:203], s[62:63], 0, v[146:147]
	global_load_lds_dwordx4 v[202:203], off
	s_mov_b32 m0, s69
	s_nop 0
	global_load_lds_dwordx4 v[218:219], off
	s_waitcnt vmcnt(8)
	s_waitcnt lgkmcnt(0)
	s_barrier
	s_setprio 1
	v_mfma_f32_16x16x32_bf16 v[60:63], v[128:131], v[178:181], v[60:63]
	v_mfma_f32_16x16x32_bf16 v[56:59], v[136:139], v[178:181], v[56:59]
	v_mfma_f32_16x16x32_bf16 v[48:51], v[128:131], v[186:189], v[48:51]
	v_mfma_f32_16x16x32_bf16 v[44:47], v[136:139], v[186:189], v[44:47]
	v_mfma_f32_16x16x32_bf16 v[32:35], v[128:131], v[194:197], v[32:35]
	v_mfma_f32_16x16x32_bf16 v[28:31], v[136:139], v[194:197], v[28:31]
	v_mfma_f32_16x16x32_bf16 v[16:19], v[128:131], v[210:213], v[16:19]
	v_mfma_f32_16x16x32_bf16 v[12:15], v[136:139], v[210:213], v[12:15]
	v_mfma_f32_16x16x32_bf16 v[60:63], v[132:135], v[182:185], v[60:63]
	v_mfma_f32_16x16x32_bf16 v[56:59], v[140:143], v[182:185], v[56:59]
	v_mfma_f32_16x16x32_bf16 v[48:51], v[132:135], v[190:193], v[48:51]
	v_mfma_f32_16x16x32_bf16 v[44:47], v[140:143], v[190:193], v[44:47]
	v_mfma_f32_16x16x32_bf16 v[32:35], v[132:135], v[206:209], v[32:35]
	v_mfma_f32_16x16x32_bf16 v[28:31], v[140:143], v[206:209], v[28:31]
	v_mfma_f32_16x16x32_bf16 v[16:19], v[132:135], v[214:217], v[16:19]
	v_mfma_f32_16x16x32_bf16 v[12:15], v[140:143], v[214:217], v[12:15]
	v_mfma_f32_16x16x32_bf16 v[52:55], v[160:163], v[178:181], v[52:55]
	v_mfma_f32_16x16x32_bf16 v[40:43], v[168:171], v[178:181], v[40:43]
	v_mfma_f32_16x16x32_bf16 v[36:39], v[160:163], v[186:189], v[36:39]
	v_mfma_f32_16x16x32_bf16 v[24:27], v[168:171], v[186:189], v[24:27]
	v_mfma_f32_16x16x32_bf16 v[20:23], v[160:163], v[194:197], v[20:23]
	v_mfma_f32_16x16x32_bf16 v[8:11], v[168:171], v[194:197], v[8:11]
	v_mfma_f32_16x16x32_bf16 v[4:7], v[160:163], v[210:213], v[4:7]
	v_mfma_f32_16x16x32_bf16 v[0:3], v[168:171], v[210:213], v[0:3]
	v_mfma_f32_16x16x32_bf16 v[52:55], v[164:167], v[182:185], v[52:55]
	v_mfma_f32_16x16x32_bf16 v[40:43], v[172:175], v[182:185], v[40:43]
	v_mfma_f32_16x16x32_bf16 v[36:39], v[164:167], v[190:193], v[36:39]
	v_mfma_f32_16x16x32_bf16 v[24:27], v[172:175], v[190:193], v[24:27]
	v_mfma_f32_16x16x32_bf16 v[20:23], v[164:167], v[206:209], v[20:23]
	v_mfma_f32_16x16x32_bf16 v[8:11], v[172:175], v[206:209], v[8:11]
	v_mfma_f32_16x16x32_bf16 v[4:7], v[164:167], v[214:217], v[4:7]
	v_mfma_f32_16x16x32_bf16 v[0:3], v[172:175], v[214:217], v[0:3]
	s_setprio 0
	s_barrier
	ds_read_b128 v[178:181], v159 offset:32768
	ds_read_b128 v[182:185], v159 offset:33792
	ds_read_b128 v[186:189], v159 offset:34816
	ds_read_b128 v[190:193], v159 offset:35840
	ds_read_b128 v[194:197], v159 offset:36864
	ds_read_b128 v[206:209], v159 offset:37888
	ds_read_b128 v[210:213], v159 offset:38912
	ds_read_b128 v[214:217], v159 offset:39936
	s_add_i32 s2, 0, 0x18000
	s_add_i32 s3, 0, 0x1c000
	v_add_u32_e32 v140, s2, v156
	v_add_u32_e32 v172, s3, v156
	ds_read_b128 v[128:131], v140
	ds_read_b128 v[132:135], v140 offset:1024
	ds_read_b128 v[136:139], v140 offset:2048
	ds_read_b128 v[140:143], v140 offset:3072
	ds_read_b128 v[160:163], v172
	ds_read_b128 v[164:167], v172 offset:1024
	ds_read_b128 v[168:171], v172 offset:2048
	ds_read_b128 v[172:175], v172 offset:3072
	s_add_u32 s0, s62, 0x100000
	s_addc_u32 s1, s63, 0
	s_mov_b32 m0, s70
	v_lshl_add_u64 v[220:221], s[0:1], 0, v[146:147]
	global_load_lds_dwordx4 v[220:221], off
	s_mov_b32 m0, s71
	v_lshl_add_u64 v[220:221], s[0:1], 0, v[144:145]
	global_load_lds_dwordx4 v[220:221], off
	s_waitcnt vmcnt(8)
	s_waitcnt lgkmcnt(0)
	s_barrier
	s_setprio 1
	v_mfma_f32_16x16x32_bf16 v[124:127], v[128:131], v[178:181], v[124:127]
	v_mfma_f32_16x16x32_bf16 v[120:123], v[136:139], v[178:181], v[120:123]
	v_mfma_f32_16x16x32_bf16 v[112:115], v[128:131], v[186:189], v[112:115]
	v_mfma_f32_16x16x32_bf16 v[108:111], v[136:139], v[186:189], v[108:111]
	v_mfma_f32_16x16x32_bf16 v[96:99], v[128:131], v[194:197], v[96:99]
	v_mfma_f32_16x16x32_bf16 v[92:95], v[136:139], v[194:197], v[92:95]
	v_mfma_f32_16x16x32_bf16 v[80:83], v[128:131], v[210:213], v[80:83]
	v_mfma_f32_16x16x32_bf16 v[76:79], v[136:139], v[210:213], v[76:79]
	v_mfma_f32_16x16x32_bf16 v[124:127], v[132:135], v[182:185], v[124:127]
	v_mfma_f32_16x16x32_bf16 v[120:123], v[140:143], v[182:185], v[120:123]
	v_mfma_f32_16x16x32_bf16 v[112:115], v[132:135], v[190:193], v[112:115]
	v_mfma_f32_16x16x32_bf16 v[108:111], v[140:143], v[190:193], v[108:111]
	v_mfma_f32_16x16x32_bf16 v[96:99], v[132:135], v[206:209], v[96:99]
	v_mfma_f32_16x16x32_bf16 v[92:95], v[140:143], v[206:209], v[92:95]
	v_mfma_f32_16x16x32_bf16 v[80:83], v[132:135], v[214:217], v[80:83]
	v_mfma_f32_16x16x32_bf16 v[76:79], v[140:143], v[214:217], v[76:79]
	v_mfma_f32_16x16x32_bf16 v[116:119], v[160:163], v[178:181], v[116:119]
	v_mfma_f32_16x16x32_bf16 v[104:107], v[168:171], v[178:181], v[104:107]
	v_mfma_f32_16x16x32_bf16 v[100:103], v[160:163], v[186:189], v[100:103]
	v_mfma_f32_16x16x32_bf16 v[88:91], v[168:171], v[186:189], v[88:91]
	v_mfma_f32_16x16x32_bf16 v[84:87], v[160:163], v[194:197], v[84:87]
	v_mfma_f32_16x16x32_bf16 v[72:75], v[168:171], v[194:197], v[72:75]
	v_mfma_f32_16x16x32_bf16 v[68:71], v[160:163], v[210:213], v[68:71]
	v_mfma_f32_16x16x32_bf16 v[64:67], v[168:171], v[210:213], v[64:67]
	v_mfma_f32_16x16x32_bf16 v[116:119], v[164:167], v[182:185], v[116:119]
	v_mfma_f32_16x16x32_bf16 v[104:107], v[172:175], v[182:185], v[104:107]
	v_mfma_f32_16x16x32_bf16 v[100:103], v[164:167], v[190:193], v[100:103]
	v_mfma_f32_16x16x32_bf16 v[88:91], v[172:175], v[190:193], v[88:91]
	v_mfma_f32_16x16x32_bf16 v[84:87], v[164:167], v[206:209], v[84:87]
	v_mfma_f32_16x16x32_bf16 v[72:75], v[172:175], v[206:209], v[72:75]
	v_mfma_f32_16x16x32_bf16 v[68:71], v[164:167], v[214:217], v[68:71]
	v_mfma_f32_16x16x32_bf16 v[64:67], v[172:175], v[214:217], v[64:67]
	s_setprio 0
	s_barrier
	ds_read_b128 v[178:181], v159 offset:49152
	ds_read_b128 v[182:185], v159 offset:50176
	ds_read_b128 v[186:189], v159 offset:51200
	ds_read_b128 v[190:193], v159 offset:52224
	ds_read_b128 v[194:197], v159 offset:53248
	ds_read_b128 v[206:209], v159 offset:54272
	ds_read_b128 v[210:213], v159 offset:55296
	ds_read_b128 v[214:217], v159 offset:56320
	s_add_i32 s0, s2, s67
	s_mov_b32 m0, s0
	v_lshl_add_u64 v[152:153], v[152:153], 0, s[10:11]
	global_load_lds_dwordx4 v[152:153], off
	s_add_i32 m0, s0, 0x2000
	s_add_u32 s0, s60, 0x100080
	v_lshl_add_u64 v[152:153], v[198:199], 0, s[10:11]
	s_addc_u32 s1, s61, 0
	s_add_i32 s2, s3, s67
	global_load_lds_dwordx4 v[152:153], off
	s_mov_b32 m0, s2
	v_lshl_add_u64 v[152:153], s[0:1], 0, v[146:147]
	global_load_lds_dwordx4 v[152:153], off
	s_add_i32 m0, s2, 0x2000
	v_lshl_add_u64 v[152:153], s[0:1], 0, v[144:145]
	global_load_lds_dwordx4 v[152:153], off
	s_mov_b32 m0, s79
	v_lshl_add_u64 v[152:153], v[202:203], 0, s[10:11]
	global_load_lds_dwordx4 v[152:153], off
	s_mov_b32 m0, s80
	v_lshl_add_u64 v[152:153], v[218:219], 0, s[10:11]
	global_load_lds_dwordx4 v[152:153], off
	s_waitcnt vmcnt(8)
	s_waitcnt lgkmcnt(0)
	s_barrier
	s_setprio 1
	v_mfma_f32_16x16x32_bf16 v[60:63], v[128:131], v[178:181], v[60:63]
	v_mfma_f32_16x16x32_bf16 v[56:59], v[136:139], v[178:181], v[56:59]
	v_mfma_f32_16x16x32_bf16 v[48:51], v[128:131], v[186:189], v[48:51]
	v_mfma_f32_16x16x32_bf16 v[44:47], v[136:139], v[186:189], v[44:47]
	v_mfma_f32_16x16x32_bf16 v[32:35], v[128:131], v[194:197], v[32:35]
	v_mfma_f32_16x16x32_bf16 v[28:31], v[136:139], v[194:197], v[28:31]
	v_mfma_f32_16x16x32_bf16 v[16:19], v[128:131], v[210:213], v[16:19]
	v_mfma_f32_16x16x32_bf16 v[12:15], v[136:139], v[210:213], v[12:15]
	v_mfma_f32_16x16x32_bf16 v[60:63], v[132:135], v[182:185], v[60:63]
	v_mfma_f32_16x16x32_bf16 v[56:59], v[140:143], v[182:185], v[56:59]
	v_mfma_f32_16x16x32_bf16 v[48:51], v[132:135], v[190:193], v[48:51]
	v_mfma_f32_16x16x32_bf16 v[44:47], v[140:143], v[190:193], v[44:47]
	v_mfma_f32_16x16x32_bf16 v[32:35], v[132:135], v[206:209], v[32:35]
	v_mfma_f32_16x16x32_bf16 v[28:31], v[140:143], v[206:209], v[28:31]
	v_mfma_f32_16x16x32_bf16 v[16:19], v[132:135], v[214:217], v[16:19]
	v_mfma_f32_16x16x32_bf16 v[12:15], v[140:143], v[214:217], v[12:15]
	v_mfma_f32_16x16x32_bf16 v[52:55], v[160:163], v[178:181], v[52:55]
	v_mfma_f32_16x16x32_bf16 v[40:43], v[168:171], v[178:181], v[40:43]
	v_mfma_f32_16x16x32_bf16 v[36:39], v[160:163], v[186:189], v[36:39]
	v_mfma_f32_16x16x32_bf16 v[24:27], v[168:171], v[186:189], v[24:27]
	v_mfma_f32_16x16x32_bf16 v[20:23], v[160:163], v[194:197], v[20:23]
	v_mfma_f32_16x16x32_bf16 v[8:11], v[168:171], v[194:197], v[8:11]
	v_mfma_f32_16x16x32_bf16 v[4:7], v[160:163], v[210:213], v[4:7]
	v_mfma_f32_16x16x32_bf16 v[0:3], v[168:171], v[210:213], v[0:3]
	v_mfma_f32_16x16x32_bf16 v[52:55], v[164:167], v[182:185], v[52:55]
	v_mfma_f32_16x16x32_bf16 v[40:43], v[172:175], v[182:185], v[40:43]
	v_mfma_f32_16x16x32_bf16 v[36:39], v[164:167], v[190:193], v[36:39]
	v_mfma_f32_16x16x32_bf16 v[24:27], v[172:175], v[190:193], v[24:27]
	v_mfma_f32_16x16x32_bf16 v[20:23], v[164:167], v[206:209], v[20:23]
	v_mfma_f32_16x16x32_bf16 v[8:11], v[172:175], v[206:209], v[8:11]
	v_mfma_f32_16x16x32_bf16 v[4:7], v[164:167], v[214:217], v[4:7]
	v_mfma_f32_16x16x32_bf16 v[0:3], v[172:175], v[214:217], v[0:3]
	s_setprio 0
	s_barrier
	s_add_i32 s87, s87, 2
	s_add_u32 s58, s58, 0x100
	s_addc_u32 s59, s59, 0
	s_add_u32 s65, s65, 0x100
	s_addc_u32 s86, s86, 0
	s_cmp_gt_u32 s87, 61
	s_cbranch_scc0 .LBB0_1037
	s_and_b64 vcc, exec, s[14:15]
	s_cbranch_vccz .LBB0_1040
	s_barrier

.LBB0_1107:
	ds_read_b128 v[128:131], v203
	ds_read_b128 v[132:135], v203 offset:1024
	ds_read_b128 v[136:139], v203 offset:2048
	ds_read_b128 v[140:143], v203 offset:3072
	ds_read_b128 v[144:147], v204
	ds_read_b128 v[148:151], v204 offset:1024
	ds_read_b128 v[152:155], v204 offset:2048
	ds_read_b128 v[156:159], v204 offset:3072
	ds_read_b128 v[160:163], v205
	ds_read_b128 v[164:167], v205 offset:1024
	ds_read_b128 v[168:171], v205 offset:2048
	ds_read_b128 v[172:175], v205 offset:3072
	ds_read_b128 v[190:193], v205 offset:4096
	ds_read_b128 v[194:197], v205 offset:5120
	ds_read_b128 v[206:209], v205 offset:6144
	ds_read_b128 v[210:213], v205 offset:7168
	s_add_u32 s0, s4, 0xfff80080
	s_addc_u32 s1, s5, -1
	s_cmp_eq_u32 s96, 28
	s_cselect_b32 s9, s13, s1
	s_cselect_b32 s8, s15, s0
	s_cselect_b32 s7, s37, s11
	s_cselect_b32 s6, s63, s10
	s_add_i32 m0, s77, 0xc000
	v_lshl_add_u64 v[198:199], s[4:5], 0, v[186:187]
	global_load_lds_dwordx4 v[198:199], off
	s_add_i32 m0, s77, 0xe000
	v_lshl_add_u64 v[198:199], s[4:5], 0, v[188:189]
	global_load_lds_dwordx4 v[198:199], off
	s_waitcnt vmcnt(8)
	s_waitcnt lgkmcnt(0)
	s_barrier
	s_setprio 1
	v_mfma_f32_16x16x32_bf16 v[124:127], v[128:131], v[160:163], v[124:127]
	v_mfma_f32_16x16x32_bf16 v[56:59], v[136:139], v[160:163], v[56:59]
	v_mfma_f32_16x16x32_bf16 v[116:119], v[128:131], v[168:171], v[116:119]
	v_mfma_f32_16x16x32_bf16 v[52:55], v[136:139], v[168:171], v[52:55]
	v_mfma_f32_16x16x32_bf16 v[108:111], v[128:131], v[190:193], v[108:111]
	v_mfma_f32_16x16x32_bf16 v[44:47], v[136:139], v[190:193], v[44:47]
	v_mfma_f32_16x16x32_bf16 v[104:107], v[128:131], v[206:209], v[104:107]
	v_mfma_f32_16x16x32_bf16 v[32:35], v[136:139], v[206:209], v[32:35]
	v_mfma_f32_16x16x32_bf16 v[124:127], v[132:135], v[164:167], v[124:127]
	v_mfma_f32_16x16x32_bf16 v[56:59], v[140:143], v[164:167], v[56:59]
	v_mfma_f32_16x16x32_bf16 v[116:119], v[132:135], v[172:175], v[116:119]
	v_mfma_f32_16x16x32_bf16 v[52:55], v[140:143], v[172:175], v[52:55]
	v_mfma_f32_16x16x32_bf16 v[108:111], v[132:135], v[194:197], v[108:111]
	v_mfma_f32_16x16x32_bf16 v[44:47], v[140:143], v[194:197], v[44:47]
	v_mfma_f32_16x16x32_bf16 v[104:107], v[132:135], v[210:213], v[104:107]
	v_mfma_f32_16x16x32_bf16 v[32:35], v[140:143], v[210:213], v[32:35]
	v_mfma_f32_16x16x32_bf16 v[120:123], v[144:147], v[160:163], v[120:123]
	v_mfma_f32_16x16x32_bf16 v[60:63], v[152:155], v[160:163], v[60:63]
	v_mfma_f32_16x16x32_bf16 v[112:115], v[144:147], v[168:171], v[112:115]
	v_mfma_f32_16x16x32_bf16 v[48:51], v[152:155], v[168:171], v[48:51]
	v_mfma_f32_16x16x32_bf16 v[100:103], v[144:147], v[190:193], v[100:103]
	v_mfma_f32_16x16x32_bf16 v[40:43], v[152:155], v[190:193], v[40:43]
	v_mfma_f32_16x16x32_bf16 v[96:99], v[144:147], v[206:209], v[96:99]
	v_mfma_f32_16x16x32_bf16 v[36:39], v[152:155], v[206:209], v[36:39]
	v_mfma_f32_16x16x32_bf16 v[120:123], v[148:151], v[164:167], v[120:123]
	v_mfma_f32_16x16x32_bf16 v[60:63], v[156:159], v[164:167], v[60:63]
	v_mfma_f32_16x16x32_bf16 v[112:115], v[148:151], v[172:175], v[112:115]
	v_mfma_f32_16x16x32_bf16 v[48:51], v[156:159], v[172:175], v[48:51]
	v_mfma_f32_16x16x32_bf16 v[100:103], v[148:151], v[194:197], v[100:103]
	v_mfma_f32_16x16x32_bf16 v[40:43], v[156:159], v[194:197], v[40:43]
	v_mfma_f32_16x16x32_bf16 v[96:99], v[148:151], v[210:213], v[96:99]
	v_mfma_f32_16x16x32_bf16 v[36:39], v[156:159], v[210:213], v[36:39]
	s_setprio 0
	s_barrier
	ds_read_b128 v[160:163], v205 offset:16384
	ds_read_b128 v[164:167], v205 offset:17408
	ds_read_b128 v[168:171], v205 offset:18432
	ds_read_b128 v[172:175], v205 offset:19456
	ds_read_b128 v[190:193], v205 offset:20480
	ds_read_b128 v[194:197], v205 offset:21504
	ds_read_b128 v[206:209], v205 offset:22528
	ds_read_b128 v[210:213], v205 offset:23552
	s_add_i32 s0, s92, s76
	s_mov_b32 m0, s0
	v_lshl_add_u64 v[198:199], s[6:7], 0, v[180:181]
	global_load_lds_dwordx4 v[198:199], off
	s_add_i32 m0, s0, 0x2000
	s_add_u32 s0, s6, 0x80000
	v_lshl_add_u64 v[214:215], s[6:7], 0, v[184:185]
	s_addc_u32 s1, s7, 0
	s_add_i32 s2, s93, s76
	global_load_lds_dwordx4 v[214:215], off
	v_lshl_add_u64 v[216:217], s[0:1], 0, v[180:181]
	s_mov_b32 m0, s2
	v_lshl_add_u64 v[218:219], s[8:9], 0, v[182:183]
	global_load_lds_dwordx4 v[216:217], off
	s_add_i32 m0, s2, 0x2000
	v_lshl_add_u64 v[216:217], s[0:1], 0, v[184:185]
	global_load_lds_dwordx4 v[216:217], off
	s_mov_b32 m0, s77
	v_lshl_add_u64 v[216:217], s[8:9], 0, v[178:179]
	global_load_lds_dwordx4 v[216:217], off
	s_mov_b32 m0, s78
	s_nop 0
	global_load_lds_dwordx4 v[218:219], off
	s_waitcnt vmcnt(8)
	s_waitcnt lgkmcnt(0)
	s_barrier
	s_setprio 1
	v_mfma_f32_16x16x32_bf16 v[92:95], v[128:131], v[160:163], v[92:95]
	v_mfma_f32_16x16x32_bf16 v[24:27], v[136:139], v[160:163], v[24:27]
	v_mfma_f32_16x16x32_bf16 v[84:87], v[128:131], v[168:171], v[84:87]
	v_mfma_f32_16x16x32_bf16 v[20:23], v[136:139], v[168:171], v[20:23]
	v_mfma_f32_16x16x32_bf16 v[76:79], v[128:131], v[190:193], v[76:79]
	v_mfma_f32_16x16x32_bf16 v[12:15], v[136:139], v[190:193], v[12:15]
	v_mfma_f32_16x16x32_bf16 v[72:75], v[128:131], v[206:209], v[72:75]
	v_mfma_f32_16x16x32_bf16 v[0:3], v[136:139], v[206:209], v[0:3]
	v_mfma_f32_16x16x32_bf16 v[92:95], v[132:135], v[164:167], v[92:95]
	v_mfma_f32_16x16x32_bf16 v[24:27], v[140:143], v[164:167], v[24:27]
	v_mfma_f32_16x16x32_bf16 v[84:87], v[132:135], v[172:175], v[84:87]
	v_mfma_f32_16x16x32_bf16 v[20:23], v[140:143], v[172:175], v[20:23]
	v_mfma_f32_16x16x32_bf16 v[76:79], v[132:135], v[194:197], v[76:79]
	v_mfma_f32_16x16x32_bf16 v[12:15], v[140:143], v[194:197], v[12:15]
	v_mfma_f32_16x16x32_bf16 v[72:75], v[132:135], v[210:213], v[72:75]
	v_mfma_f32_16x16x32_bf16 v[0:3], v[140:143], v[210:213], v[0:3]
	v_mfma_f32_16x16x32_bf16 v[88:91], v[144:147], v[160:163], v[88:91]
	v_mfma_f32_16x16x32_bf16 v[28:31], v[152:155], v[160:163], v[28:31]
	v_mfma_f32_16x16x32_bf16 v[80:83], v[144:147], v[168:171], v[80:83]
	v_mfma_f32_16x16x32_bf16 v[16:19], v[152:155], v[168:171], v[16:19]
	v_mfma_f32_16x16x32_bf16 v[68:71], v[144:147], v[190:193], v[68:71]
	v_mfma_f32_16x16x32_bf16 v[8:11], v[152:155], v[190:193], v[8:11]
	v_mfma_f32_16x16x32_bf16 v[64:67], v[144:147], v[206:209], v[64:67]
	v_mfma_f32_16x16x32_bf16 v[4:7], v[152:155], v[206:209], v[4:7]
	v_mfma_f32_16x16x32_bf16 v[88:91], v[148:151], v[164:167], v[88:91]
	v_mfma_f32_16x16x32_bf16 v[28:31], v[156:159], v[164:167], v[28:31]
	v_mfma_f32_16x16x32_bf16 v[80:83], v[148:151], v[172:175], v[80:83]
	v_mfma_f32_16x16x32_bf16 v[16:19], v[156:159], v[172:175], v[16:19]
	v_mfma_f32_16x16x32_bf16 v[68:71], v[148:151], v[194:197], v[68:71]
	v_mfma_f32_16x16x32_bf16 v[8:11], v[156:159], v[194:197], v[8:11]
	v_mfma_f32_16x16x32_bf16 v[64:67], v[148:151], v[210:213], v[64:67]
	v_mfma_f32_16x16x32_bf16 v[4:7], v[156:159], v[210:213], v[4:7]
	s_setprio 0
	s_barrier
	ds_read_b128 v[160:163], v205 offset:32768
	ds_read_b128 v[164:167], v205 offset:33792
	ds_read_b128 v[168:171], v205 offset:34816
	ds_read_b128 v[172:175], v205 offset:35840
	ds_read_b128 v[190:193], v205 offset:36864
	ds_read_b128 v[194:197], v205 offset:37888
	ds_read_b128 v[206:209], v205 offset:38912
	ds_read_b128 v[210:213], v205 offset:39936
	s_add_i32 s2, 0, 0x18000
	s_add_i32 s38, 0, 0x1c000
	v_add_u32_e32 v140, s2, v202
	v_add_u32_e32 v156, s38, v202
	ds_read_b128 v[128:131], v140
	ds_read_b128 v[132:135], v140 offset:1024
	ds_read_b128 v[136:139], v140 offset:2048
	ds_read_b128 v[140:143], v140 offset:3072
	ds_read_b128 v[144:147], v156
	ds_read_b128 v[148:151], v156 offset:1024
	ds_read_b128 v[152:155], v156 offset:2048
	ds_read_b128 v[156:159], v156 offset:3072
	s_add_u32 s0, s8, 0x80000
	s_addc_u32 s1, s9, 0
	s_mov_b32 m0, s79
	v_lshl_add_u64 v[220:221], s[0:1], 0, v[178:179]
	global_load_lds_dwordx4 v[220:221], off
	s_mov_b32 m0, s80
	v_lshl_add_u64 v[220:221], s[0:1], 0, v[182:183]
	global_load_lds_dwordx4 v[220:221], off
	s_waitcnt vmcnt(8)
	s_waitcnt lgkmcnt(0)
	s_barrier
	s_setprio 1
	v_mfma_f32_16x16x32_bf16 v[124:127], v[128:131], v[160:163], v[124:127]
	v_mfma_f32_16x16x32_bf16 v[56:59], v[136:139], v[160:163], v[56:59]
	v_mfma_f32_16x16x32_bf16 v[116:119], v[128:131], v[168:171], v[116:119]
	v_mfma_f32_16x16x32_bf16 v[52:55], v[136:139], v[168:171], v[52:55]
	v_mfma_f32_16x16x32_bf16 v[108:111], v[128:131], v[190:193], v[108:111]
	v_mfma_f32_16x16x32_bf16 v[44:47], v[136:139], v[190:193], v[44:47]
	v_mfma_f32_16x16x32_bf16 v[104:107], v[128:131], v[206:209], v[104:107]
	v_mfma_f32_16x16x32_bf16 v[32:35], v[136:139], v[206:209], v[32:35]
	v_mfma_f32_16x16x32_bf16 v[124:127], v[132:135], v[164:167], v[124:127]
	v_mfma_f32_16x16x32_bf16 v[56:59], v[140:143], v[164:167], v[56:59]
	v_mfma_f32_16x16x32_bf16 v[116:119], v[132:135], v[172:175], v[116:119]
	v_mfma_f32_16x16x32_bf16 v[52:55], v[140:143], v[172:175], v[52:55]
	v_mfma_f32_16x16x32_bf16 v[108:111], v[132:135], v[194:197], v[108:111]
	v_mfma_f32_16x16x32_bf16 v[44:47], v[140:143], v[194:197], v[44:47]
	v_mfma_f32_16x16x32_bf16 v[104:107], v[132:135], v[210:213], v[104:107]
	v_mfma_f32_16x16x32_bf16 v[32:35], v[140:143], v[210:213], v[32:35]
	v_mfma_f32_16x16x32_bf16 v[120:123], v[144:147], v[160:163], v[120:123]
	v_mfma_f32_16x16x32_bf16 v[60:63], v[152:155], v[160:163], v[60:63]
	v_mfma_f32_16x16x32_bf16 v[112:115], v[144:147], v[168:171], v[112:115]
	v_mfma_f32_16x16x32_bf16 v[48:51], v[152:155], v[168:171], v[48:51]
	v_mfma_f32_16x16x32_bf16 v[100:103], v[144:147], v[190:193], v[100:103]
	v_mfma_f32_16x16x32_bf16 v[40:43], v[152:155], v[190:193], v[40:43]
	v_mfma_f32_16x16x32_bf16 v[96:99], v[144:147], v[206:209], v[96:99]
	v_mfma_f32_16x16x32_bf16 v[36:39], v[152:155], v[206:209], v[36:39]
	v_mfma_f32_16x16x32_bf16 v[120:123], v[148:151], v[164:167], v[120:123]
	v_mfma_f32_16x16x32_bf16 v[60:63], v[156:159], v[164:167], v[60:63]
	v_mfma_f32_16x16x32_bf16 v[112:115], v[148:151], v[172:175], v[112:115]
	v_mfma_f32_16x16x32_bf16 v[48:51], v[156:159], v[172:175], v[48:51]
	v_mfma_f32_16x16x32_bf16 v[100:103], v[148:151], v[194:197], v[100:103]
	v_mfma_f32_16x16x32_bf16 v[40:43], v[156:159], v[194:197], v[40:43]
	v_mfma_f32_16x16x32_bf16 v[96:99], v[148:151], v[210:213], v[96:99]
	v_mfma_f32_16x16x32_bf16 v[36:39], v[156:159], v[210:213], v[36:39]
	s_setprio 0
	s_barrier
	ds_read_b128 v[160:163], v205 offset:49152
	ds_read_b128 v[164:167], v205 offset:50176
	ds_read_b128 v[168:171], v205 offset:51200
	ds_read_b128 v[172:175], v205 offset:52224
	ds_read_b128 v[190:193], v205 offset:53248
	ds_read_b128 v[194:197], v205 offset:54272
	ds_read_b128 v[206:209], v205 offset:55296
	ds_read_b128 v[210:213], v205 offset:56320
	s_add_i32 s0, s2, s76
	s_mov_b32 m0, s0
	v_lshl_add_u64 v[198:199], v[198:199], 0, s[24:25]
	global_load_lds_dwordx4 v[198:199], off
	s_add_i32 m0, s0, 0x2000
	s_add_u32 s0, s6, 0x80080
	v_lshl_add_u64 v[198:199], v[214:215], 0, s[24:25]
	s_addc_u32 s1, s7, 0
	s_add_i32 s2, s38, s76
	global_load_lds_dwordx4 v[198:199], off
	s_mov_b32 m0, s2
	v_lshl_add_u64 v[198:199], s[0:1], 0, v[180:181]
	global_load_lds_dwordx4 v[198:199], off
	s_add_i32 m0, s2, 0x2000
	v_lshl_add_u64 v[198:199], s[0:1], 0, v[184:185]
	global_load_lds_dwordx4 v[198:199], off
	s_mov_b32 m0, s86
	v_lshl_add_u64 v[198:199], v[216:217], 0, s[24:25]
	global_load_lds_dwordx4 v[198:199], off
	s_mov_b32 m0, s87
	v_lshl_add_u64 v[198:199], v[218:219], 0, s[24:25]
	global_load_lds_dwordx4 v[198:199], off
	s_waitcnt vmcnt(8)
	s_waitcnt lgkmcnt(0)
	s_barrier
	s_setprio 1
	v_mfma_f32_16x16x32_bf16 v[92:95], v[128:131], v[160:163], v[92:95]
	v_mfma_f32_16x16x32_bf16 v[24:27], v[136:139], v[160:163], v[24:27]
	v_mfma_f32_16x16x32_bf16 v[84:87], v[128:131], v[168:171], v[84:87]
	v_mfma_f32_16x16x32_bf16 v[20:23], v[136:139], v[168:171], v[20:23]
	v_mfma_f32_16x16x32_bf16 v[76:79], v[128:131], v[190:193], v[76:79]
	v_mfma_f32_16x16x32_bf16 v[12:15], v[136:139], v[190:193], v[12:15]
	v_mfma_f32_16x16x32_bf16 v[72:75], v[128:131], v[206:209], v[72:75]
	v_mfma_f32_16x16x32_bf16 v[0:3], v[136:139], v[206:209], v[0:3]
	v_mfma_f32_16x16x32_bf16 v[92:95], v[132:135], v[164:167], v[92:95]
	v_mfma_f32_16x16x32_bf16 v[24:27], v[140:143], v[164:167], v[24:27]
	v_mfma_f32_16x16x32_bf16 v[84:87], v[132:135], v[172:175], v[84:87]
	v_mfma_f32_16x16x32_bf16 v[20:23], v[140:143], v[172:175], v[20:23]
	v_mfma_f32_16x16x32_bf16 v[76:79], v[132:135], v[194:197], v[76:79]
	v_mfma_f32_16x16x32_bf16 v[12:15], v[140:143], v[194:197], v[12:15]
	v_mfma_f32_16x16x32_bf16 v[72:75], v[132:135], v[210:213], v[72:75]
	v_mfma_f32_16x16x32_bf16 v[0:3], v[140:143], v[210:213], v[0:3]
	v_mfma_f32_16x16x32_bf16 v[88:91], v[144:147], v[160:163], v[88:91]
	v_mfma_f32_16x16x32_bf16 v[28:31], v[152:155], v[160:163], v[28:31]
	v_mfma_f32_16x16x32_bf16 v[80:83], v[144:147], v[168:171], v[80:83]
	v_mfma_f32_16x16x32_bf16 v[16:19], v[152:155], v[168:171], v[16:19]
	v_mfma_f32_16x16x32_bf16 v[68:71], v[144:147], v[190:193], v[68:71]
	v_mfma_f32_16x16x32_bf16 v[8:11], v[152:155], v[190:193], v[8:11]
	v_mfma_f32_16x16x32_bf16 v[64:67], v[144:147], v[206:209], v[64:67]
	v_mfma_f32_16x16x32_bf16 v[4:7], v[152:155], v[206:209], v[4:7]
	v_mfma_f32_16x16x32_bf16 v[88:91], v[148:151], v[164:167], v[88:91]
	v_mfma_f32_16x16x32_bf16 v[28:31], v[156:159], v[164:167], v[28:31]
	v_mfma_f32_16x16x32_bf16 v[80:83], v[148:151], v[172:175], v[80:83]
	v_mfma_f32_16x16x32_bf16 v[16:19], v[156:159], v[172:175], v[16:19]
	v_mfma_f32_16x16x32_bf16 v[68:71], v[148:151], v[194:197], v[68:71]
	v_mfma_f32_16x16x32_bf16 v[8:11], v[156:159], v[194:197], v[8:11]
	v_mfma_f32_16x16x32_bf16 v[64:67], v[148:151], v[210:213], v[64:67]
	v_mfma_f32_16x16x32_bf16 v[4:7], v[156:159], v[210:213], v[4:7]
	s_setprio 0
	s_barrier
	s_add_i32 s96, s96, 2
	s_add_u32 s4, s4, 0x100
	s_addc_u32 s5, s5, 0
	s_add_u32 s10, s10, 0x100
	s_addc_u32 s11, s11, 0
	s_cmp_gt_u32 s96, 29
	s_cbranch_scc0 .LBB0_1107
	s_and_b64 vcc, exec, s[26:27]
	s_cbranch_vccz .LBB0_1110
	s_barrier

.LBB0_1249:
	ds_read_b128 v[128:131], v157
	ds_read_b128 v[132:135], v157 offset:1024
	ds_read_b128 v[136:139], v157 offset:2048
	ds_read_b128 v[140:143], v157 offset:3072
	ds_read_b128 v[160:163], v158
	ds_read_b128 v[164:167], v158 offset:1024
	ds_read_b128 v[168:171], v158 offset:2048
	ds_read_b128 v[172:175], v158 offset:3072
	ds_read_b128 v[176:179], v159
	ds_read_b128 v[180:183], v159 offset:1024
	ds_read_b128 v[184:187], v159 offset:2048
	ds_read_b128 v[188:191], v159 offset:3072
	ds_read_b128 v[192:195], v159 offset:4096
	ds_read_b128 v[196:199], v159 offset:5120
	ds_read_b128 v[200:203], v159 offset:6144
	ds_read_b128 v[204:207], v159 offset:7168
	s_add_u32 s38, s36, 0x100
	s_addc_u32 s39, s37, 0
	s_cmpk_eq_i32 s74, 0x54
	s_cselect_b32 s45, s6, s39
	s_cselect_b32 s44, s35, s38
	s_cselect_b32 s43, s70, s73
	s_cselect_b32 s42, s71, s72
	s_add_i32 m0, s52, 0xc000
	v_lshl_add_u64 v[152:153], s[36:37], 0, v[148:149]
	global_load_lds_dwordx4 v[152:153], off
	s_add_i32 m0, s52, 0xe000
	v_lshl_add_u64 v[152:153], s[36:37], 0, v[150:151]
	global_load_lds_dwordx4 v[152:153], off
	s_waitcnt vmcnt(8)
	s_waitcnt lgkmcnt(0)
	s_barrier
	s_setprio 1
	v_mfma_f32_16x16x32_bf16 v[124:127], v[128:131], v[176:179], v[124:127]
	v_mfma_f32_16x16x32_bf16 v[120:123], v[136:139], v[176:179], v[120:123]
	v_mfma_f32_16x16x32_bf16 v[112:115], v[128:131], v[184:187], v[112:115]
	v_mfma_f32_16x16x32_bf16 v[108:111], v[136:139], v[184:187], v[108:111]
	v_mfma_f32_16x16x32_bf16 v[96:99], v[128:131], v[192:195], v[96:99]
	v_mfma_f32_16x16x32_bf16 v[92:95], v[136:139], v[192:195], v[92:95]
	v_mfma_f32_16x16x32_bf16 v[80:83], v[128:131], v[200:203], v[80:83]
	v_mfma_f32_16x16x32_bf16 v[76:79], v[136:139], v[200:203], v[76:79]
	v_mfma_f32_16x16x32_bf16 v[124:127], v[132:135], v[180:183], v[124:127]
	v_mfma_f32_16x16x32_bf16 v[120:123], v[140:143], v[180:183], v[120:123]
	v_mfma_f32_16x16x32_bf16 v[112:115], v[132:135], v[188:191], v[112:115]
	v_mfma_f32_16x16x32_bf16 v[108:111], v[140:143], v[188:191], v[108:111]
	v_mfma_f32_16x16x32_bf16 v[96:99], v[132:135], v[196:199], v[96:99]
	v_mfma_f32_16x16x32_bf16 v[92:95], v[140:143], v[196:199], v[92:95]
	v_mfma_f32_16x16x32_bf16 v[80:83], v[132:135], v[204:207], v[80:83]
	v_mfma_f32_16x16x32_bf16 v[76:79], v[140:143], v[204:207], v[76:79]
	v_mfma_f32_16x16x32_bf16 v[116:119], v[160:163], v[176:179], v[116:119]
	v_mfma_f32_16x16x32_bf16 v[104:107], v[168:171], v[176:179], v[104:107]
	v_mfma_f32_16x16x32_bf16 v[100:103], v[160:163], v[184:187], v[100:103]
	v_mfma_f32_16x16x32_bf16 v[88:91], v[168:171], v[184:187], v[88:91]
	v_mfma_f32_16x16x32_bf16 v[84:87], v[160:163], v[192:195], v[84:87]
	v_mfma_f32_16x16x32_bf16 v[72:75], v[168:171], v[192:195], v[72:75]
	v_mfma_f32_16x16x32_bf16 v[68:71], v[160:163], v[200:203], v[68:71]
	v_mfma_f32_16x16x32_bf16 v[64:67], v[168:171], v[200:203], v[64:67]
	v_mfma_f32_16x16x32_bf16 v[116:119], v[164:167], v[180:183], v[116:119]
	v_mfma_f32_16x16x32_bf16 v[104:107], v[172:175], v[180:183], v[104:107]
	v_mfma_f32_16x16x32_bf16 v[100:103], v[164:167], v[188:191], v[100:103]
	v_mfma_f32_16x16x32_bf16 v[88:91], v[172:175], v[188:191], v[88:91]
	v_mfma_f32_16x16x32_bf16 v[84:87], v[164:167], v[196:199], v[84:87]
	v_mfma_f32_16x16x32_bf16 v[72:75], v[172:175], v[196:199], v[72:75]
	v_mfma_f32_16x16x32_bf16 v[68:71], v[164:167], v[204:207], v[68:71]
	v_mfma_f32_16x16x32_bf16 v[64:67], v[172:175], v[204:207], v[64:67]
	s_setprio 0
	s_barrier
	ds_read_b128 v[176:179], v159 offset:16384
	ds_read_b128 v[180:183], v159 offset:17408
	ds_read_b128 v[184:187], v159 offset:18432
	ds_read_b128 v[188:191], v159 offset:19456
	ds_read_b128 v[192:195], v159 offset:20480
	ds_read_b128 v[196:199], v159 offset:21504
	ds_read_b128 v[200:203], v159 offset:22528
	ds_read_b128 v[204:207], v159 offset:23552
	s_add_i32 s36, s64, s51
	s_mov_b32 m0, s36
	v_lshl_add_u64 v[152:153], s[42:43], 0, v[146:147]
	global_load_lds_dwordx4 v[152:153], off
	s_add_i32 m0, s36, 0x2000
	s_add_u32 s36, s42, 0x160000
	v_lshl_add_u64 v[208:209], s[42:43], 0, v[144:145]
	s_addc_u32 s37, s43, 0
	s_add_i32 s75, s65, s51
	global_load_lds_dwordx4 v[208:209], off
	v_lshl_add_u64 v[210:211], s[36:37], 0, v[146:147]
	s_mov_b32 m0, s75
	v_lshl_add_u64 v[212:213], s[44:45], 0, v[144:145]
	global_load_lds_dwordx4 v[210:211], off
	s_add_i32 m0, s75, 0x2000
	v_lshl_add_u64 v[210:211], s[36:37], 0, v[144:145]
	global_load_lds_dwordx4 v[210:211], off
	s_mov_b32 m0, s52
	v_lshl_add_u64 v[210:211], s[44:45], 0, v[146:147]
	global_load_lds_dwordx4 v[210:211], off
	s_mov_b32 m0, s53
	s_nop 0
	global_load_lds_dwordx4 v[212:213], off
	s_waitcnt vmcnt(8)
	s_waitcnt lgkmcnt(0)
	s_barrier
	s_setprio 1
	v_mfma_f32_16x16x32_bf16 v[60:63], v[128:131], v[176:179], v[60:63]
	v_mfma_f32_16x16x32_bf16 v[56:59], v[136:139], v[176:179], v[56:59]
	v_mfma_f32_16x16x32_bf16 v[48:51], v[128:131], v[184:187], v[48:51]
	v_mfma_f32_16x16x32_bf16 v[44:47], v[136:139], v[184:187], v[44:47]
	v_mfma_f32_16x16x32_bf16 v[32:35], v[128:131], v[192:195], v[32:35]
	v_mfma_f32_16x16x32_bf16 v[28:31], v[136:139], v[192:195], v[28:31]
	v_mfma_f32_16x16x32_bf16 v[16:19], v[128:131], v[200:203], v[16:19]
	v_mfma_f32_16x16x32_bf16 v[12:15], v[136:139], v[200:203], v[12:15]
	v_mfma_f32_16x16x32_bf16 v[60:63], v[132:135], v[180:183], v[60:63]
	v_mfma_f32_16x16x32_bf16 v[56:59], v[140:143], v[180:183], v[56:59]
	v_mfma_f32_16x16x32_bf16 v[48:51], v[132:135], v[188:191], v[48:51]
	v_mfma_f32_16x16x32_bf16 v[44:47], v[140:143], v[188:191], v[44:47]
	v_mfma_f32_16x16x32_bf16 v[32:35], v[132:135], v[196:199], v[32:35]
	v_mfma_f32_16x16x32_bf16 v[28:31], v[140:143], v[196:199], v[28:31]
	v_mfma_f32_16x16x32_bf16 v[16:19], v[132:135], v[204:207], v[16:19]
	v_mfma_f32_16x16x32_bf16 v[12:15], v[140:143], v[204:207], v[12:15]
	v_mfma_f32_16x16x32_bf16 v[52:55], v[160:163], v[176:179], v[52:55]
	v_mfma_f32_16x16x32_bf16 v[40:43], v[168:171], v[176:179], v[40:43]
	v_mfma_f32_16x16x32_bf16 v[36:39], v[160:163], v[184:187], v[36:39]
	v_mfma_f32_16x16x32_bf16 v[24:27], v[168:171], v[184:187], v[24:27]
	v_mfma_f32_16x16x32_bf16 v[20:23], v[160:163], v[192:195], v[20:23]
	v_mfma_f32_16x16x32_bf16 v[8:11], v[168:171], v[192:195], v[8:11]
	v_mfma_f32_16x16x32_bf16 v[4:7], v[160:163], v[200:203], v[4:7]
	v_mfma_f32_16x16x32_bf16 v[0:3], v[168:171], v[200:203], v[0:3]
	v_mfma_f32_16x16x32_bf16 v[52:55], v[164:167], v[180:183], v[52:55]
	v_mfma_f32_16x16x32_bf16 v[40:43], v[172:175], v[180:183], v[40:43]
	v_mfma_f32_16x16x32_bf16 v[36:39], v[164:167], v[188:191], v[36:39]
	v_mfma_f32_16x16x32_bf16 v[24:27], v[172:175], v[188:191], v[24:27]
	v_mfma_f32_16x16x32_bf16 v[20:23], v[164:167], v[196:199], v[20:23]
	v_mfma_f32_16x16x32_bf16 v[8:11], v[172:175], v[196:199], v[8:11]
	v_mfma_f32_16x16x32_bf16 v[4:7], v[164:167], v[204:207], v[4:7]
	v_mfma_f32_16x16x32_bf16 v[0:3], v[172:175], v[204:207], v[0:3]
	s_setprio 0
	s_barrier
	ds_read_b128 v[176:179], v159 offset:32768
	ds_read_b128 v[180:183], v159 offset:33792
	ds_read_b128 v[184:187], v159 offset:34816
	ds_read_b128 v[188:191], v159 offset:35840
	ds_read_b128 v[192:195], v159 offset:36864
	ds_read_b128 v[196:199], v159 offset:37888
	ds_read_b128 v[200:203], v159 offset:38912
	ds_read_b128 v[204:207], v159 offset:39936
	s_add_i32 s75, 0, 0x18000
	s_add_i32 s76, 0, 0x1c000
	v_add_u32_e32 v140, s75, v156
	v_add_u32_e32 v172, s76, v156
	ds_read_b128 v[128:131], v140
	ds_read_b128 v[132:135], v140 offset:1024
	ds_read_b128 v[136:139], v140 offset:2048
	ds_read_b128 v[140:143], v140 offset:3072
	ds_read_b128 v[160:163], v172
	ds_read_b128 v[164:167], v172 offset:1024
	ds_read_b128 v[168:171], v172 offset:2048
	ds_read_b128 v[172:175], v172 offset:3072
	s_add_u32 s36, s44, 0x160000
	s_addc_u32 s37, s45, 0
	s_mov_b32 m0, s54
	v_lshl_add_u64 v[214:215], s[36:37], 0, v[146:147]
	global_load_lds_dwordx4 v[214:215], off
	s_mov_b32 m0, s55
	v_lshl_add_u64 v[214:215], s[36:37], 0, v[144:145]
	global_load_lds_dwordx4 v[214:215], off
	s_waitcnt vmcnt(8)
	s_waitcnt lgkmcnt(0)
	s_barrier
	s_setprio 1
	v_mfma_f32_16x16x32_bf16 v[124:127], v[128:131], v[176:179], v[124:127]
	v_mfma_f32_16x16x32_bf16 v[120:123], v[136:139], v[176:179], v[120:123]
	v_mfma_f32_16x16x32_bf16 v[112:115], v[128:131], v[184:187], v[112:115]
	v_mfma_f32_16x16x32_bf16 v[108:111], v[136:139], v[184:187], v[108:111]
	v_mfma_f32_16x16x32_bf16 v[96:99], v[128:131], v[192:195], v[96:99]
	v_mfma_f32_16x16x32_bf16 v[92:95], v[136:139], v[192:195], v[92:95]
	v_mfma_f32_16x16x32_bf16 v[80:83], v[128:131], v[200:203], v[80:83]
	v_mfma_f32_16x16x32_bf16 v[76:79], v[136:139], v[200:203], v[76:79]
	v_mfma_f32_16x16x32_bf16 v[124:127], v[132:135], v[180:183], v[124:127]
	v_mfma_f32_16x16x32_bf16 v[120:123], v[140:143], v[180:183], v[120:123]
	v_mfma_f32_16x16x32_bf16 v[112:115], v[132:135], v[188:191], v[112:115]
	v_mfma_f32_16x16x32_bf16 v[108:111], v[140:143], v[188:191], v[108:111]
	v_mfma_f32_16x16x32_bf16 v[96:99], v[132:135], v[196:199], v[96:99]
	v_mfma_f32_16x16x32_bf16 v[92:95], v[140:143], v[196:199], v[92:95]
	v_mfma_f32_16x16x32_bf16 v[80:83], v[132:135], v[204:207], v[80:83]
	v_mfma_f32_16x16x32_bf16 v[76:79], v[140:143], v[204:207], v[76:79]
	v_mfma_f32_16x16x32_bf16 v[116:119], v[160:163], v[176:179], v[116:119]
	v_mfma_f32_16x16x32_bf16 v[104:107], v[168:171], v[176:179], v[104:107]
	v_mfma_f32_16x16x32_bf16 v[100:103], v[160:163], v[184:187], v[100:103]
	v_mfma_f32_16x16x32_bf16 v[88:91], v[168:171], v[184:187], v[88:91]
	v_mfma_f32_16x16x32_bf16 v[84:87], v[160:163], v[192:195], v[84:87]
	v_mfma_f32_16x16x32_bf16 v[72:75], v[168:171], v[192:195], v[72:75]
	v_mfma_f32_16x16x32_bf16 v[68:71], v[160:163], v[200:203], v[68:71]
	v_mfma_f32_16x16x32_bf16 v[64:67], v[168:171], v[200:203], v[64:67]
	v_mfma_f32_16x16x32_bf16 v[116:119], v[164:167], v[180:183], v[116:119]
	v_mfma_f32_16x16x32_bf16 v[104:107], v[172:175], v[180:183], v[104:107]
	v_mfma_f32_16x16x32_bf16 v[100:103], v[164:167], v[188:191], v[100:103]
	v_mfma_f32_16x16x32_bf16 v[88:91], v[172:175], v[188:191], v[88:91]
	v_mfma_f32_16x16x32_bf16 v[84:87], v[164:167], v[196:199], v[84:87]
	v_mfma_f32_16x16x32_bf16 v[72:75], v[172:175], v[196:199], v[72:75]
	v_mfma_f32_16x16x32_bf16 v[68:71], v[164:167], v[204:207], v[68:71]
	v_mfma_f32_16x16x32_bf16 v[64:67], v[172:175], v[204:207], v[64:67]
	s_setprio 0
	s_barrier
	ds_read_b128 v[176:179], v159 offset:49152
	ds_read_b128 v[180:183], v159 offset:50176
	ds_read_b128 v[184:187], v159 offset:51200
	ds_read_b128 v[188:191], v159 offset:52224
	ds_read_b128 v[192:195], v159 offset:53248
	ds_read_b128 v[196:199], v159 offset:54272
	ds_read_b128 v[200:203], v159 offset:55296
	ds_read_b128 v[204:207], v159 offset:56320
	s_add_i32 s36, s75, s51
	s_mov_b32 m0, s36
	v_lshl_add_u64 v[152:153], v[152:153], 0, s[4:5]
	global_load_lds_dwordx4 v[152:153], off
	s_add_i32 m0, s36, 0x2000
	s_add_u32 s36, s42, 0x160080
	v_lshl_add_u64 v[152:153], v[208:209], 0, s[4:5]
	s_addc_u32 s37, s43, 0
	s_add_i32 s42, s76, s51
	global_load_lds_dwordx4 v[152:153], off
	s_mov_b32 m0, s42
	v_lshl_add_u64 v[152:153], s[36:37], 0, v[146:147]
	global_load_lds_dwordx4 v[152:153], off
	s_add_i32 m0, s42, 0x2000
	v_lshl_add_u64 v[152:153], s[36:37], 0, v[144:145]
	global_load_lds_dwordx4 v[152:153], off
	s_mov_b32 m0, s62
	v_lshl_add_u64 v[152:153], v[210:211], 0, s[4:5]
	global_load_lds_dwordx4 v[152:153], off
	s_mov_b32 m0, s63
	v_lshl_add_u64 v[152:153], v[212:213], 0, s[4:5]
	global_load_lds_dwordx4 v[152:153], off
	s_waitcnt vmcnt(8)
	s_waitcnt lgkmcnt(0)
	s_barrier
	s_setprio 1
	v_mfma_f32_16x16x32_bf16 v[60:63], v[128:131], v[176:179], v[60:63]
	v_mfma_f32_16x16x32_bf16 v[56:59], v[136:139], v[176:179], v[56:59]
	v_mfma_f32_16x16x32_bf16 v[48:51], v[128:131], v[184:187], v[48:51]
	v_mfma_f32_16x16x32_bf16 v[44:47], v[136:139], v[184:187], v[44:47]
	v_mfma_f32_16x16x32_bf16 v[32:35], v[128:131], v[192:195], v[32:35]
	v_mfma_f32_16x16x32_bf16 v[28:31], v[136:139], v[192:195], v[28:31]
	v_mfma_f32_16x16x32_bf16 v[16:19], v[128:131], v[200:203], v[16:19]
	v_mfma_f32_16x16x32_bf16 v[12:15], v[136:139], v[200:203], v[12:15]
	v_mfma_f32_16x16x32_bf16 v[60:63], v[132:135], v[180:183], v[60:63]
	v_mfma_f32_16x16x32_bf16 v[56:59], v[140:143], v[180:183], v[56:59]
	v_mfma_f32_16x16x32_bf16 v[48:51], v[132:135], v[188:191], v[48:51]
	v_mfma_f32_16x16x32_bf16 v[44:47], v[140:143], v[188:191], v[44:47]
	v_mfma_f32_16x16x32_bf16 v[32:35], v[132:135], v[196:199], v[32:35]
	v_mfma_f32_16x16x32_bf16 v[28:31], v[140:143], v[196:199], v[28:31]
	v_mfma_f32_16x16x32_bf16 v[16:19], v[132:135], v[204:207], v[16:19]
	v_mfma_f32_16x16x32_bf16 v[12:15], v[140:143], v[204:207], v[12:15]
	v_mfma_f32_16x16x32_bf16 v[52:55], v[160:163], v[176:179], v[52:55]
	v_mfma_f32_16x16x32_bf16 v[40:43], v[168:171], v[176:179], v[40:43]
	v_mfma_f32_16x16x32_bf16 v[36:39], v[160:163], v[184:187], v[36:39]
	v_mfma_f32_16x16x32_bf16 v[24:27], v[168:171], v[184:187], v[24:27]
	v_mfma_f32_16x16x32_bf16 v[20:23], v[160:163], v[192:195], v[20:23]
	v_mfma_f32_16x16x32_bf16 v[8:11], v[168:171], v[192:195], v[8:11]
	v_mfma_f32_16x16x32_bf16 v[4:7], v[160:163], v[200:203], v[4:7]
	v_mfma_f32_16x16x32_bf16 v[0:3], v[168:171], v[200:203], v[0:3]
	v_mfma_f32_16x16x32_bf16 v[52:55], v[164:167], v[180:183], v[52:55]
	v_mfma_f32_16x16x32_bf16 v[40:43], v[172:175], v[180:183], v[40:43]
	v_mfma_f32_16x16x32_bf16 v[36:39], v[164:167], v[188:191], v[36:39]
	v_mfma_f32_16x16x32_bf16 v[24:27], v[172:175], v[188:191], v[24:27]
	v_mfma_f32_16x16x32_bf16 v[20:23], v[164:167], v[196:199], v[20:23]
	v_mfma_f32_16x16x32_bf16 v[8:11], v[172:175], v[196:199], v[8:11]
	v_mfma_f32_16x16x32_bf16 v[4:7], v[164:167], v[204:207], v[4:7]
	v_mfma_f32_16x16x32_bf16 v[0:3], v[172:175], v[204:207], v[0:3]
	s_setprio 0
	s_barrier
	s_add_i32 s74, s74, 2
	s_add_u32 s72, s72, 0x100
	s_addc_u32 s73, s73, 0
	s_cmpk_gt_u32 s74, 0x55
	s_mov_b64 s[36:37], s[38:39]
	s_cbranch_scc0 .LBB0_1249
	s_and_b64 vcc, exec, s[8:9]
	s_cbranch_vccz .LBB0_1252
	s_barrier
